# v3 + residual (h) loads of the 7 bf16 fused gate/residual epilogues hoisted: 2 batches of 8 loads instead of 16 serialized load-wait steps
# baseline (speedup 1.0000x reference)
; __device__ __forceinline__ unsigned cvt_pk_bf16(float lo, float hi) { unsigned r; asm volatile("v_cvt_pk_bf16_f32 %0, %1, %2" : "=v"(r) : "v"(lo), "v"(hi)); return r; }
;     __device__ __forceinline__ void fused(f32x4 (&acc)[2][2][4][2], const Unit& un, int wr, int wc, int fr, int fq, PG8_LAS unsigned char* lds, int wid, int lane) const {
;     ...
;         const int row0 = un.pm * BM + wr * 64 + fr, col0 = un.pn * BM + wc * 32 + 8 * fq;
;         const size_t boff = (size_t)(un.pm >> 3) * bstride + col0;
;         { f32x4 gv[2][2];
; #pragma unroll
;           for (int bj = 0; bj < 2; ++bj)
; #pragma unroll
;               for (int n = 0; n < 2; ++n) gv[bj][n] = *(const f32x4*)(gate + boff + bj * HALF + n * 4);
; #pragma unroll
;           for (int ai = 0; ai < 2; ++ai)
; #pragma unroll
;               for (int m = 0; m < 4; ++m) { const size_t off = (size_t)(row0 + ai * HALF + m * 16) * ldc + col0;
; #pragma unroll
;                   for (int bj = 0; bj < 2; ++bj) {
; #pragma unroll
;                       for (int n = 0; n < 2; ++n) { f32x4 bs;
;                           if (BASE_F32) bs = *(const f32x4*)((const float*)base + off + bj * HALF + n * 4);
;                           else { const u32x2v hw = *(const u32x2v*)((const bf16_t*)base + off + bj * HALF + n * 4);
;                                  bs = (f32x4){__uint_as_float(hw.x << 16), __uint_as_float(hw.x & 0xffff0000u), __uint_as_float(hw.y << 16), __uint_as_float(hw.y & 0xffff0000u)}; }
;                           acc[ai][bj][m][n] = bs + gv[bj][n] * acc[ai][bj][m][n]; }
;                       if (out_h) { const f32x4 a0 = acc[ai][bj][m][0], a1 = acc[ai][bj][m][1]; u32x4 w; w.x = cvt_pk_bf16(a0[0], a0[1]); w.y = cvt_pk_bf16(a0[2], a0[3]); w.z = cvt_pk_bf16(a1[0], a1[1]); w.w = cvt_pk_bf16(a1[2], a1[3]);
;                           *(u32x4*)(out_h + off + bj * HALF) = w; } }
.LBB0_1231:
	v_mov_b32_e32 v32, 0
	s_barrier
	s_lshl_b32 s4, s7, 5
	v_mbcnt_lo_u32_b32 v32, -1, v32
	s_add_u32 s0, s12, 0x1a600000
	v_mbcnt_hi_u32_b32 v32, -1, v32
	s_addc_u32 s1, s13, 0
	v_or_b32_e32 v158, s33, v32
	s_lshl_b32 s5, s2, 8
	s_lshl_b32 s14, s62, 8
	s_or_b32 s4, s5, s4
	v_lshrrev_b32_e32 v32, 1, v158
	v_and_b32_e32 v159, 15, v158
	s_add_i32 s15, s14, s6
	v_and_or_b32 v152, v32, 24, s4
	s_ashr_i32 s4, s62, 3
	v_ashrrev_i32_e32 v153, 31, v152
	v_mov_b32_e32 v32, 0x3000
	v_or_b32_e32 v156, s15, v159
	v_mad_i64_i32 v[32:33], s[4:5], s4, v32, v[152:153]
	v_ashrrev_i32_e32 v157, 31, v156
	v_lshl_add_u64 v[150:151], v[32:33], 2, s[12:13]
	v_lshlrev_b64 v[32:33], 12, v[156:157]
	v_lshl_add_u64 v[32:33], s[0:1], 0, v[32:33]
	v_lshlrev_b64 v[148:149], 1, v[152:153]
	s_mov_b32 s15, 0x10a000
	v_lshl_add_u64 v[154:155], v[32:33], 0, v[148:149]
	v_add_co_u32_e32 v132, vcc, s15, v150
	s_nop 0
	v_addc_co_u32_e32 v133, vcc, 0, v151, vcc
	s_mov_b64 s[4:5], 0x10a000
	flat_load_dwordx4 v[144:147], v[132:133]
	v_lshl_add_u64 v[132:133], v[150:151], 0, s[4:5]
	flat_load_dwordx4 v[140:143], v[132:133] offset:16
	flat_load_dwordx4 v[136:139], v[132:133] offset:512
	s_nop 0
	flat_load_dwordx4 v[132:135], v[132:133] offset:528
	v_or_b32_e32 v164, 16, v156
	v_ashrrev_i32_e32 v165, 31, v164
	v_lshlrev_b64 v[164:165], 12, v[164:165]
	v_lshl_add_u64 v[164:165], s[0:1], 0, v[164:165]
	v_lshl_add_u64 v[164:165], v[164:165], 0, v[148:149]
	s_mov_b64 s[98:99], 0x10000
	s_mov_b64 s[100:101], 0x80000
	v_lshl_add_u64 v[232:233], v[154:155], 0, 0
	v_lshl_add_u64 v[234:235], v[232:233], 0, s[98:99]
	v_lshl_add_u64 v[236:237], v[234:235], 0, s[98:99]
	v_lshl_add_u64 v[238:239], v[236:237], 0, s[98:99]
	global_load_dwordx4 v[200:203], v[232:233], off
	global_load_dwordx4 v[204:207], v[232:233], off offset:256
	global_load_dwordx4 v[208:211], v[234:235], off
	global_load_dwordx4 v[212:215], v[234:235], off offset:256
	global_load_dwordx4 v[216:219], v[236:237], off
	global_load_dwordx4 v[220:223], v[236:237], off offset:256
	global_load_dwordx4 v[224:227], v[238:239], off
	global_load_dwordx4 v[228:231], v[238:239], off offset:256
	s_waitcnt vmcnt(0) lgkmcnt(0)
	v_lshlrev_b32_e32 v160, 16, v200
	v_and_b32_e32 v161, 0xffff0000, v200
	v_lshlrev_b32_e32 v32, 16, v201
	v_and_b32_e32 v33, 0xffff0000, v201
	v_lshlrev_b32_e32 v162, 16, v202
	v_and_b32_e32 v163, 0xffff0000, v202
	v_lshlrev_b32_e32 v34, 16, v203
	v_and_b32_e32 v35, 0xffff0000, v203
	v_pk_fma_f32 v[10:11], v[10:11], v[146:147], v[32:33]
	v_pk_fma_f32 v[8:9], v[8:9], v[144:145], v[160:161]
	v_pk_fma_f32 v[14:15], v[14:15], v[142:143], v[34:35]
	v_pk_fma_f32 v[12:13], v[12:13], v[140:141], v[162:163]
	v_cvt_pk_bf16_f32 v32, v8, v9
	v_cvt_pk_bf16_f32 v33, v10, v11
	s_nop 0
	v_cvt_pk_bf16_f32 v34, v12, v13
	v_cvt_pk_bf16_f32 v35, v14, v15
	s_nop 0
	flat_store_dwordx4 v[154:155], v[32:35]
	s_nop 1
	s_nop 0
	v_lshlrev_b32_e32 v32, 16, v204
	v_and_b32_e32 v33, 0xffff0000, v204
	v_lshlrev_b32_e32 v34, 16, v205
	v_and_b32_e32 v35, 0xffff0000, v205
	v_lshlrev_b32_e32 v160, 16, v206
	v_and_b32_e32 v161, 0xffff0000, v206
	v_lshlrev_b32_e32 v162, 16, v207
	v_and_b32_e32 v163, 0xffff0000, v207
	v_pk_fma_f32 v[34:35], v[30:31], v[138:139], v[34:35]
	v_pk_fma_f32 v[32:33], v[28:29], v[136:137], v[32:33]
	v_pk_fma_f32 v[30:31], v[18:19], v[134:135], v[162:163]
	v_pk_fma_f32 v[28:29], v[16:17], v[132:133], v[160:161]
	v_cvt_pk_bf16_f32 v16, v32, v33
	v_cvt_pk_bf16_f32 v17, v34, v35
	s_nop 0
	v_cvt_pk_bf16_f32 v18, v28, v29
	v_cvt_pk_bf16_f32 v19, v30, v31
	flat_store_dwordx4 v[154:155], v[16:19] offset:256
	s_nop 1
	v_lshlrev_b32_e32 v160, 16, v208
	v_and_b32_e32 v161, 0xffff0000, v208
	v_lshlrev_b32_e32 v16, 16, v209
	v_and_b32_e32 v17, 0xffff0000, v209
	v_lshlrev_b32_e32 v162, 16, v210
	v_and_b32_e32 v163, 0xffff0000, v210
	v_lshlrev_b32_e32 v166, 16, v211
	v_and_b32_e32 v167, 0xffff0000, v211
	v_pk_fma_f32 v[18:19], v[62:63], v[146:147], v[16:17]
	v_pk_fma_f32 v[16:17], v[60:61], v[144:145], v[160:161]
	v_pk_fma_f32 v[22:23], v[22:23], v[142:143], v[166:167]
	v_pk_fma_f32 v[20:21], v[20:21], v[140:141], v[162:163]
	v_cvt_pk_bf16_f32 v60, v16, v17
	v_cvt_pk_bf16_f32 v61, v18, v19
	v_or_b32_e32 v166, 32, v156
	v_cvt_pk_bf16_f32 v62, v20, v21
	v_cvt_pk_bf16_f32 v63, v22, v23
	v_ashrrev_i32_e32 v167, 31, v166
	v_lshlrev_b64 v[166:167], 12, v[166:167]
	flat_store_dwordx4 v[164:165], v[60:63]
	v_lshl_add_u64 v[166:167], s[0:1], 0, v[166:167]
	v_lshl_add_u64 v[166:167], v[166:167], 0, v[148:149]
	v_or_b32_e32 v156, 48, v156
	v_ashrrev_i32_e32 v157, 31, v156
	v_lshlrev_b64 v[156:157], 12, v[156:157]
	v_lshl_add_u64 v[156:157], s[0:1], 0, v[156:157]
	v_lshl_add_u64 v[156:157], v[156:157], 0, v[148:149]
	s_mov_b32 s0, 0x80000
	s_nop 1
	v_lshlrev_b32_e32 v60, 16, v212
	v_and_b32_e32 v61, 0xffff0000, v212
	v_lshlrev_b32_e32 v62, 16, v213
	v_and_b32_e32 v63, 0xffff0000, v213
	v_lshlrev_b32_e32 v160, 16, v214
	v_and_b32_e32 v161, 0xffff0000, v214
	v_lshlrev_b32_e32 v162, 16, v215
	v_and_b32_e32 v163, 0xffff0000, v215
	v_pk_fma_f32 v[62:63], v[58:59], v[138:139], v[62:63]
	v_pk_fma_f32 v[60:61], v[56:57], v[136:137], v[60:61]
	v_pk_fma_f32 v[58:59], v[50:51], v[134:135], v[162:163]
	v_pk_fma_f32 v[56:57], v[48:49], v[132:133], v[160:161]
	v_cvt_pk_bf16_f32 v48, v60, v61
	v_cvt_pk_bf16_f32 v49, v62, v63
	s_nop 0
	v_cvt_pk_bf16_f32 v50, v56, v57
	v_cvt_pk_bf16_f32 v51, v58, v59
	flat_store_dwordx4 v[164:165], v[48:51] offset:256
	s_nop 1
	v_lshlrev_b32_e32 v160, 16, v216
	v_and_b32_e32 v161, 0xffff0000, v216
	v_lshlrev_b32_e32 v48, 16, v217
	v_and_b32_e32 v49, 0xffff0000, v217
	v_lshlrev_b32_e32 v162, 16, v218
	v_and_b32_e32 v163, 0xffff0000, v218
; __device__ __forceinline__ unsigned cvt_pk_bf16(float lo, float hi) { unsigned r; asm volatile("v_cvt_pk_bf16_f32 %0, %1, %2" : "=v"(r) : "v"(lo), "v"(hi)); return r; }
;     __device__ __forceinline__ void fused(f32x4 (&acc)[2][2][4][2], const Unit& un, int wr, int wc, int fr, int fq, PG8_LAS unsigned char* lds, int wid, int lane) const {
;     ...
;               for (int m = 0; m < 4; ++m) { const size_t off = (size_t)(row0 + ai * HALF + m * 16) * ldc + col0;
; #pragma unroll
;                   for (int bj = 0; bj < 2; ++bj) {
; #pragma unroll
;                       for (int n = 0; n < 2; ++n) { f32x4 bs;
;                           if (BASE_F32) bs = *(const f32x4*)((const float*)base + off + bj * HALF + n * 4);
;                           else { const u32x2v hw = *(const u32x2v*)((const bf16_t*)base + off + bj * HALF + n * 4);
;                                  bs = (f32x4){__uint_as_float(hw.x << 16), __uint_as_float(hw.x & 0xffff0000u), __uint_as_float(hw.y << 16), __uint_as_float(hw.y & 0xffff0000u)}; }
;                           acc[ai][bj][m][n] = bs + gv[bj][n] * acc[ai][bj][m][n]; }
;                       if (out_h) { const f32x4 a0 = acc[ai][bj][m][0], a1 = acc[ai][bj][m][1]; u32x4 w; w.x = cvt_pk_bf16(a0[0], a0[1]); w.y = cvt_pk_bf16(a0[2], a0[3]); w.z = cvt_pk_bf16(a1[0], a1[1]); w.w = cvt_pk_bf16(a1[2], a1[3]);
;                           *(u32x4*)(out_h + off + bj * HALF) = w; } }
	v_lshlrev_b32_e32 v164, 16, v219
	v_and_b32_e32 v165, 0xffff0000, v219
	v_pk_fma_f32 v[50:51], v[78:79], v[146:147], v[48:49]
	v_pk_fma_f32 v[48:49], v[76:77], v[144:145], v[160:161]
	v_pk_fma_f32 v[54:55], v[54:55], v[142:143], v[164:165]
	v_pk_fma_f32 v[52:53], v[52:53], v[140:141], v[162:163]
	v_cvt_pk_bf16_f32 v76, v48, v49
	v_cvt_pk_bf16_f32 v77, v50, v51
	s_nop 0
	v_cvt_pk_bf16_f32 v78, v52, v53
	v_cvt_pk_bf16_f32 v79, v54, v55
	s_nop 0
	flat_store_dwordx4 v[166:167], v[76:79]
	s_nop 1
	s_nop 0
	v_lshlrev_b32_e32 v76, 16, v220
	v_and_b32_e32 v77, 0xffff0000, v220
	v_lshlrev_b32_e32 v78, 16, v221
	v_and_b32_e32 v79, 0xffff0000, v221
	v_lshlrev_b32_e32 v160, 16, v222
	v_and_b32_e32 v161, 0xffff0000, v222
	v_lshlrev_b32_e32 v162, 16, v223
	v_and_b32_e32 v163, 0xffff0000, v223
	v_pk_fma_f32 v[78:79], v[74:75], v[138:139], v[78:79]
	v_pk_fma_f32 v[76:77], v[72:73], v[136:137], v[76:77]
	v_pk_fma_f32 v[74:75], v[66:67], v[134:135], v[162:163]
	v_pk_fma_f32 v[72:73], v[64:65], v[132:133], v[160:161]
	v_cvt_pk_bf16_f32 v64, v76, v77
	v_cvt_pk_bf16_f32 v65, v78, v79
	s_nop 0
	v_cvt_pk_bf16_f32 v66, v72, v73
	v_cvt_pk_bf16_f32 v67, v74, v75
	flat_store_dwordx4 v[166:167], v[64:67] offset:256
	s_nop 1
	v_lshlrev_b32_e32 v160, 16, v224
	v_and_b32_e32 v161, 0xffff0000, v224
	v_lshlrev_b32_e32 v64, 16, v225
	v_and_b32_e32 v65, 0xffff0000, v225
	v_lshlrev_b32_e32 v162, 16, v226
	v_and_b32_e32 v163, 0xffff0000, v226
	v_lshlrev_b32_e32 v164, 16, v227
	v_and_b32_e32 v165, 0xffff0000, v227
	v_pk_fma_f32 v[66:67], v[130:131], v[146:147], v[64:65]
	v_pk_fma_f32 v[64:65], v[128:129], v[144:145], v[160:161]
	v_pk_fma_f32 v[70:71], v[70:71], v[142:143], v[164:165]
	v_pk_fma_f32 v[68:69], v[68:69], v[140:141], v[162:163]
	v_cvt_pk_bf16_f32 v128, v64, v65
	v_cvt_pk_bf16_f32 v129, v66, v67
	v_add_co_u32_e32 v164, vcc, s0, v154
	v_cvt_pk_bf16_f32 v130, v68, v69
	v_cvt_pk_bf16_f32 v131, v70, v71
	s_nop 0
	v_addc_co_u32_e32 v165, vcc, 0, v155, vcc
	flat_store_dwordx4 v[156:157], v[128:131]
	s_mov_b64 s[0:1], 0x80000
	s_nop 1
	v_lshlrev_b32_e32 v128, 16, v228
	v_and_b32_e32 v129, 0xffff0000, v228
	v_lshlrev_b32_e32 v130, 16, v229
	v_and_b32_e32 v131, 0xffff0000, v229
	v_lshlrev_b32_e32 v160, 16, v230
	v_and_b32_e32 v161, 0xffff0000, v230
	v_lshlrev_b32_e32 v162, 16, v231
	v_and_b32_e32 v163, 0xffff0000, v231
	v_pk_fma_f32 v[110:111], v[110:111], v[138:139], v[130:131]
	v_pk_fma_f32 v[108:109], v[108:109], v[136:137], v[128:129]
	v_pk_fma_f32 v[98:99], v[98:99], v[134:135], v[162:163]
	v_pk_fma_f32 v[96:97], v[96:97], v[132:133], v[160:161]
	v_cvt_pk_bf16_f32 v128, v108, v109
	v_cvt_pk_bf16_f32 v129, v110, v111
	s_nop 0
	v_cvt_pk_bf16_f32 v130, v96, v97
	v_cvt_pk_bf16_f32 v131, v98, v99
	flat_store_dwordx4 v[156:157], v[128:131] offset:256
	v_lshl_add_u64 v[156:157], v[154:155], 0, s[0:1]
	s_mov_b32 s0, 0x90000
	v_add_co_u32_e32 v166, vcc, s0, v154
	s_mov_b64 s[0:1], 0x90000
	s_nop 0
	v_addc_co_u32_e32 v167, vcc, 0, v155, vcc
	v_lshl_add_u64 v[232:233], v[232:233], 0, s[100:101]
	v_lshl_add_u64 v[234:235], v[234:235], 0, s[100:101]
	v_lshl_add_u64 v[236:237], v[236:237], 0, s[100:101]
	v_lshl_add_u64 v[238:239], v[238:239], 0, s[100:101]
	global_load_dwordx4 v[200:203], v[232:233], off
	global_load_dwordx4 v[204:207], v[232:233], off offset:256
	global_load_dwordx4 v[208:211], v[234:235], off
	global_load_dwordx4 v[212:215], v[234:235], off offset:256
	global_load_dwordx4 v[216:219], v[236:237], off
	global_load_dwordx4 v[220:223], v[236:237], off offset:256
	global_load_dwordx4 v[224:227], v[238:239], off
	global_load_dwordx4 v[228:231], v[238:239], off offset:256
	s_waitcnt vmcnt(0) lgkmcnt(0)
	v_lshlrev_b32_e32 v160, 16, v200
	v_and_b32_e32 v161, 0xffff0000, v200
	v_lshlrev_b32_e32 v128, 16, v201
	v_and_b32_e32 v129, 0xffff0000, v201
	v_lshlrev_b32_e32 v162, 16, v202
	v_and_b32_e32 v163, 0xffff0000, v202
	v_lshlrev_b32_e32 v130, 16, v203
	v_and_b32_e32 v131, 0xffff0000, v203
	v_pk_fma_f32 v[102:103], v[102:103], v[146:147], v[128:129]
	v_pk_fma_f32 v[100:101], v[100:101], v[144:145], v[160:161]
	v_pk_fma_f32 v[106:107], v[106:107], v[142:143], v[130:131]
	v_pk_fma_f32 v[104:105], v[104:105], v[140:141], v[162:163]
	v_cvt_pk_bf16_f32 v128, v100, v101
	v_cvt_pk_bf16_f32 v129, v102, v103
	s_nop 0
	v_cvt_pk_bf16_f32 v130, v104, v105
	v_cvt_pk_bf16_f32 v131, v106, v107
	s_nop 0
	flat_store_dwordx4 v[164:165], v[128:131]
	s_nop 1
	s_nop 0
	v_lshlrev_b32_e32 v128, 16, v204
	v_and_b32_e32 v129, 0xffff0000, v204
	v_lshlrev_b32_e32 v130, 16, v205
	v_and_b32_e32 v131, 0xffff0000, v205
	v_lshlrev_b32_e32 v160, 16, v206
	v_and_b32_e32 v161, 0xffff0000, v206
	v_lshlrev_b32_e32 v162, 16, v207
	v_and_b32_e32 v163, 0xffff0000, v207
	v_pk_fma_f32 v[126:127], v[126:127], v[138:139], v[130:131]
	v_pk_fma_f32 v[124:125], v[124:125], v[136:137], v[128:129]
	v_pk_fma_f32 v[114:115], v[114:115], v[134:135], v[162:163]
	v_pk_fma_f32 v[112:113], v[112:113], v[132:133], v[160:161]
	v_cvt_pk_bf16_f32 v128, v124, v125
	v_cvt_pk_bf16_f32 v129, v126, v127
	s_nop 0
	v_cvt_pk_bf16_f32 v130, v112, v113
	v_cvt_pk_bf16_f32 v131, v114, v115
	flat_store_dwordx4 v[156:157], v[128:131] offset:256
	v_lshl_add_u64 v[156:157], v[154:155], 0, s[0:1]
	s_mov_b32 s0, 0xa0000
	v_add_co_u32_e32 v164, vcc, s0, v154
	s_mov_b64 s[0:1], 0xa0000
	s_nop 0
	v_addc_co_u32_e32 v165, vcc, 0, v155, vcc
	s_nop 1
	v_lshlrev_b32_e32 v160, 16, v208
	v_and_b32_e32 v161, 0xffff0000, v208
	v_lshlrev_b32_e32 v128, 16, v209
	v_and_b32_e32 v129, 0xffff0000, v209
	v_lshlrev_b32_e32 v162, 16, v210
	v_and_b32_e32 v163, 0xffff0000, v210
	v_lshlrev_b32_e32 v130, 16, v211
	v_and_b32_e32 v131, 0xffff0000, v211
; __device__ __forceinline__ unsigned cvt_pk_bf16(float lo, float hi) { unsigned r; asm volatile("v_cvt_pk_bf16_f32 %0, %1, %2" : "=v"(r) : "v"(lo), "v"(hi)); return r; }
;     __device__ __forceinline__ void fused(f32x4 (&acc)[2][2][4][2], const Unit& un, int wr, int wc, int fr, int fq, PG8_LAS unsigned char* lds, int wid, int lane) const {
;     ...
;               for (int m = 0; m < 4; ++m) { const size_t off = (size_t)(row0 + ai * HALF + m * 16) * ldc + col0;
; #pragma unroll
;                   for (int bj = 0; bj < 2; ++bj) {
; #pragma unroll
;                       for (int n = 0; n < 2; ++n) { f32x4 bs;
;                           if (BASE_F32) bs = *(const f32x4*)((const float*)base + off + bj * HALF + n * 4);
;                           else { const u32x2v hw = *(const u32x2v*)((const bf16_t*)base + off + bj * HALF + n * 4);
;                                  bs = (f32x4){__uint_as_float(hw.x << 16), __uint_as_float(hw.x & 0xffff0000u), __uint_as_float(hw.y << 16), __uint_as_float(hw.y & 0xffff0000u)}; }
;                           acc[ai][bj][m][n] = bs + gv[bj][n] * acc[ai][bj][m][n]; }
;                       if (out_h) { const f32x4 a0 = acc[ai][bj][m][0], a1 = acc[ai][bj][m][1]; u32x4 w; w.x = cvt_pk_bf16(a0[0], a0[1]); w.y = cvt_pk_bf16(a0[2], a0[3]); w.z = cvt_pk_bf16(a1[0], a1[1]); w.w = cvt_pk_bf16(a1[2], a1[3]);
;                           *(u32x4*)(out_h + off + bj * HALF) = w; } }
;                   asm volatile("" : "+v"(acc[ai][0][m][0]), "+v"(acc[ai][0][m][1]), "+v"(acc[ai][1][m][0]), "+v"(acc[ai][1][m][1]));
;                   asm volatile("" ::: "memory"); } }
; #pragma unroll
;         for (int ai = 0; ai < 2; ++ai)
; #pragma unroll
;             for (int m = 0; m < 4; ++m) { float s = 0.f;
; #pragma unroll
;                 for (int bj = 0; bj < 2; ++bj)
; #pragma unroll
;                     for (int n = 0; n < 2; ++n) { const f32x4 x = acc[ai][bj][m][n]; s += (x[0] * x[0] + x[1] * x[1]) + (x[2] * x[2] + x[3] * x[3]); }
;                 s += __shfl_xor(s, 16); s += __shfl_xor(s, 32);
;                 if (fq == 0) P[(ai * HALF + wr * 64 + m * 16 + fr) * 4 + wc] = s; }
	v_pk_fma_f32 v[118:119], v[118:119], v[146:147], v[128:129]
	v_pk_fma_f32 v[116:117], v[116:117], v[144:145], v[160:161]
	v_pk_fma_f32 v[122:123], v[122:123], v[142:143], v[130:131]
	v_pk_fma_f32 v[120:121], v[120:121], v[140:141], v[162:163]
	v_cvt_pk_bf16_f32 v128, v116, v117
	v_cvt_pk_bf16_f32 v129, v118, v119
	s_nop 0
	v_cvt_pk_bf16_f32 v130, v120, v121
	v_cvt_pk_bf16_f32 v131, v122, v123
	s_nop 0
	flat_store_dwordx4 v[166:167], v[128:131]
	s_nop 1
	s_nop 0
	v_lshlrev_b32_e32 v128, 16, v212
	v_and_b32_e32 v129, 0xffff0000, v212
	v_lshlrev_b32_e32 v130, 16, v213
	v_and_b32_e32 v131, 0xffff0000, v213
	v_lshlrev_b32_e32 v160, 16, v214
	v_and_b32_e32 v161, 0xffff0000, v214
	v_lshlrev_b32_e32 v162, 16, v215
	v_and_b32_e32 v163, 0xffff0000, v215
	v_pk_fma_f32 v[94:95], v[94:95], v[138:139], v[130:131]
	v_pk_fma_f32 v[92:93], v[92:93], v[136:137], v[128:129]
	v_pk_fma_f32 v[90:91], v[90:91], v[134:135], v[162:163]
	v_pk_fma_f32 v[88:89], v[88:89], v[132:133], v[160:161]
	v_cvt_pk_bf16_f32 v128, v92, v93
	v_cvt_pk_bf16_f32 v129, v94, v95
	s_nop 0
	v_cvt_pk_bf16_f32 v130, v88, v89
	v_cvt_pk_bf16_f32 v131, v90, v91
	flat_store_dwordx4 v[156:157], v[128:131] offset:256
	v_lshl_add_u64 v[156:157], v[154:155], 0, s[0:1]
	s_mov_b32 s0, 0xb0000
	v_add_co_u32_e32 v166, vcc, s0, v154
	s_mov_b64 s[0:1], 0xb0000
	s_nop 0
	v_addc_co_u32_e32 v167, vcc, 0, v155, vcc
	s_nop 1
	v_lshlrev_b32_e32 v160, 16, v216
	v_and_b32_e32 v161, 0xffff0000, v216
	v_lshlrev_b32_e32 v128, 16, v217
	v_and_b32_e32 v129, 0xffff0000, v217
	v_lshlrev_b32_e32 v162, 16, v218
	v_and_b32_e32 v163, 0xffff0000, v218
	v_lshlrev_b32_e32 v130, 16, v219
	v_and_b32_e32 v131, 0xffff0000, v219
	v_pk_fma_f32 v[86:87], v[86:87], v[146:147], v[128:129]
	v_pk_fma_f32 v[84:85], v[84:85], v[144:145], v[160:161]
	v_pk_fma_f32 v[82:83], v[82:83], v[142:143], v[130:131]
	v_pk_fma_f32 v[80:81], v[80:81], v[140:141], v[162:163]
	v_cvt_pk_bf16_f32 v128, v84, v85
	v_cvt_pk_bf16_f32 v129, v86, v87
	s_nop 0
	v_cvt_pk_bf16_f32 v130, v80, v81
	v_cvt_pk_bf16_f32 v131, v82, v83
	s_nop 0
	flat_store_dwordx4 v[164:165], v[128:131]
	v_mul_f32_e32 v164, v29, v29
	v_mul_f32_e32 v165, v31, v31
	v_fmac_f32_e32 v164, v28, v28
	v_fmac_f32_e32 v165, v30, v30
	s_nop 1
	v_lshlrev_b32_e32 v128, 16, v220
	v_and_b32_e32 v129, 0xffff0000, v220
	v_lshlrev_b32_e32 v130, 16, v221
	v_and_b32_e32 v131, 0xffff0000, v221
	v_lshlrev_b32_e32 v160, 16, v222
	v_and_b32_e32 v161, 0xffff0000, v222
	v_lshlrev_b32_e32 v162, 16, v223
	v_and_b32_e32 v163, 0xffff0000, v223
	v_pk_fma_f32 v[46:47], v[46:47], v[138:139], v[130:131]
	v_pk_fma_f32 v[44:45], v[44:45], v[136:137], v[128:129]
	v_pk_fma_f32 v[42:43], v[42:43], v[134:135], v[162:163]
	v_pk_fma_f32 v[40:41], v[40:41], v[132:133], v[160:161]
	v_cvt_pk_bf16_f32 v128, v44, v45
	v_cvt_pk_bf16_f32 v129, v46, v47
	v_lshl_add_u64 v[160:161], v[154:155], 0, s[0:1]
	v_cvt_pk_bf16_f32 v130, v40, v41
	v_cvt_pk_bf16_f32 v131, v42, v43
	flat_store_dwordx4 v[156:157], v[128:131] offset:256
	v_mul_f32_e32 v162, v33, v33
	v_mul_f32_e32 v163, v35, v35
	v_fmac_f32_e32 v162, v32, v32
	v_fmac_f32_e32 v163, v34, v34
	s_lshl_b32 s0, s7, 2
	s_add_i32 s0, s0, 0
	s_nop 1
	v_lshlrev_b32_e32 v154, 16, v224
	v_and_b32_e32 v155, 0xffff0000, v224
	v_lshlrev_b32_e32 v128, 16, v225
	v_and_b32_e32 v129, 0xffff0000, v225
	v_lshlrev_b32_e32 v156, 16, v226
	v_and_b32_e32 v157, 0xffff0000, v226
	v_lshlrev_b32_e32 v130, 16, v227
	v_and_b32_e32 v131, 0xffff0000, v227
	v_pk_fma_f32 v[38:39], v[38:39], v[146:147], v[128:129]
	v_pk_fma_f32 v[36:37], v[36:37], v[144:145], v[154:155]
	v_pk_fma_f32 v[26:27], v[26:27], v[142:143], v[130:131]
	v_pk_fma_f32 v[24:25], v[24:25], v[140:141], v[156:157]
	v_cvt_pk_bf16_f32 v142, v36, v37
	v_cvt_pk_bf16_f32 v143, v38, v39
	v_mbcnt_lo_u32_b32 v128, -1, 0
	v_cvt_pk_bf16_f32 v144, v24, v25
	v_cvt_pk_bf16_f32 v145, v26, v27
	v_mbcnt_hi_u32_b32 v129, -1, v128
	v_mul_f32_e32 v140, v9, v9
	v_mul_f32_e32 v141, v11, v11
	v_mul_f32_e32 v146, v13, v13
	v_mul_f32_e32 v147, v15, v15
	v_and_b32_e32 v130, 64, v129
	v_fmac_f32_e32 v140, v8, v8
	v_fmac_f32_e32 v141, v10, v10
	v_fmac_f32_e32 v146, v12, v12
	v_fmac_f32_e32 v147, v14, v14
	v_xor_b32_e32 v128, 16, v129
	v_add_u32_e32 v130, 64, v130
	v_add_f32_e32 v140, v140, v141
	v_add_f32_e32 v141, v146, v147
	v_cmp_lt_i32_e32 vcc, v128, v130
	v_add_f32_e32 v146, v162, v163
	v_add_f32_e32 v140, v140, v141
	v_cndmask_b32_e32 v128, v129, v128, vcc
	v_add_f32_e32 v147, v164, v165
	v_add_f32_e32 v140, v146, v140
	v_lshlrev_b32_e32 v128, 2, v128
	v_add_f32_e32 v140, v147, v140
	ds_bpermute_b32 v141, v128, v140
	v_xor_b32_e32 v131, 32, v129
	v_cmp_lt_i32_e32 vcc, v131, v130
	flat_store_dwordx4 v[166:167], v[142:145]
	v_and_b32_e32 v130, 63, v158
	v_cndmask_b32_e32 v129, v129, v131, vcc
	v_lshlrev_b32_e32 v129, 2, v129
	s_waitcnt lgkmcnt(0)
	v_add_f32_e32 v140, v140, v141
	ds_bpermute_b32 v141, v129, v140
	v_cmp_gt_u32_e32 vcc, 16, v130
	s_waitcnt vmcnt(0)
	v_lshlrev_b32_e32 v142, 16, v228
	v_and_b32_e32 v143, 0xffff0000, v228
	v_lshlrev_b32_e32 v144, 16, v229
	v_and_b32_e32 v145, 0xffff0000, v229
	v_lshlrev_b32_e32 v146, 16, v230
	v_and_b32_e32 v147, 0xffff0000, v230
	v_lshlrev_b32_e32 v154, 16, v231
	v_and_b32_e32 v155, 0xffff0000, v231
	v_pk_fma_f32 v[6:7], v[6:7], v[138:139], v[144:145]
	v_pk_fma_f32 v[4:5], v[4:5], v[136:137], v[142:143]
	v_pk_fma_f32 v[2:3], v[2:3], v[134:135], v[154:155]
	v_pk_fma_f32 v[0:1], v[0:1], v[132:133], v[146:147]
	v_cvt_pk_bf16_f32 v132, v4, v5
	v_cvt_pk_bf16_f32 v133, v6, v7
	v_or_b32_e32 v144, s6, v159
	v_cvt_pk_bf16_f32 v134, v0, v1
	v_cvt_pk_bf16_f32 v135, v2, v3
	flat_store_dwordx4 v[160:161], v[132:135] offset:256
	v_lshl_add_u32 v131, v144, 4, s0
	s_and_saveexec_b64 s[0:1], vcc
	v_readlane_b32 s96, v254, 47
	s_cbranch_execz .LBB0_1233
	s_waitcnt lgkmcnt(0)
	v_add_f32_e32 v132, v140, v141
	ds_write_b32 v131, v132

; __device__ __forceinline__ unsigned cvt_pk_bf16(float lo, float hi) { unsigned r; asm volatile("v_cvt_pk_bf16_f32 %0, %1, %2" : "=v"(r) : "v"(lo), "v"(hi)); return r; }
;     __device__ __forceinline__ void fused(f32x4 (&acc)[2][2][4][2], const Unit& un, int wr, int wc, int fr, int fq, PG8_LAS unsigned char* lds, int wid, int lane) const {
;     ...
;         const int row0 = un.pm * BM + wr * 64 + fr, col0 = un.pn * BM + wc * 32 + 8 * fq;
;         const size_t boff = (size_t)(un.pm >> 3) * bstride + col0;
;         { f32x4 gv[2][2];
; #pragma unroll
;           for (int bj = 0; bj < 2; ++bj)
; #pragma unroll
;               for (int n = 0; n < 2; ++n) gv[bj][n] = *(const f32x4*)(gate + boff + bj * HALF + n * 4);
; #pragma unroll
;           for (int ai = 0; ai < 2; ++ai)
; #pragma unroll
;               for (int m = 0; m < 4; ++m) { const size_t off = (size_t)(row0 + ai * HALF + m * 16) * ldc + col0;
; #pragma unroll
;                   for (int bj = 0; bj < 2; ++bj) {
; #pragma unroll
;                       for (int n = 0; n < 2; ++n) { f32x4 bs;
;                           if (BASE_F32) bs = *(const f32x4*)((const float*)base + off + bj * HALF + n * 4);
;                           else { const u32x2v hw = *(const u32x2v*)((const bf16_t*)base + off + bj * HALF + n * 4);
;                                  bs = (f32x4){__uint_as_float(hw.x << 16), __uint_as_float(hw.x & 0xffff0000u), __uint_as_float(hw.y << 16), __uint_as_float(hw.y & 0xffff0000u)}; }
;                           acc[ai][bj][m][n] = bs + gv[bj][n] * acc[ai][bj][m][n]; }
;                       if (out_h) { const f32x4 a0 = acc[ai][bj][m][0], a1 = acc[ai][bj][m][1]; u32x4 w; w.x = cvt_pk_bf16(a0[0], a0[1]); w.y = cvt_pk_bf16(a0[2], a0[3]); w.z = cvt_pk_bf16(a1[0], a1[1]); w.w = cvt_pk_bf16(a1[2], a1[3]);
;                           *(u32x4*)(out_h + off + bj * HALF) = w; } }
.LBB0_1844:
	v_mov_b32_e32 v32, 0
	s_barrier
	s_lshl_b32 s6, s9, 5
	v_mbcnt_lo_u32_b32 v32, -1, v32
	s_add_u32 s2, s60, 0x1a600000
	v_mbcnt_hi_u32_b32 v32, -1, v32
	s_addc_u32 s3, s61, 0
	v_or_b32_e32 v158, s33, v32
	s_lshl_b32 s7, s4, 8
	s_lshl_b32 s14, s62, 8
	s_or_b32 s6, s7, s6
	v_lshrrev_b32_e32 v32, 1, v158
	v_and_b32_e32 v159, 15, v158
	s_add_i32 s15, s14, s8
	v_and_or_b32 v152, v32, 24, s6
	s_ashr_i32 s6, s62, 3
	v_ashrrev_i32_e32 v153, 31, v152
	v_mov_b32_e32 v32, 0x3000
	v_or_b32_e32 v156, s15, v159
	v_mad_i64_i32 v[32:33], s[6:7], s6, v32, v[152:153]
	v_ashrrev_i32_e32 v157, 31, v156
	v_lshl_add_u64 v[150:151], v[32:33], 2, s[60:61]
	v_lshlrev_b64 v[32:33], 12, v[156:157]
	v_lshl_add_u64 v[32:33], s[2:3], 0, v[32:33]
	v_lshlrev_b64 v[148:149], 1, v[152:153]
	s_mov_b32 s15, 0x134000
	v_lshl_add_u64 v[154:155], v[32:33], 0, v[148:149]
	v_add_co_u32_e32 v132, vcc, s15, v150
	s_nop 0
	v_addc_co_u32_e32 v133, vcc, 0, v151, vcc
	s_mov_b64 s[6:7], 0x134000
	flat_load_dwordx4 v[144:147], v[132:133]
	v_lshl_add_u64 v[132:133], v[150:151], 0, s[6:7]
	flat_load_dwordx4 v[140:143], v[132:133] offset:16
	flat_load_dwordx4 v[136:139], v[132:133] offset:512
	s_nop 0
	flat_load_dwordx4 v[132:135], v[132:133] offset:528
	v_or_b32_e32 v164, 16, v156
	v_ashrrev_i32_e32 v165, 31, v164
	v_lshlrev_b64 v[164:165], 12, v[164:165]
	v_lshl_add_u64 v[164:165], s[2:3], 0, v[164:165]
	v_lshl_add_u64 v[164:165], v[164:165], 0, v[148:149]
	s_mov_b64 s[98:99], 0x10000
	s_mov_b64 s[100:101], 0x80000
	v_lshl_add_u64 v[232:233], v[154:155], 0, 0
	v_lshl_add_u64 v[234:235], v[232:233], 0, s[98:99]
	v_lshl_add_u64 v[236:237], v[234:235], 0, s[98:99]
	v_lshl_add_u64 v[238:239], v[236:237], 0, s[98:99]
	global_load_dwordx4 v[200:203], v[232:233], off
	global_load_dwordx4 v[204:207], v[232:233], off offset:256
	global_load_dwordx4 v[208:211], v[234:235], off
	global_load_dwordx4 v[212:215], v[234:235], off offset:256
	global_load_dwordx4 v[216:219], v[236:237], off
	global_load_dwordx4 v[220:223], v[236:237], off offset:256
	global_load_dwordx4 v[224:227], v[238:239], off
	global_load_dwordx4 v[228:231], v[238:239], off offset:256
	s_waitcnt vmcnt(0) lgkmcnt(0)
	v_lshlrev_b32_e32 v160, 16, v200
	v_and_b32_e32 v161, 0xffff0000, v200
	v_lshlrev_b32_e32 v32, 16, v201
	v_and_b32_e32 v33, 0xffff0000, v201
	v_lshlrev_b32_e32 v162, 16, v202
	v_and_b32_e32 v163, 0xffff0000, v202
	v_lshlrev_b32_e32 v34, 16, v203
	v_and_b32_e32 v35, 0xffff0000, v203
	v_pk_fma_f32 v[10:11], v[10:11], v[146:147], v[32:33]
	v_pk_fma_f32 v[8:9], v[8:9], v[144:145], v[160:161]
	v_pk_fma_f32 v[14:15], v[14:15], v[142:143], v[34:35]
	v_pk_fma_f32 v[12:13], v[12:13], v[140:141], v[162:163]
	v_cvt_pk_bf16_f32 v32, v8, v9
	v_cvt_pk_bf16_f32 v33, v10, v11
	s_nop 0
	v_cvt_pk_bf16_f32 v34, v12, v13
	v_cvt_pk_bf16_f32 v35, v14, v15
	s_nop 0
	flat_store_dwordx4 v[154:155], v[32:35]
	s_nop 1
	s_nop 0
	v_lshlrev_b32_e32 v32, 16, v204
	v_and_b32_e32 v33, 0xffff0000, v204
	v_lshlrev_b32_e32 v34, 16, v205
	v_and_b32_e32 v35, 0xffff0000, v205
	v_lshlrev_b32_e32 v160, 16, v206
	v_and_b32_e32 v161, 0xffff0000, v206
	v_lshlrev_b32_e32 v162, 16, v207
	v_and_b32_e32 v163, 0xffff0000, v207
	v_pk_fma_f32 v[34:35], v[26:27], v[138:139], v[34:35]
	v_pk_fma_f32 v[32:33], v[24:25], v[136:137], v[32:33]
	v_pk_fma_f32 v[26:27], v[18:19], v[134:135], v[162:163]
	v_pk_fma_f32 v[24:25], v[16:17], v[132:133], v[160:161]
	v_cvt_pk_bf16_f32 v16, v32, v33
	v_cvt_pk_bf16_f32 v17, v34, v35
	s_nop 0
	v_cvt_pk_bf16_f32 v18, v24, v25
	v_cvt_pk_bf16_f32 v19, v26, v27
	flat_store_dwordx4 v[154:155], v[16:19] offset:256
	s_nop 1
	v_lshlrev_b32_e32 v160, 16, v208
	v_and_b32_e32 v161, 0xffff0000, v208
	v_lshlrev_b32_e32 v16, 16, v209
	v_and_b32_e32 v17, 0xffff0000, v209
	v_lshlrev_b32_e32 v162, 16, v210
	v_and_b32_e32 v163, 0xffff0000, v210
	v_lshlrev_b32_e32 v166, 16, v211
	v_and_b32_e32 v167, 0xffff0000, v211
	v_pk_fma_f32 v[18:19], v[62:63], v[146:147], v[16:17]
	v_pk_fma_f32 v[16:17], v[60:61], v[144:145], v[160:161]
	v_pk_fma_f32 v[22:23], v[22:23], v[142:143], v[166:167]
	v_pk_fma_f32 v[20:21], v[20:21], v[140:141], v[162:163]
	v_cvt_pk_bf16_f32 v60, v16, v17
	v_cvt_pk_bf16_f32 v61, v18, v19
	v_or_b32_e32 v166, 32, v156
	v_cvt_pk_bf16_f32 v62, v20, v21
	v_cvt_pk_bf16_f32 v63, v22, v23
	v_ashrrev_i32_e32 v167, 31, v166
	v_lshlrev_b64 v[166:167], 12, v[166:167]
	flat_store_dwordx4 v[164:165], v[60:63]
	v_lshl_add_u64 v[166:167], s[2:3], 0, v[166:167]
	v_lshl_add_u64 v[166:167], v[166:167], 0, v[148:149]
	v_or_b32_e32 v156, 48, v156
	v_ashrrev_i32_e32 v157, 31, v156
	v_lshlrev_b64 v[156:157], 12, v[156:157]
	v_lshl_add_u64 v[156:157], s[2:3], 0, v[156:157]
	v_lshl_add_u64 v[156:157], v[156:157], 0, v[148:149]
	s_mov_b32 s2, 0x80000
	s_nop 1
	v_lshlrev_b32_e32 v60, 16, v212
	v_and_b32_e32 v61, 0xffff0000, v212
	v_lshlrev_b32_e32 v62, 16, v213
	v_and_b32_e32 v63, 0xffff0000, v213
	v_lshlrev_b32_e32 v160, 16, v214
	v_and_b32_e32 v161, 0xffff0000, v214
	v_lshlrev_b32_e32 v162, 16, v215
	v_and_b32_e32 v163, 0xffff0000, v215
	v_pk_fma_f32 v[62:63], v[58:59], v[138:139], v[62:63]
	v_pk_fma_f32 v[60:61], v[56:57], v[136:137], v[60:61]
	v_pk_fma_f32 v[58:59], v[50:51], v[134:135], v[162:163]
	v_pk_fma_f32 v[56:57], v[48:49], v[132:133], v[160:161]
	v_cvt_pk_bf16_f32 v48, v60, v61
	v_cvt_pk_bf16_f32 v49, v62, v63
	s_nop 0
	v_cvt_pk_bf16_f32 v50, v56, v57
	v_cvt_pk_bf16_f32 v51, v58, v59
	flat_store_dwordx4 v[164:165], v[48:51] offset:256
	s_nop 1
	v_lshlrev_b32_e32 v160, 16, v216
	v_and_b32_e32 v161, 0xffff0000, v216
	v_lshlrev_b32_e32 v48, 16, v217
	v_and_b32_e32 v49, 0xffff0000, v217
	v_lshlrev_b32_e32 v162, 16, v218
	v_and_b32_e32 v163, 0xffff0000, v218
; __device__ __forceinline__ unsigned cvt_pk_bf16(float lo, float hi) { unsigned r; asm volatile("v_cvt_pk_bf16_f32 %0, %1, %2" : "=v"(r) : "v"(lo), "v"(hi)); return r; }
;     __device__ __forceinline__ void fused(f32x4 (&acc)[2][2][4][2], const Unit& un, int wr, int wc, int fr, int fq, PG8_LAS unsigned char* lds, int wid, int lane) const {
;     ...
;               for (int m = 0; m < 4; ++m) { const size_t off = (size_t)(row0 + ai * HALF + m * 16) * ldc + col0;
; #pragma unroll
;                   for (int bj = 0; bj < 2; ++bj) {
; #pragma unroll
;                       for (int n = 0; n < 2; ++n) { f32x4 bs;
;                           if (BASE_F32) bs = *(const f32x4*)((const float*)base + off + bj * HALF + n * 4);
;                           else { const u32x2v hw = *(const u32x2v*)((const bf16_t*)base + off + bj * HALF + n * 4);
;                                  bs = (f32x4){__uint_as_float(hw.x << 16), __uint_as_float(hw.x & 0xffff0000u), __uint_as_float(hw.y << 16), __uint_as_float(hw.y & 0xffff0000u)}; }
;                           acc[ai][bj][m][n] = bs + gv[bj][n] * acc[ai][bj][m][n]; }
;                       if (out_h) { const f32x4 a0 = acc[ai][bj][m][0], a1 = acc[ai][bj][m][1]; u32x4 w; w.x = cvt_pk_bf16(a0[0], a0[1]); w.y = cvt_pk_bf16(a0[2], a0[3]); w.z = cvt_pk_bf16(a1[0], a1[1]); w.w = cvt_pk_bf16(a1[2], a1[3]);
;                           *(u32x4*)(out_h + off + bj * HALF) = w; } }
	v_lshlrev_b32_e32 v164, 16, v219
	v_and_b32_e32 v165, 0xffff0000, v219
	v_pk_fma_f32 v[50:51], v[78:79], v[146:147], v[48:49]
	v_pk_fma_f32 v[48:49], v[76:77], v[144:145], v[160:161]
	v_pk_fma_f32 v[54:55], v[54:55], v[142:143], v[164:165]
	v_pk_fma_f32 v[52:53], v[52:53], v[140:141], v[162:163]
	v_cvt_pk_bf16_f32 v76, v48, v49
	v_cvt_pk_bf16_f32 v77, v50, v51
	s_nop 0
	v_cvt_pk_bf16_f32 v78, v52, v53
	v_cvt_pk_bf16_f32 v79, v54, v55
	s_nop 0
	flat_store_dwordx4 v[166:167], v[76:79]
	s_nop 1
	s_nop 0
	v_lshlrev_b32_e32 v76, 16, v220
	v_and_b32_e32 v77, 0xffff0000, v220
	v_lshlrev_b32_e32 v78, 16, v221
	v_and_b32_e32 v79, 0xffff0000, v221
	v_lshlrev_b32_e32 v160, 16, v222
	v_and_b32_e32 v161, 0xffff0000, v222
	v_lshlrev_b32_e32 v162, 16, v223
	v_and_b32_e32 v163, 0xffff0000, v223
	v_pk_fma_f32 v[78:79], v[74:75], v[138:139], v[78:79]
	v_pk_fma_f32 v[76:77], v[72:73], v[136:137], v[76:77]
	v_pk_fma_f32 v[74:75], v[66:67], v[134:135], v[162:163]
	v_pk_fma_f32 v[72:73], v[64:65], v[132:133], v[160:161]
	v_cvt_pk_bf16_f32 v64, v76, v77
	v_cvt_pk_bf16_f32 v65, v78, v79
	s_nop 0
	v_cvt_pk_bf16_f32 v66, v72, v73
	v_cvt_pk_bf16_f32 v67, v74, v75
	flat_store_dwordx4 v[166:167], v[64:67] offset:256
	s_nop 1
	v_lshlrev_b32_e32 v160, 16, v224
	v_and_b32_e32 v161, 0xffff0000, v224
	v_lshlrev_b32_e32 v64, 16, v225
	v_and_b32_e32 v65, 0xffff0000, v225
	v_lshlrev_b32_e32 v162, 16, v226
	v_and_b32_e32 v163, 0xffff0000, v226
	v_lshlrev_b32_e32 v164, 16, v227
	v_and_b32_e32 v165, 0xffff0000, v227
	v_pk_fma_f32 v[66:67], v[130:131], v[146:147], v[64:65]
	v_pk_fma_f32 v[64:65], v[128:129], v[144:145], v[160:161]
	v_pk_fma_f32 v[70:71], v[70:71], v[142:143], v[164:165]
	v_pk_fma_f32 v[68:69], v[68:69], v[140:141], v[162:163]
	v_cvt_pk_bf16_f32 v128, v64, v65
	v_cvt_pk_bf16_f32 v129, v66, v67
	v_add_co_u32_e32 v164, vcc, s2, v154
	v_cvt_pk_bf16_f32 v130, v68, v69
	v_cvt_pk_bf16_f32 v131, v70, v71
	s_nop 0
	v_addc_co_u32_e32 v165, vcc, 0, v155, vcc
	flat_store_dwordx4 v[156:157], v[128:131]
	s_mov_b64 s[2:3], 0x80000
	s_nop 1
	v_lshlrev_b32_e32 v128, 16, v228
	v_and_b32_e32 v129, 0xffff0000, v228
	v_lshlrev_b32_e32 v130, 16, v229
	v_and_b32_e32 v131, 0xffff0000, v229
	v_lshlrev_b32_e32 v160, 16, v230
	v_and_b32_e32 v161, 0xffff0000, v230
	v_lshlrev_b32_e32 v162, 16, v231
	v_and_b32_e32 v163, 0xffff0000, v231
	v_pk_fma_f32 v[110:111], v[110:111], v[138:139], v[130:131]
	v_pk_fma_f32 v[108:109], v[108:109], v[136:137], v[128:129]
	v_pk_fma_f32 v[98:99], v[98:99], v[134:135], v[162:163]
	v_pk_fma_f32 v[96:97], v[96:97], v[132:133], v[160:161]
	v_cvt_pk_bf16_f32 v128, v108, v109
	v_cvt_pk_bf16_f32 v129, v110, v111
	s_nop 0
	v_cvt_pk_bf16_f32 v130, v96, v97
	v_cvt_pk_bf16_f32 v131, v98, v99
	flat_store_dwordx4 v[156:157], v[128:131] offset:256
	v_lshl_add_u64 v[156:157], v[154:155], 0, s[2:3]
	s_mov_b32 s2, 0x90000
	v_add_co_u32_e32 v166, vcc, s2, v154
	s_mov_b64 s[2:3], 0x90000
	s_nop 0
	v_addc_co_u32_e32 v167, vcc, 0, v155, vcc
	v_lshl_add_u64 v[232:233], v[232:233], 0, s[100:101]
	v_lshl_add_u64 v[234:235], v[234:235], 0, s[100:101]
	v_lshl_add_u64 v[236:237], v[236:237], 0, s[100:101]
	v_lshl_add_u64 v[238:239], v[238:239], 0, s[100:101]
	global_load_dwordx4 v[200:203], v[232:233], off
	global_load_dwordx4 v[204:207], v[232:233], off offset:256
	global_load_dwordx4 v[208:211], v[234:235], off
	global_load_dwordx4 v[212:215], v[234:235], off offset:256
	global_load_dwordx4 v[216:219], v[236:237], off
	global_load_dwordx4 v[220:223], v[236:237], off offset:256
	global_load_dwordx4 v[224:227], v[238:239], off
	global_load_dwordx4 v[228:231], v[238:239], off offset:256
	s_waitcnt vmcnt(0) lgkmcnt(0)
	v_lshlrev_b32_e32 v160, 16, v200
	v_and_b32_e32 v161, 0xffff0000, v200
	v_lshlrev_b32_e32 v128, 16, v201
	v_and_b32_e32 v129, 0xffff0000, v201
	v_lshlrev_b32_e32 v162, 16, v202
	v_and_b32_e32 v163, 0xffff0000, v202
	v_lshlrev_b32_e32 v130, 16, v203
	v_and_b32_e32 v131, 0xffff0000, v203
	v_pk_fma_f32 v[102:103], v[102:103], v[146:147], v[128:129]
	v_pk_fma_f32 v[100:101], v[100:101], v[144:145], v[160:161]
	v_pk_fma_f32 v[106:107], v[106:107], v[142:143], v[130:131]
	v_pk_fma_f32 v[104:105], v[104:105], v[140:141], v[162:163]
	v_cvt_pk_bf16_f32 v128, v100, v101
	v_cvt_pk_bf16_f32 v129, v102, v103
	s_nop 0
	v_cvt_pk_bf16_f32 v130, v104, v105
	v_cvt_pk_bf16_f32 v131, v106, v107
	s_nop 0
	flat_store_dwordx4 v[164:165], v[128:131]
	s_nop 1
	s_nop 0
	v_lshlrev_b32_e32 v128, 16, v204
	v_and_b32_e32 v129, 0xffff0000, v204
	v_lshlrev_b32_e32 v130, 16, v205
	v_and_b32_e32 v131, 0xffff0000, v205
	v_lshlrev_b32_e32 v160, 16, v206
	v_and_b32_e32 v161, 0xffff0000, v206
	v_lshlrev_b32_e32 v162, 16, v207
	v_and_b32_e32 v163, 0xffff0000, v207
	v_pk_fma_f32 v[126:127], v[126:127], v[138:139], v[130:131]
	v_pk_fma_f32 v[124:125], v[124:125], v[136:137], v[128:129]
	v_pk_fma_f32 v[114:115], v[114:115], v[134:135], v[162:163]
	v_pk_fma_f32 v[112:113], v[112:113], v[132:133], v[160:161]
	v_cvt_pk_bf16_f32 v128, v124, v125
	v_cvt_pk_bf16_f32 v129, v126, v127
	s_nop 0
	v_cvt_pk_bf16_f32 v130, v112, v113
	v_cvt_pk_bf16_f32 v131, v114, v115
	flat_store_dwordx4 v[156:157], v[128:131] offset:256
	v_lshl_add_u64 v[156:157], v[154:155], 0, s[2:3]
	s_mov_b32 s2, 0xa0000
	v_add_co_u32_e32 v164, vcc, s2, v154
	s_mov_b64 s[2:3], 0xa0000
	s_nop 0
	v_addc_co_u32_e32 v165, vcc, 0, v155, vcc
	s_nop 1
	v_lshlrev_b32_e32 v160, 16, v208
	v_and_b32_e32 v161, 0xffff0000, v208
	v_lshlrev_b32_e32 v128, 16, v209
	v_and_b32_e32 v129, 0xffff0000, v209
	v_lshlrev_b32_e32 v162, 16, v210
	v_and_b32_e32 v163, 0xffff0000, v210
	v_lshlrev_b32_e32 v130, 16, v211
	v_and_b32_e32 v131, 0xffff0000, v211
; __device__ __forceinline__ unsigned cvt_pk_bf16(float lo, float hi) { unsigned r; asm volatile("v_cvt_pk_bf16_f32 %0, %1, %2" : "=v"(r) : "v"(lo), "v"(hi)); return r; }
;     __device__ __forceinline__ void fused(f32x4 (&acc)[2][2][4][2], const Unit& un, int wr, int wc, int fr, int fq, PG8_LAS unsigned char* lds, int wid, int lane) const {
;     ...
;               for (int m = 0; m < 4; ++m) { const size_t off = (size_t)(row0 + ai * HALF + m * 16) * ldc + col0;
; #pragma unroll
;                   for (int bj = 0; bj < 2; ++bj) {
; #pragma unroll
;                       for (int n = 0; n < 2; ++n) { f32x4 bs;
;                           if (BASE_F32) bs = *(const f32x4*)((const float*)base + off + bj * HALF + n * 4);
;                           else { const u32x2v hw = *(const u32x2v*)((const bf16_t*)base + off + bj * HALF + n * 4);
;                                  bs = (f32x4){__uint_as_float(hw.x << 16), __uint_as_float(hw.x & 0xffff0000u), __uint_as_float(hw.y << 16), __uint_as_float(hw.y & 0xffff0000u)}; }
;                           acc[ai][bj][m][n] = bs + gv[bj][n] * acc[ai][bj][m][n]; }
;                       if (out_h) { const f32x4 a0 = acc[ai][bj][m][0], a1 = acc[ai][bj][m][1]; u32x4 w; w.x = cvt_pk_bf16(a0[0], a0[1]); w.y = cvt_pk_bf16(a0[2], a0[3]); w.z = cvt_pk_bf16(a1[0], a1[1]); w.w = cvt_pk_bf16(a1[2], a1[3]);
;                           *(u32x4*)(out_h + off + bj * HALF) = w; } }
;                   asm volatile("" : "+v"(acc[ai][0][m][0]), "+v"(acc[ai][0][m][1]), "+v"(acc[ai][1][m][0]), "+v"(acc[ai][1][m][1]));
;                   asm volatile("" ::: "memory"); } }
; #pragma unroll
;         for (int ai = 0; ai < 2; ++ai)
; #pragma unroll
;             for (int m = 0; m < 4; ++m) { float s = 0.f;
; #pragma unroll
;                 for (int bj = 0; bj < 2; ++bj)
; #pragma unroll
;                     for (int n = 0; n < 2; ++n) { const f32x4 x = acc[ai][bj][m][n]; s += (x[0] * x[0] + x[1] * x[1]) + (x[2] * x[2] + x[3] * x[3]); }
;                 s += __shfl_xor(s, 16); s += __shfl_xor(s, 32);
;                 if (fq == 0) P[(ai * HALF + wr * 64 + m * 16 + fr) * 4 + wc] = s; }
	v_pk_fma_f32 v[118:119], v[118:119], v[146:147], v[128:129]
	v_pk_fma_f32 v[116:117], v[116:117], v[144:145], v[160:161]
	v_pk_fma_f32 v[122:123], v[122:123], v[142:143], v[130:131]
	v_pk_fma_f32 v[120:121], v[120:121], v[140:141], v[162:163]
	v_cvt_pk_bf16_f32 v128, v116, v117
	v_cvt_pk_bf16_f32 v129, v118, v119
	s_nop 0
	v_cvt_pk_bf16_f32 v130, v120, v121
	v_cvt_pk_bf16_f32 v131, v122, v123
	s_nop 0
	flat_store_dwordx4 v[166:167], v[128:131]
	s_nop 1
	s_nop 0
	v_lshlrev_b32_e32 v128, 16, v212
	v_and_b32_e32 v129, 0xffff0000, v212
	v_lshlrev_b32_e32 v130, 16, v213
	v_and_b32_e32 v131, 0xffff0000, v213
	v_lshlrev_b32_e32 v160, 16, v214
	v_and_b32_e32 v161, 0xffff0000, v214
	v_lshlrev_b32_e32 v162, 16, v215
	v_and_b32_e32 v163, 0xffff0000, v215
	v_pk_fma_f32 v[94:95], v[94:95], v[138:139], v[130:131]
	v_pk_fma_f32 v[92:93], v[92:93], v[136:137], v[128:129]
	v_pk_fma_f32 v[90:91], v[90:91], v[134:135], v[162:163]
	v_pk_fma_f32 v[88:89], v[88:89], v[132:133], v[160:161]
	v_cvt_pk_bf16_f32 v128, v92, v93
	v_cvt_pk_bf16_f32 v129, v94, v95
	s_nop 0
	v_cvt_pk_bf16_f32 v130, v88, v89
	v_cvt_pk_bf16_f32 v131, v90, v91
	flat_store_dwordx4 v[156:157], v[128:131] offset:256
	v_lshl_add_u64 v[156:157], v[154:155], 0, s[2:3]
	s_mov_b32 s2, 0xb0000
	v_add_co_u32_e32 v166, vcc, s2, v154
	s_mov_b64 s[2:3], 0xb0000
	s_nop 0
	v_addc_co_u32_e32 v167, vcc, 0, v155, vcc
	s_nop 1
	v_lshlrev_b32_e32 v160, 16, v216
	v_and_b32_e32 v161, 0xffff0000, v216
	v_lshlrev_b32_e32 v128, 16, v217
	v_and_b32_e32 v129, 0xffff0000, v217
	v_lshlrev_b32_e32 v162, 16, v218
	v_and_b32_e32 v163, 0xffff0000, v218
	v_lshlrev_b32_e32 v130, 16, v219
	v_and_b32_e32 v131, 0xffff0000, v219
	v_pk_fma_f32 v[86:87], v[86:87], v[146:147], v[128:129]
	v_pk_fma_f32 v[84:85], v[84:85], v[144:145], v[160:161]
	v_pk_fma_f32 v[82:83], v[82:83], v[142:143], v[130:131]
	v_pk_fma_f32 v[80:81], v[80:81], v[140:141], v[162:163]
	v_cvt_pk_bf16_f32 v128, v84, v85
	v_cvt_pk_bf16_f32 v129, v86, v87
	s_nop 0
	v_cvt_pk_bf16_f32 v130, v80, v81
	v_cvt_pk_bf16_f32 v131, v82, v83
	s_nop 0
	flat_store_dwordx4 v[164:165], v[128:131]
	v_mul_f32_e32 v164, v25, v25
	v_mul_f32_e32 v165, v27, v27
	v_fmac_f32_e32 v164, v24, v24
	v_fmac_f32_e32 v165, v26, v26
	s_nop 1
	v_lshlrev_b32_e32 v128, 16, v220
	v_and_b32_e32 v129, 0xffff0000, v220
	v_lshlrev_b32_e32 v130, 16, v221
	v_and_b32_e32 v131, 0xffff0000, v221
	v_lshlrev_b32_e32 v160, 16, v222
	v_and_b32_e32 v161, 0xffff0000, v222
	v_lshlrev_b32_e32 v162, 16, v223
	v_and_b32_e32 v163, 0xffff0000, v223
	v_pk_fma_f32 v[46:47], v[46:47], v[138:139], v[130:131]
	v_pk_fma_f32 v[44:45], v[44:45], v[136:137], v[128:129]
	v_pk_fma_f32 v[42:43], v[42:43], v[134:135], v[162:163]
	v_pk_fma_f32 v[40:41], v[40:41], v[132:133], v[160:161]
	v_cvt_pk_bf16_f32 v128, v44, v45
	v_cvt_pk_bf16_f32 v129, v46, v47
	v_lshl_add_u64 v[160:161], v[154:155], 0, s[2:3]
	v_cvt_pk_bf16_f32 v130, v40, v41
	v_cvt_pk_bf16_f32 v131, v42, v43
	flat_store_dwordx4 v[156:157], v[128:131] offset:256
	v_mul_f32_e32 v162, v33, v33
	v_mul_f32_e32 v163, v35, v35
	v_fmac_f32_e32 v162, v32, v32
	v_fmac_f32_e32 v163, v34, v34
	s_lshl_b32 s2, s9, 2
	s_add_i32 s2, s2, 0
	s_nop 1
	v_lshlrev_b32_e32 v154, 16, v224
	v_and_b32_e32 v155, 0xffff0000, v224
	v_lshlrev_b32_e32 v128, 16, v225
	v_and_b32_e32 v129, 0xffff0000, v225
	v_lshlrev_b32_e32 v156, 16, v226
	v_and_b32_e32 v157, 0xffff0000, v226
	v_lshlrev_b32_e32 v130, 16, v227
	v_and_b32_e32 v131, 0xffff0000, v227
	v_pk_fma_f32 v[38:39], v[38:39], v[146:147], v[128:129]
	v_pk_fma_f32 v[36:37], v[36:37], v[144:145], v[154:155]
	v_pk_fma_f32 v[30:31], v[30:31], v[142:143], v[130:131]
	v_pk_fma_f32 v[28:29], v[28:29], v[140:141], v[156:157]
	v_cvt_pk_bf16_f32 v142, v36, v37
	v_cvt_pk_bf16_f32 v143, v38, v39
	v_mbcnt_lo_u32_b32 v128, -1, 0
	v_cvt_pk_bf16_f32 v144, v28, v29
	v_cvt_pk_bf16_f32 v145, v30, v31
	v_mbcnt_hi_u32_b32 v129, -1, v128
	v_mul_f32_e32 v140, v9, v9
	v_mul_f32_e32 v141, v11, v11
	v_mul_f32_e32 v146, v13, v13
	v_mul_f32_e32 v147, v15, v15
	v_and_b32_e32 v130, 64, v129
	v_fmac_f32_e32 v140, v8, v8
	v_fmac_f32_e32 v141, v10, v10
	v_fmac_f32_e32 v146, v12, v12
	v_fmac_f32_e32 v147, v14, v14
	v_xor_b32_e32 v128, 16, v129
	v_add_u32_e32 v130, 64, v130
	v_add_f32_e32 v140, v140, v141
	v_add_f32_e32 v141, v146, v147
	v_cmp_lt_i32_e32 vcc, v128, v130
	v_add_f32_e32 v146, v162, v163
	v_add_f32_e32 v140, v140, v141
	v_cndmask_b32_e32 v128, v129, v128, vcc
	v_add_f32_e32 v147, v164, v165
	v_add_f32_e32 v140, v146, v140
	v_lshlrev_b32_e32 v128, 2, v128
	v_add_f32_e32 v140, v147, v140
	ds_bpermute_b32 v141, v128, v140
	v_xor_b32_e32 v131, 32, v129
	v_cmp_lt_i32_e32 vcc, v131, v130
	flat_store_dwordx4 v[166:167], v[142:145]
	v_and_b32_e32 v130, 63, v158
	v_cndmask_b32_e32 v129, v129, v131, vcc
	v_lshlrev_b32_e32 v129, 2, v129
	s_waitcnt lgkmcnt(0)
	v_add_f32_e32 v140, v140, v141
	ds_bpermute_b32 v141, v129, v140
	v_cmp_gt_u32_e32 vcc, 16, v130
	s_waitcnt vmcnt(0)
	v_lshlrev_b32_e32 v142, 16, v228
	v_and_b32_e32 v143, 0xffff0000, v228
	v_lshlrev_b32_e32 v144, 16, v229
	v_and_b32_e32 v145, 0xffff0000, v229
	v_lshlrev_b32_e32 v146, 16, v230
	v_and_b32_e32 v147, 0xffff0000, v230
	v_lshlrev_b32_e32 v154, 16, v231
	v_and_b32_e32 v155, 0xffff0000, v231
	v_pk_fma_f32 v[6:7], v[6:7], v[138:139], v[144:145]
	v_pk_fma_f32 v[4:5], v[4:5], v[136:137], v[142:143]
	v_pk_fma_f32 v[2:3], v[2:3], v[134:135], v[154:155]
	v_pk_fma_f32 v[0:1], v[0:1], v[132:133], v[146:147]
	v_cvt_pk_bf16_f32 v132, v4, v5
	v_cvt_pk_bf16_f32 v133, v6, v7
	v_or_b32_e32 v144, s8, v159
	v_cvt_pk_bf16_f32 v134, v0, v1
	v_cvt_pk_bf16_f32 v135, v2, v3
	flat_store_dwordx4 v[160:161], v[132:135] offset:256
	v_lshl_add_u32 v131, v144, 4, s2
	s_and_saveexec_b64 s[2:3], vcc
	v_readlane_b32 s96, v254, 47
	s_cbranch_execz .LBB0_1846
	s_waitcnt lgkmcnt(0)
	v_add_f32_e32 v132, v140, v141
	ds_write_b32 v131, v132

; __device__ __forceinline__ unsigned cvt_pk_bf16(float lo, float hi) { unsigned r; asm volatile("v_cvt_pk_bf16_f32 %0, %1, %2" : "=v"(r) : "v"(lo), "v"(hi)); return r; }
;     __device__ __forceinline__ void fused(f32x4 (&acc)[2][2][4][2], const Unit& un, int wr, int wc, int fr, int fq, PG8_LAS unsigned char* lds, int wid, int lane) const {
;     ...
;         const int row0 = un.pm * BM + wr * 64 + fr, col0 = un.pn * BM + wc * 32 + 8 * fq;
;         const size_t boff = (size_t)(un.pm >> 3) * bstride + col0;
;         { f32x4 gv[2][2];
; #pragma unroll
;           for (int bj = 0; bj < 2; ++bj)
; #pragma unroll
;               for (int n = 0; n < 2; ++n) gv[bj][n] = *(const f32x4*)(gate + boff + bj * HALF + n * 4);
; #pragma unroll
;           for (int ai = 0; ai < 2; ++ai)
; #pragma unroll
;               for (int m = 0; m < 4; ++m) { const size_t off = (size_t)(row0 + ai * HALF + m * 16) * ldc + col0;
; #pragma unroll
;                   for (int bj = 0; bj < 2; ++bj) {
; #pragma unroll
;                       for (int n = 0; n < 2; ++n) { f32x4 bs;
;                           if (BASE_F32) bs = *(const f32x4*)((const float*)base + off + bj * HALF + n * 4);
;                           else { const u32x2v hw = *(const u32x2v*)((const bf16_t*)base + off + bj * HALF + n * 4);
;                                  bs = (f32x4){__uint_as_float(hw.x << 16), __uint_as_float(hw.x & 0xffff0000u), __uint_as_float(hw.y << 16), __uint_as_float(hw.y & 0xffff0000u)}; }
;                           acc[ai][bj][m][n] = bs + gv[bj][n] * acc[ai][bj][m][n]; }
;                       if (out_h) { const f32x4 a0 = acc[ai][bj][m][0], a1 = acc[ai][bj][m][1]; u32x4 w; w.x = cvt_pk_bf16(a0[0], a0[1]); w.y = cvt_pk_bf16(a0[2], a0[3]); w.z = cvt_pk_bf16(a1[0], a1[1]); w.w = cvt_pk_bf16(a1[2], a1[3]);
;                           *(u32x4*)(out_h + off + bj * HALF) = w; } }
;                   asm volatile("" : "+v"(acc[ai][0][m][0]), "+v"(acc[ai][0][m][1]), "+v"(acc[ai][1][m][0]), "+v"(acc[ai][1][m][1]));
.LBB0_2029:
	v_mov_b32_e32 v32, 0
	s_barrier
	s_lshl_b32 s6, s9, 5
	v_mbcnt_lo_u32_b32 v32, -1, v32
	s_add_u32 s2, s60, 0x1a600000
	v_mbcnt_hi_u32_b32 v32, -1, v32
	s_addc_u32 s3, s61, 0
	v_or_b32_e32 v158, s33, v32
	s_lshl_b32 s7, s4, 8
	s_lshl_b32 s14, s62, 8
	s_or_b32 s6, s7, s6
	v_lshrrev_b32_e32 v32, 1, v158
	v_and_b32_e32 v159, 15, v158
	s_add_i32 s15, s14, s8
	v_and_or_b32 v152, v32, 24, s6
	s_ashr_i32 s6, s62, 3
	v_ashrrev_i32_e32 v153, 31, v152
	v_mov_b32_e32 v32, 0x3000
	v_or_b32_e32 v156, s15, v159
	v_mad_i64_i32 v[32:33], s[6:7], s6, v32, v[152:153]
	v_ashrrev_i32_e32 v157, 31, v156
	v_lshl_add_u64 v[150:151], v[32:33], 2, s[60:61]
	v_lshlrev_b64 v[32:33], 12, v[156:157]
	v_lshl_add_u64 v[32:33], s[2:3], 0, v[32:33]
	v_lshlrev_b64 v[148:149], 1, v[152:153]
	s_mov_b32 s15, 0x13a000
	v_lshl_add_u64 v[154:155], v[32:33], 0, v[148:149]
	v_add_co_u32_e32 v132, vcc, s15, v150
	s_nop 0
	v_addc_co_u32_e32 v133, vcc, 0, v151, vcc
	s_mov_b64 s[6:7], 0x13a000
	flat_load_dwordx4 v[144:147], v[132:133]
	v_lshl_add_u64 v[132:133], v[150:151], 0, s[6:7]
	flat_load_dwordx4 v[140:143], v[132:133] offset:16
	flat_load_dwordx4 v[136:139], v[132:133] offset:512
	s_nop 0
	flat_load_dwordx4 v[132:135], v[132:133] offset:528
	v_or_b32_e32 v164, 16, v156
	v_ashrrev_i32_e32 v165, 31, v164
	v_lshlrev_b64 v[164:165], 12, v[164:165]
	v_lshl_add_u64 v[164:165], s[2:3], 0, v[164:165]
	v_lshl_add_u64 v[164:165], v[164:165], 0, v[148:149]
	s_mov_b64 s[98:99], 0x10000
	s_mov_b64 s[100:101], 0x80000
	v_lshl_add_u64 v[232:233], v[154:155], 0, 0
	v_lshl_add_u64 v[234:235], v[232:233], 0, s[98:99]
	v_lshl_add_u64 v[236:237], v[234:235], 0, s[98:99]
	v_lshl_add_u64 v[238:239], v[236:237], 0, s[98:99]
	global_load_dwordx4 v[200:203], v[232:233], off
	global_load_dwordx4 v[204:207], v[232:233], off offset:256
	global_load_dwordx4 v[208:211], v[234:235], off
	global_load_dwordx4 v[212:215], v[234:235], off offset:256
	global_load_dwordx4 v[216:219], v[236:237], off
	global_load_dwordx4 v[220:223], v[236:237], off offset:256
	global_load_dwordx4 v[224:227], v[238:239], off
	global_load_dwordx4 v[228:231], v[238:239], off offset:256
	s_waitcnt vmcnt(0) lgkmcnt(0)
	v_lshlrev_b32_e32 v160, 16, v200
	v_and_b32_e32 v161, 0xffff0000, v200
	v_lshlrev_b32_e32 v32, 16, v201
	v_and_b32_e32 v33, 0xffff0000, v201
	v_lshlrev_b32_e32 v162, 16, v202
	v_and_b32_e32 v163, 0xffff0000, v202
	v_lshlrev_b32_e32 v34, 16, v203
	v_and_b32_e32 v35, 0xffff0000, v203
	v_pk_fma_f32 v[10:11], v[10:11], v[146:147], v[32:33]
	v_pk_fma_f32 v[8:9], v[8:9], v[144:145], v[160:161]
	v_pk_fma_f32 v[14:15], v[14:15], v[142:143], v[34:35]
	v_pk_fma_f32 v[12:13], v[12:13], v[140:141], v[162:163]
	v_cvt_pk_bf16_f32 v32, v8, v9
	v_cvt_pk_bf16_f32 v33, v10, v11
	s_nop 0
	v_cvt_pk_bf16_f32 v34, v12, v13
	v_cvt_pk_bf16_f32 v35, v14, v15
	s_nop 0
	flat_store_dwordx4 v[154:155], v[32:35]
	s_nop 1
	s_nop 0
	v_lshlrev_b32_e32 v32, 16, v204
	v_and_b32_e32 v33, 0xffff0000, v204
	v_lshlrev_b32_e32 v34, 16, v205
	v_and_b32_e32 v35, 0xffff0000, v205
	v_lshlrev_b32_e32 v160, 16, v206
	v_and_b32_e32 v161, 0xffff0000, v206
	v_lshlrev_b32_e32 v162, 16, v207
	v_and_b32_e32 v163, 0xffff0000, v207
	v_pk_fma_f32 v[34:35], v[30:31], v[138:139], v[34:35]
	v_pk_fma_f32 v[32:33], v[28:29], v[136:137], v[32:33]
	v_pk_fma_f32 v[30:31], v[18:19], v[134:135], v[162:163]
	v_pk_fma_f32 v[28:29], v[16:17], v[132:133], v[160:161]
	v_cvt_pk_bf16_f32 v16, v32, v33
	v_cvt_pk_bf16_f32 v17, v34, v35
	s_nop 0
	v_cvt_pk_bf16_f32 v18, v28, v29
	v_cvt_pk_bf16_f32 v19, v30, v31
	flat_store_dwordx4 v[154:155], v[16:19] offset:256
	s_nop 1
	v_lshlrev_b32_e32 v160, 16, v208
	v_and_b32_e32 v161, 0xffff0000, v208
	v_lshlrev_b32_e32 v16, 16, v209
	v_and_b32_e32 v17, 0xffff0000, v209
	v_lshlrev_b32_e32 v162, 16, v210
	v_and_b32_e32 v163, 0xffff0000, v210
	v_lshlrev_b32_e32 v166, 16, v211
	v_and_b32_e32 v167, 0xffff0000, v211
	v_pk_fma_f32 v[18:19], v[62:63], v[146:147], v[16:17]
	v_pk_fma_f32 v[16:17], v[60:61], v[144:145], v[160:161]
	v_pk_fma_f32 v[22:23], v[22:23], v[142:143], v[166:167]
	v_pk_fma_f32 v[20:21], v[20:21], v[140:141], v[162:163]
	v_cvt_pk_bf16_f32 v60, v16, v17
	v_cvt_pk_bf16_f32 v61, v18, v19
	v_or_b32_e32 v166, 32, v156
	v_cvt_pk_bf16_f32 v62, v20, v21
	v_cvt_pk_bf16_f32 v63, v22, v23
	v_ashrrev_i32_e32 v167, 31, v166
	v_lshlrev_b64 v[166:167], 12, v[166:167]
	flat_store_dwordx4 v[164:165], v[60:63]
	v_lshl_add_u64 v[166:167], s[2:3], 0, v[166:167]
	v_lshl_add_u64 v[166:167], v[166:167], 0, v[148:149]
	v_or_b32_e32 v156, 48, v156
	v_ashrrev_i32_e32 v157, 31, v156
	v_lshlrev_b64 v[156:157], 12, v[156:157]
	v_lshl_add_u64 v[156:157], s[2:3], 0, v[156:157]
	v_lshl_add_u64 v[156:157], v[156:157], 0, v[148:149]
	s_mov_b32 s2, 0x80000
	s_nop 1
	v_lshlrev_b32_e32 v60, 16, v212
	v_and_b32_e32 v61, 0xffff0000, v212
	v_lshlrev_b32_e32 v62, 16, v213
	v_and_b32_e32 v63, 0xffff0000, v213
	v_lshlrev_b32_e32 v160, 16, v214
	v_and_b32_e32 v161, 0xffff0000, v214
	v_lshlrev_b32_e32 v162, 16, v215
	v_and_b32_e32 v163, 0xffff0000, v215
	v_pk_fma_f32 v[62:63], v[58:59], v[138:139], v[62:63]
	v_pk_fma_f32 v[60:61], v[56:57], v[136:137], v[60:61]
	v_pk_fma_f32 v[58:59], v[50:51], v[134:135], v[162:163]
	v_pk_fma_f32 v[56:57], v[48:49], v[132:133], v[160:161]
	v_cvt_pk_bf16_f32 v48, v60, v61
	v_cvt_pk_bf16_f32 v49, v62, v63
	s_nop 0
	v_cvt_pk_bf16_f32 v50, v56, v57
	v_cvt_pk_bf16_f32 v51, v58, v59
	flat_store_dwordx4 v[164:165], v[48:51] offset:256
	s_nop 1
	v_lshlrev_b32_e32 v160, 16, v216
	v_and_b32_e32 v161, 0xffff0000, v216
	v_lshlrev_b32_e32 v48, 16, v217
	v_and_b32_e32 v49, 0xffff0000, v217
	v_lshlrev_b32_e32 v162, 16, v218
	v_and_b32_e32 v163, 0xffff0000, v218
; __device__ __forceinline__ unsigned cvt_pk_bf16(float lo, float hi) { unsigned r; asm volatile("v_cvt_pk_bf16_f32 %0, %1, %2" : "=v"(r) : "v"(lo), "v"(hi)); return r; }
;     __device__ __forceinline__ void fused(f32x4 (&acc)[2][2][4][2], const Unit& un, int wr, int wc, int fr, int fq, PG8_LAS unsigned char* lds, int wid, int lane) const {
;     ...
;           for (int ai = 0; ai < 2; ++ai)
; #pragma unroll
;               for (int m = 0; m < 4; ++m) { const size_t off = (size_t)(row0 + ai * HALF + m * 16) * ldc + col0;
; #pragma unroll
;                   for (int bj = 0; bj < 2; ++bj) {
; #pragma unroll
;                       for (int n = 0; n < 2; ++n) { f32x4 bs;
;                           if (BASE_F32) bs = *(const f32x4*)((const float*)base + off + bj * HALF + n * 4);
;                           else { const u32x2v hw = *(const u32x2v*)((const bf16_t*)base + off + bj * HALF + n * 4);
;                                  bs = (f32x4){__uint_as_float(hw.x << 16), __uint_as_float(hw.x & 0xffff0000u), __uint_as_float(hw.y << 16), __uint_as_float(hw.y & 0xffff0000u)}; }
;                           acc[ai][bj][m][n] = bs + gv[bj][n] * acc[ai][bj][m][n]; }
;                       if (out_h) { const f32x4 a0 = acc[ai][bj][m][0], a1 = acc[ai][bj][m][1]; u32x4 w; w.x = cvt_pk_bf16(a0[0], a0[1]); w.y = cvt_pk_bf16(a0[2], a0[3]); w.z = cvt_pk_bf16(a1[0], a1[1]); w.w = cvt_pk_bf16(a1[2], a1[3]);
;                           *(u32x4*)(out_h + off + bj * HALF) = w; } }
;                   asm volatile("" : "+v"(acc[ai][0][m][0]), "+v"(acc[ai][0][m][1]), "+v"(acc[ai][1][m][0]), "+v"(acc[ai][1][m][1]));
	v_lshlrev_b32_e32 v164, 16, v219
	v_and_b32_e32 v165, 0xffff0000, v219
	v_pk_fma_f32 v[50:51], v[78:79], v[146:147], v[48:49]
	v_pk_fma_f32 v[48:49], v[76:77], v[144:145], v[160:161]
	v_pk_fma_f32 v[54:55], v[54:55], v[142:143], v[164:165]
	v_pk_fma_f32 v[52:53], v[52:53], v[140:141], v[162:163]
	v_cvt_pk_bf16_f32 v76, v48, v49
	v_cvt_pk_bf16_f32 v77, v50, v51
	s_nop 0
	v_cvt_pk_bf16_f32 v78, v52, v53
	v_cvt_pk_bf16_f32 v79, v54, v55
	s_nop 0
	flat_store_dwordx4 v[166:167], v[76:79]
	s_nop 1
	s_nop 0
	v_lshlrev_b32_e32 v76, 16, v220
	v_and_b32_e32 v77, 0xffff0000, v220
	v_lshlrev_b32_e32 v78, 16, v221
	v_and_b32_e32 v79, 0xffff0000, v221
	v_lshlrev_b32_e32 v160, 16, v222
	v_and_b32_e32 v161, 0xffff0000, v222
	v_lshlrev_b32_e32 v162, 16, v223
	v_and_b32_e32 v163, 0xffff0000, v223
	v_pk_fma_f32 v[78:79], v[74:75], v[138:139], v[78:79]
	v_pk_fma_f32 v[76:77], v[72:73], v[136:137], v[76:77]
	v_pk_fma_f32 v[74:75], v[66:67], v[134:135], v[162:163]
	v_pk_fma_f32 v[72:73], v[64:65], v[132:133], v[160:161]
	v_cvt_pk_bf16_f32 v64, v76, v77
	v_cvt_pk_bf16_f32 v65, v78, v79
	s_nop 0
	v_cvt_pk_bf16_f32 v66, v72, v73
	v_cvt_pk_bf16_f32 v67, v74, v75
	flat_store_dwordx4 v[166:167], v[64:67] offset:256
	s_nop 1
	v_lshlrev_b32_e32 v160, 16, v224
	v_and_b32_e32 v161, 0xffff0000, v224
	v_lshlrev_b32_e32 v64, 16, v225
	v_and_b32_e32 v65, 0xffff0000, v225
	v_lshlrev_b32_e32 v162, 16, v226
	v_and_b32_e32 v163, 0xffff0000, v226
	v_lshlrev_b32_e32 v164, 16, v227
	v_and_b32_e32 v165, 0xffff0000, v227
	v_pk_fma_f32 v[66:67], v[130:131], v[146:147], v[64:65]
	v_pk_fma_f32 v[64:65], v[128:129], v[144:145], v[160:161]
	v_pk_fma_f32 v[70:71], v[70:71], v[142:143], v[164:165]
	v_pk_fma_f32 v[68:69], v[68:69], v[140:141], v[162:163]
	v_cvt_pk_bf16_f32 v128, v64, v65
	v_cvt_pk_bf16_f32 v129, v66, v67
	v_add_co_u32_e32 v164, vcc, s2, v154
	v_cvt_pk_bf16_f32 v130, v68, v69
	v_cvt_pk_bf16_f32 v131, v70, v71
	s_nop 0
	v_addc_co_u32_e32 v165, vcc, 0, v155, vcc
	flat_store_dwordx4 v[156:157], v[128:131]
	s_mov_b64 s[2:3], 0x80000
	s_nop 1
	v_lshlrev_b32_e32 v128, 16, v228
	v_and_b32_e32 v129, 0xffff0000, v228
	v_lshlrev_b32_e32 v130, 16, v229
	v_and_b32_e32 v131, 0xffff0000, v229
	v_lshlrev_b32_e32 v160, 16, v230
	v_and_b32_e32 v161, 0xffff0000, v230
	v_lshlrev_b32_e32 v162, 16, v231
	v_and_b32_e32 v163, 0xffff0000, v231
	v_pk_fma_f32 v[110:111], v[110:111], v[138:139], v[130:131]
	v_pk_fma_f32 v[108:109], v[108:109], v[136:137], v[128:129]
	v_pk_fma_f32 v[98:99], v[98:99], v[134:135], v[162:163]
	v_pk_fma_f32 v[96:97], v[96:97], v[132:133], v[160:161]
	v_cvt_pk_bf16_f32 v128, v108, v109
	v_cvt_pk_bf16_f32 v129, v110, v111
	s_nop 0
	v_cvt_pk_bf16_f32 v130, v96, v97
	v_cvt_pk_bf16_f32 v131, v98, v99
	flat_store_dwordx4 v[156:157], v[128:131] offset:256
	v_lshl_add_u64 v[156:157], v[154:155], 0, s[2:3]
	s_mov_b32 s2, 0x90000
	v_add_co_u32_e32 v166, vcc, s2, v154
	s_mov_b64 s[2:3], 0x90000
	s_nop 0
	v_addc_co_u32_e32 v167, vcc, 0, v155, vcc
	v_lshl_add_u64 v[232:233], v[232:233], 0, s[100:101]
	v_lshl_add_u64 v[234:235], v[234:235], 0, s[100:101]
	v_lshl_add_u64 v[236:237], v[236:237], 0, s[100:101]
	v_lshl_add_u64 v[238:239], v[238:239], 0, s[100:101]
	global_load_dwordx4 v[200:203], v[232:233], off
	global_load_dwordx4 v[204:207], v[232:233], off offset:256
	global_load_dwordx4 v[208:211], v[234:235], off
	global_load_dwordx4 v[212:215], v[234:235], off offset:256
	global_load_dwordx4 v[216:219], v[236:237], off
	global_load_dwordx4 v[220:223], v[236:237], off offset:256
	global_load_dwordx4 v[224:227], v[238:239], off
	global_load_dwordx4 v[228:231], v[238:239], off offset:256
	s_waitcnt vmcnt(0) lgkmcnt(0)
	v_lshlrev_b32_e32 v160, 16, v200
	v_and_b32_e32 v161, 0xffff0000, v200
	v_lshlrev_b32_e32 v128, 16, v201
	v_and_b32_e32 v129, 0xffff0000, v201
	v_lshlrev_b32_e32 v162, 16, v202
	v_and_b32_e32 v163, 0xffff0000, v202
	v_lshlrev_b32_e32 v130, 16, v203
	v_and_b32_e32 v131, 0xffff0000, v203
	v_pk_fma_f32 v[102:103], v[102:103], v[146:147], v[128:129]
	v_pk_fma_f32 v[100:101], v[100:101], v[144:145], v[160:161]
	v_pk_fma_f32 v[106:107], v[106:107], v[142:143], v[130:131]
	v_pk_fma_f32 v[104:105], v[104:105], v[140:141], v[162:163]
	v_cvt_pk_bf16_f32 v128, v100, v101
	v_cvt_pk_bf16_f32 v129, v102, v103
	s_nop 0
	v_cvt_pk_bf16_f32 v130, v104, v105
	v_cvt_pk_bf16_f32 v131, v106, v107
	s_nop 0
	flat_store_dwordx4 v[164:165], v[128:131]
	s_nop 1
	s_nop 0
	v_lshlrev_b32_e32 v128, 16, v204
	v_and_b32_e32 v129, 0xffff0000, v204
	v_lshlrev_b32_e32 v130, 16, v205
	v_and_b32_e32 v131, 0xffff0000, v205
	v_lshlrev_b32_e32 v160, 16, v206
	v_and_b32_e32 v161, 0xffff0000, v206
	v_lshlrev_b32_e32 v162, 16, v207
	v_and_b32_e32 v163, 0xffff0000, v207
	v_pk_fma_f32 v[126:127], v[126:127], v[138:139], v[130:131]
	v_pk_fma_f32 v[124:125], v[124:125], v[136:137], v[128:129]
	v_pk_fma_f32 v[114:115], v[114:115], v[134:135], v[162:163]
	v_pk_fma_f32 v[112:113], v[112:113], v[132:133], v[160:161]
	v_cvt_pk_bf16_f32 v128, v124, v125
	v_cvt_pk_bf16_f32 v129, v126, v127
	s_nop 0
	v_cvt_pk_bf16_f32 v130, v112, v113
	v_cvt_pk_bf16_f32 v131, v114, v115
	flat_store_dwordx4 v[156:157], v[128:131] offset:256
	v_lshl_add_u64 v[156:157], v[154:155], 0, s[2:3]
	s_mov_b32 s2, 0xa0000
	v_add_co_u32_e32 v164, vcc, s2, v154
	s_mov_b64 s[2:3], 0xa0000
	s_nop 0
	v_addc_co_u32_e32 v165, vcc, 0, v155, vcc
	s_nop 1
	v_lshlrev_b32_e32 v160, 16, v208
	v_and_b32_e32 v161, 0xffff0000, v208
	v_lshlrev_b32_e32 v128, 16, v209
	v_and_b32_e32 v129, 0xffff0000, v209
	v_lshlrev_b32_e32 v162, 16, v210
	v_and_b32_e32 v163, 0xffff0000, v210
	v_lshlrev_b32_e32 v130, 16, v211
	v_and_b32_e32 v131, 0xffff0000, v211
; __device__ __forceinline__ unsigned cvt_pk_bf16(float lo, float hi) { unsigned r; asm volatile("v_cvt_pk_bf16_f32 %0, %1, %2" : "=v"(r) : "v"(lo), "v"(hi)); return r; }
;     __device__ __forceinline__ void fused(f32x4 (&acc)[2][2][4][2], const Unit& un, int wr, int wc, int fr, int fq, PG8_LAS unsigned char* lds, int wid, int lane) const {
;     ...
;           for (int ai = 0; ai < 2; ++ai)
; #pragma unroll
;               for (int m = 0; m < 4; ++m) { const size_t off = (size_t)(row0 + ai * HALF + m * 16) * ldc + col0;
; #pragma unroll
;                   for (int bj = 0; bj < 2; ++bj) {
; #pragma unroll
;                       for (int n = 0; n < 2; ++n) { f32x4 bs;
;                           if (BASE_F32) bs = *(const f32x4*)((const float*)base + off + bj * HALF + n * 4);
;                           else { const u32x2v hw = *(const u32x2v*)((const bf16_t*)base + off + bj * HALF + n * 4);
;                                  bs = (f32x4){__uint_as_float(hw.x << 16), __uint_as_float(hw.x & 0xffff0000u), __uint_as_float(hw.y << 16), __uint_as_float(hw.y & 0xffff0000u)}; }
;                           acc[ai][bj][m][n] = bs + gv[bj][n] * acc[ai][bj][m][n]; }
;                       if (out_h) { const f32x4 a0 = acc[ai][bj][m][0], a1 = acc[ai][bj][m][1]; u32x4 w; w.x = cvt_pk_bf16(a0[0], a0[1]); w.y = cvt_pk_bf16(a0[2], a0[3]); w.z = cvt_pk_bf16(a1[0], a1[1]); w.w = cvt_pk_bf16(a1[2], a1[3]);
;                           *(u32x4*)(out_h + off + bj * HALF) = w; } }
;                   asm volatile("" : "+v"(acc[ai][0][m][0]), "+v"(acc[ai][0][m][1]), "+v"(acc[ai][1][m][0]), "+v"(acc[ai][1][m][1]));
;                   asm volatile("" ::: "memory"); } }
; #pragma unroll
;         for (int ai = 0; ai < 2; ++ai)
; #pragma unroll
;             for (int m = 0; m < 4; ++m) { float s = 0.f;
; #pragma unroll
;                 for (int bj = 0; bj < 2; ++bj)
; #pragma unroll
;                     for (int n = 0; n < 2; ++n) { const f32x4 x = acc[ai][bj][m][n]; s += (x[0] * x[0] + x[1] * x[1]) + (x[2] * x[2] + x[3] * x[3]); }
;                 s += __shfl_xor(s, 16); s += __shfl_xor(s, 32);
;                 if (fq == 0) P[(ai * HALF + wr * 64 + m * 16 + fr) * 4 + wc] = s; }
	v_pk_fma_f32 v[118:119], v[118:119], v[146:147], v[128:129]
	v_pk_fma_f32 v[116:117], v[116:117], v[144:145], v[160:161]
	v_pk_fma_f32 v[122:123], v[122:123], v[142:143], v[130:131]
	v_pk_fma_f32 v[120:121], v[120:121], v[140:141], v[162:163]
	v_cvt_pk_bf16_f32 v128, v116, v117
	v_cvt_pk_bf16_f32 v129, v118, v119
	s_nop 0
	v_cvt_pk_bf16_f32 v130, v120, v121
	v_cvt_pk_bf16_f32 v131, v122, v123
	s_nop 0
	flat_store_dwordx4 v[166:167], v[128:131]
	s_nop 1
	s_nop 0
	v_lshlrev_b32_e32 v128, 16, v212
	v_and_b32_e32 v129, 0xffff0000, v212
	v_lshlrev_b32_e32 v130, 16, v213
	v_and_b32_e32 v131, 0xffff0000, v213
	v_lshlrev_b32_e32 v160, 16, v214
	v_and_b32_e32 v161, 0xffff0000, v214
	v_lshlrev_b32_e32 v162, 16, v215
	v_and_b32_e32 v163, 0xffff0000, v215
	v_pk_fma_f32 v[94:95], v[94:95], v[138:139], v[130:131]
	v_pk_fma_f32 v[92:93], v[92:93], v[136:137], v[128:129]
	v_pk_fma_f32 v[90:91], v[90:91], v[134:135], v[162:163]
	v_pk_fma_f32 v[88:89], v[88:89], v[132:133], v[160:161]
	v_cvt_pk_bf16_f32 v128, v92, v93
	v_cvt_pk_bf16_f32 v129, v94, v95
	s_nop 0
	v_cvt_pk_bf16_f32 v130, v88, v89
	v_cvt_pk_bf16_f32 v131, v90, v91
	flat_store_dwordx4 v[156:157], v[128:131] offset:256
	v_lshl_add_u64 v[156:157], v[154:155], 0, s[2:3]
	s_mov_b32 s2, 0xb0000
	v_add_co_u32_e32 v166, vcc, s2, v154
	s_mov_b64 s[2:3], 0xb0000
	s_nop 0
	v_addc_co_u32_e32 v167, vcc, 0, v155, vcc
	s_nop 1
	v_lshlrev_b32_e32 v160, 16, v216
	v_and_b32_e32 v161, 0xffff0000, v216
	v_lshlrev_b32_e32 v128, 16, v217
	v_and_b32_e32 v129, 0xffff0000, v217
	v_lshlrev_b32_e32 v162, 16, v218
	v_and_b32_e32 v163, 0xffff0000, v218
	v_lshlrev_b32_e32 v130, 16, v219
	v_and_b32_e32 v131, 0xffff0000, v219
	v_pk_fma_f32 v[86:87], v[86:87], v[146:147], v[128:129]
	v_pk_fma_f32 v[84:85], v[84:85], v[144:145], v[160:161]
	v_pk_fma_f32 v[82:83], v[82:83], v[142:143], v[130:131]
	v_pk_fma_f32 v[80:81], v[80:81], v[140:141], v[162:163]
	v_cvt_pk_bf16_f32 v128, v84, v85
	v_cvt_pk_bf16_f32 v129, v86, v87
	s_nop 0
	v_cvt_pk_bf16_f32 v130, v80, v81
	v_cvt_pk_bf16_f32 v131, v82, v83
	s_nop 0
	flat_store_dwordx4 v[164:165], v[128:131]
	v_mul_f32_e32 v164, v29, v29
	v_mul_f32_e32 v165, v31, v31
	v_fmac_f32_e32 v164, v28, v28
	v_fmac_f32_e32 v165, v30, v30
	s_nop 1
	v_lshlrev_b32_e32 v128, 16, v220
	v_and_b32_e32 v129, 0xffff0000, v220
	v_lshlrev_b32_e32 v130, 16, v221
	v_and_b32_e32 v131, 0xffff0000, v221
	v_lshlrev_b32_e32 v160, 16, v222
	v_and_b32_e32 v161, 0xffff0000, v222
	v_lshlrev_b32_e32 v162, 16, v223
	v_and_b32_e32 v163, 0xffff0000, v223
	v_pk_fma_f32 v[46:47], v[46:47], v[138:139], v[130:131]
	v_pk_fma_f32 v[44:45], v[44:45], v[136:137], v[128:129]
	v_pk_fma_f32 v[42:43], v[42:43], v[134:135], v[162:163]
	v_pk_fma_f32 v[40:41], v[40:41], v[132:133], v[160:161]
	v_cvt_pk_bf16_f32 v128, v44, v45
	v_cvt_pk_bf16_f32 v129, v46, v47
	v_lshl_add_u64 v[160:161], v[154:155], 0, s[2:3]
	v_cvt_pk_bf16_f32 v130, v40, v41
	v_cvt_pk_bf16_f32 v131, v42, v43
	flat_store_dwordx4 v[156:157], v[128:131] offset:256
	v_mul_f32_e32 v162, v33, v33
	v_mul_f32_e32 v163, v35, v35
	v_fmac_f32_e32 v162, v32, v32
	v_fmac_f32_e32 v163, v34, v34
	s_lshl_b32 s2, s9, 2
	s_add_i32 s2, s2, 0
	s_nop 1
	v_lshlrev_b32_e32 v154, 16, v224
	v_and_b32_e32 v155, 0xffff0000, v224
	v_lshlrev_b32_e32 v128, 16, v225
	v_and_b32_e32 v129, 0xffff0000, v225
	v_lshlrev_b32_e32 v156, 16, v226
	v_and_b32_e32 v157, 0xffff0000, v226
	v_lshlrev_b32_e32 v130, 16, v227
	v_and_b32_e32 v131, 0xffff0000, v227
	v_pk_fma_f32 v[38:39], v[38:39], v[146:147], v[128:129]
	v_pk_fma_f32 v[36:37], v[36:37], v[144:145], v[154:155]
	v_pk_fma_f32 v[26:27], v[26:27], v[142:143], v[130:131]
	v_pk_fma_f32 v[24:25], v[24:25], v[140:141], v[156:157]
	v_cvt_pk_bf16_f32 v142, v36, v37
	v_cvt_pk_bf16_f32 v143, v38, v39
	v_mbcnt_lo_u32_b32 v128, -1, 0
	v_cvt_pk_bf16_f32 v144, v24, v25
	v_cvt_pk_bf16_f32 v145, v26, v27
	v_mbcnt_hi_u32_b32 v129, -1, v128
	v_mul_f32_e32 v140, v9, v9
	v_mul_f32_e32 v141, v11, v11
	v_mul_f32_e32 v146, v13, v13
	v_mul_f32_e32 v147, v15, v15
	v_and_b32_e32 v130, 64, v129
	v_fmac_f32_e32 v140, v8, v8
	v_fmac_f32_e32 v141, v10, v10
	v_fmac_f32_e32 v146, v12, v12
	v_fmac_f32_e32 v147, v14, v14
	v_xor_b32_e32 v128, 16, v129
	v_add_u32_e32 v130, 64, v130
	v_add_f32_e32 v140, v140, v141
	v_add_f32_e32 v141, v146, v147
	v_cmp_lt_i32_e32 vcc, v128, v130
	v_add_f32_e32 v146, v162, v163
	v_add_f32_e32 v140, v140, v141
	v_cndmask_b32_e32 v128, v129, v128, vcc
	v_add_f32_e32 v147, v164, v165
	v_add_f32_e32 v140, v146, v140
	v_lshlrev_b32_e32 v128, 2, v128
	v_add_f32_e32 v140, v147, v140
	ds_bpermute_b32 v141, v128, v140
	v_xor_b32_e32 v131, 32, v129
	v_cmp_lt_i32_e32 vcc, v131, v130
	flat_store_dwordx4 v[166:167], v[142:145]
	v_and_b32_e32 v130, 63, v158
	v_cndmask_b32_e32 v129, v129, v131, vcc
	v_lshlrev_b32_e32 v129, 2, v129
	s_waitcnt lgkmcnt(0)
	v_add_f32_e32 v140, v140, v141
	ds_bpermute_b32 v141, v129, v140
	v_cmp_gt_u32_e32 vcc, 16, v130
	s_waitcnt vmcnt(0)
	v_lshlrev_b32_e32 v142, 16, v228
	v_and_b32_e32 v143, 0xffff0000, v228
	v_lshlrev_b32_e32 v144, 16, v229
	v_and_b32_e32 v145, 0xffff0000, v229
	v_lshlrev_b32_e32 v146, 16, v230
	v_and_b32_e32 v147, 0xffff0000, v230
	v_lshlrev_b32_e32 v154, 16, v231
	v_and_b32_e32 v155, 0xffff0000, v231
	v_pk_fma_f32 v[6:7], v[6:7], v[138:139], v[144:145]
	v_pk_fma_f32 v[4:5], v[4:5], v[136:137], v[142:143]
	v_pk_fma_f32 v[2:3], v[2:3], v[134:135], v[154:155]
	v_pk_fma_f32 v[0:1], v[0:1], v[132:133], v[146:147]
	v_cvt_pk_bf16_f32 v132, v4, v5
	v_cvt_pk_bf16_f32 v133, v6, v7
	v_or_b32_e32 v144, s8, v159
	v_cvt_pk_bf16_f32 v134, v0, v1
	v_cvt_pk_bf16_f32 v135, v2, v3
	flat_store_dwordx4 v[160:161], v[132:135] offset:256
	v_lshl_add_u32 v131, v144, 4, s2
	s_and_saveexec_b64 s[2:3], vcc
	v_readlane_b32 s96, v254, 47
	s_cbranch_execz .LBB0_2031
	s_waitcnt lgkmcnt(0)
	v_add_f32_e32 v132, v140, v141
	ds_write_b32 v131, v132

; __device__ __forceinline__ unsigned cvt_pk_bf16(float lo, float hi) { unsigned r; asm volatile("v_cvt_pk_bf16_f32 %0, %1, %2" : "=v"(r) : "v"(lo), "v"(hi)); return r; }
;     __device__ __forceinline__ void fused(f32x4 (&acc)[2][2][4][2], const Unit& un, int wr, int wc, int fr, int fq, PG8_LAS unsigned char* lds, int wid, int lane) const {
;     ...
;         const int row0 = un.pm * BM + wr * 64 + fr, col0 = un.pn * BM + wc * 32 + 8 * fq;
;         const size_t boff = (size_t)(un.pm >> 3) * bstride + col0;
;         { f32x4 gv[2][2];
; #pragma unroll
;           for (int bj = 0; bj < 2; ++bj)
; #pragma unroll
;               for (int n = 0; n < 2; ++n) gv[bj][n] = *(const f32x4*)(gate + boff + bj * HALF + n * 4);
; #pragma unroll
;           for (int ai = 0; ai < 2; ++ai)
; #pragma unroll
;               for (int m = 0; m < 4; ++m) { const size_t off = (size_t)(row0 + ai * HALF + m * 16) * ldc + col0;
; #pragma unroll
;                   for (int bj = 0; bj < 2; ++bj) {
; #pragma unroll
;                       for (int n = 0; n < 2; ++n) { f32x4 bs;
;                           if (BASE_F32) bs = *(const f32x4*)((const float*)base + off + bj * HALF + n * 4);
;                           else { const u32x2v hw = *(const u32x2v*)((const bf16_t*)base + off + bj * HALF + n * 4);
;                                  bs = (f32x4){__uint_as_float(hw.x << 16), __uint_as_float(hw.x & 0xffff0000u), __uint_as_float(hw.y << 16), __uint_as_float(hw.y & 0xffff0000u)}; }
;                           acc[ai][bj][m][n] = bs + gv[bj][n] * acc[ai][bj][m][n]; }
;                       if (out_h) { const f32x4 a0 = acc[ai][bj][m][0], a1 = acc[ai][bj][m][1]; u32x4 w; w.x = cvt_pk_bf16(a0[0], a0[1]); w.y = cvt_pk_bf16(a0[2], a0[3]); w.z = cvt_pk_bf16(a1[0], a1[1]); w.w = cvt_pk_bf16(a1[2], a1[3]);
;                           *(u32x4*)(out_h + off + bj * HALF) = w; } }
;                   asm volatile("" : "+v"(acc[ai][0][m][0]), "+v"(acc[ai][0][m][1]), "+v"(acc[ai][1][m][0]), "+v"(acc[ai][1][m][1]));
.LBB0_2732:
	v_mov_b32_e32 v32, 0
	s_barrier
	s_lshl_b32 s6, s9, 5
	v_mbcnt_lo_u32_b32 v32, -1, v32
	s_add_u32 s2, s44, 0x1a600000
	v_mbcnt_hi_u32_b32 v32, -1, v32
	s_addc_u32 s3, s45, 0
	v_or_b32_e32 v158, s33, v32
	s_lshl_b32 s7, s4, 8
	s_lshl_b32 s14, s46, 8
	s_or_b32 s6, s7, s6
	v_lshrrev_b32_e32 v32, 1, v158
	v_and_b32_e32 v159, 15, v158
	s_add_i32 s15, s14, s8
	v_and_or_b32 v152, v32, 24, s6
	s_ashr_i32 s6, s46, 3
	v_ashrrev_i32_e32 v153, 31, v152
	v_mov_b32_e32 v32, 0x3000
	v_or_b32_e32 v156, s15, v159
	v_mad_i64_i32 v[32:33], s[6:7], s6, v32, v[152:153]
	v_ashrrev_i32_e32 v157, 31, v156
	v_lshl_add_u64 v[150:151], v[32:33], 2, s[44:45]
	v_lshlrev_b64 v[32:33], 12, v[156:157]
	v_lshl_add_u64 v[32:33], s[2:3], 0, v[32:33]
	v_lshlrev_b64 v[148:149], 1, v[152:153]
	s_mov_b32 s15, 0x164000
	v_lshl_add_u64 v[154:155], v[32:33], 0, v[148:149]
	v_add_co_u32_e32 v132, vcc, s15, v150
	s_nop 0
	v_addc_co_u32_e32 v133, vcc, 0, v151, vcc
	s_mov_b64 s[6:7], 0x164000
	flat_load_dwordx4 v[144:147], v[132:133]
	v_lshl_add_u64 v[132:133], v[150:151], 0, s[6:7]
	flat_load_dwordx4 v[140:143], v[132:133] offset:16
	flat_load_dwordx4 v[136:139], v[132:133] offset:512
	s_nop 0
	flat_load_dwordx4 v[132:135], v[132:133] offset:528
	v_or_b32_e32 v164, 16, v156
	v_ashrrev_i32_e32 v165, 31, v164
	v_lshlrev_b64 v[164:165], 12, v[164:165]
	v_lshl_add_u64 v[164:165], s[2:3], 0, v[164:165]
	v_lshl_add_u64 v[164:165], v[164:165], 0, v[148:149]
	s_mov_b64 s[98:99], 0x10000
	s_mov_b64 s[100:101], 0x80000
	v_lshl_add_u64 v[232:233], v[154:155], 0, 0
	v_lshl_add_u64 v[234:235], v[232:233], 0, s[98:99]
	v_lshl_add_u64 v[236:237], v[234:235], 0, s[98:99]
	v_lshl_add_u64 v[238:239], v[236:237], 0, s[98:99]
	global_load_dwordx4 v[200:203], v[232:233], off
	global_load_dwordx4 v[204:207], v[232:233], off offset:256
	global_load_dwordx4 v[208:211], v[234:235], off
	global_load_dwordx4 v[212:215], v[234:235], off offset:256
	global_load_dwordx4 v[216:219], v[236:237], off
	global_load_dwordx4 v[220:223], v[236:237], off offset:256
	global_load_dwordx4 v[224:227], v[238:239], off
	global_load_dwordx4 v[228:231], v[238:239], off offset:256
	s_waitcnt vmcnt(0) lgkmcnt(0)
	v_lshlrev_b32_e32 v160, 16, v200
	v_and_b32_e32 v161, 0xffff0000, v200
	v_lshlrev_b32_e32 v32, 16, v201
	v_and_b32_e32 v33, 0xffff0000, v201
	v_lshlrev_b32_e32 v162, 16, v202
	v_and_b32_e32 v163, 0xffff0000, v202
	v_lshlrev_b32_e32 v34, 16, v203
	v_and_b32_e32 v35, 0xffff0000, v203
	v_pk_fma_f32 v[10:11], v[10:11], v[146:147], v[32:33]
	v_pk_fma_f32 v[8:9], v[8:9], v[144:145], v[160:161]
	v_pk_fma_f32 v[14:15], v[14:15], v[142:143], v[34:35]
	v_pk_fma_f32 v[12:13], v[12:13], v[140:141], v[162:163]
	v_cvt_pk_bf16_f32 v32, v8, v9
	v_cvt_pk_bf16_f32 v33, v10, v11
	s_nop 0
	v_cvt_pk_bf16_f32 v34, v12, v13
	v_cvt_pk_bf16_f32 v35, v14, v15
	s_nop 0
	flat_store_dwordx4 v[154:155], v[32:35]
	s_nop 1
	s_nop 0
	v_lshlrev_b32_e32 v32, 16, v204
	v_and_b32_e32 v33, 0xffff0000, v204
	v_lshlrev_b32_e32 v34, 16, v205
	v_and_b32_e32 v35, 0xffff0000, v205
	v_lshlrev_b32_e32 v160, 16, v206
	v_and_b32_e32 v161, 0xffff0000, v206
	v_lshlrev_b32_e32 v162, 16, v207
	v_and_b32_e32 v163, 0xffff0000, v207
	v_pk_fma_f32 v[34:35], v[26:27], v[138:139], v[34:35]
	v_pk_fma_f32 v[32:33], v[24:25], v[136:137], v[32:33]
	v_pk_fma_f32 v[26:27], v[18:19], v[134:135], v[162:163]
	v_pk_fma_f32 v[24:25], v[16:17], v[132:133], v[160:161]
	v_cvt_pk_bf16_f32 v16, v32, v33
	v_cvt_pk_bf16_f32 v17, v34, v35
	s_nop 0
	v_cvt_pk_bf16_f32 v18, v24, v25
	v_cvt_pk_bf16_f32 v19, v26, v27
	flat_store_dwordx4 v[154:155], v[16:19] offset:256
	s_nop 1
	v_lshlrev_b32_e32 v160, 16, v208
	v_and_b32_e32 v161, 0xffff0000, v208
	v_lshlrev_b32_e32 v16, 16, v209
	v_and_b32_e32 v17, 0xffff0000, v209
	v_lshlrev_b32_e32 v162, 16, v210
	v_and_b32_e32 v163, 0xffff0000, v210
	v_lshlrev_b32_e32 v166, 16, v211
	v_and_b32_e32 v167, 0xffff0000, v211
	v_pk_fma_f32 v[18:19], v[62:63], v[146:147], v[16:17]
	v_pk_fma_f32 v[16:17], v[60:61], v[144:145], v[160:161]
	v_pk_fma_f32 v[22:23], v[22:23], v[142:143], v[166:167]
	v_pk_fma_f32 v[20:21], v[20:21], v[140:141], v[162:163]
	v_cvt_pk_bf16_f32 v60, v16, v17
	v_cvt_pk_bf16_f32 v61, v18, v19
	v_or_b32_e32 v166, 32, v156
	v_cvt_pk_bf16_f32 v62, v20, v21
	v_cvt_pk_bf16_f32 v63, v22, v23
	v_ashrrev_i32_e32 v167, 31, v166
	v_lshlrev_b64 v[166:167], 12, v[166:167]
	flat_store_dwordx4 v[164:165], v[60:63]
	v_lshl_add_u64 v[166:167], s[2:3], 0, v[166:167]
	v_lshl_add_u64 v[166:167], v[166:167], 0, v[148:149]
	v_or_b32_e32 v156, 48, v156
	v_ashrrev_i32_e32 v157, 31, v156
	v_lshlrev_b64 v[156:157], 12, v[156:157]
	v_lshl_add_u64 v[156:157], s[2:3], 0, v[156:157]
	v_lshl_add_u64 v[156:157], v[156:157], 0, v[148:149]
	s_mov_b32 s2, 0x80000
	s_nop 1
	v_lshlrev_b32_e32 v60, 16, v212
	v_and_b32_e32 v61, 0xffff0000, v212
	v_lshlrev_b32_e32 v62, 16, v213
	v_and_b32_e32 v63, 0xffff0000, v213
	v_lshlrev_b32_e32 v160, 16, v214
	v_and_b32_e32 v161, 0xffff0000, v214
	v_lshlrev_b32_e32 v162, 16, v215
	v_and_b32_e32 v163, 0xffff0000, v215
	v_pk_fma_f32 v[62:63], v[58:59], v[138:139], v[62:63]
	v_pk_fma_f32 v[60:61], v[56:57], v[136:137], v[60:61]
	v_pk_fma_f32 v[58:59], v[50:51], v[134:135], v[162:163]
	v_pk_fma_f32 v[56:57], v[48:49], v[132:133], v[160:161]
	v_cvt_pk_bf16_f32 v48, v60, v61
	v_cvt_pk_bf16_f32 v49, v62, v63
	s_nop 0
	v_cvt_pk_bf16_f32 v50, v56, v57
	v_cvt_pk_bf16_f32 v51, v58, v59
	flat_store_dwordx4 v[164:165], v[48:51] offset:256
	s_nop 1
	v_lshlrev_b32_e32 v160, 16, v216
	v_and_b32_e32 v161, 0xffff0000, v216
	v_lshlrev_b32_e32 v48, 16, v217
	v_and_b32_e32 v49, 0xffff0000, v217
	v_lshlrev_b32_e32 v162, 16, v218
	v_and_b32_e32 v163, 0xffff0000, v218
; __device__ __forceinline__ unsigned cvt_pk_bf16(float lo, float hi) { unsigned r; asm volatile("v_cvt_pk_bf16_f32 %0, %1, %2" : "=v"(r) : "v"(lo), "v"(hi)); return r; }
;     __device__ __forceinline__ void fused(f32x4 (&acc)[2][2][4][2], const Unit& un, int wr, int wc, int fr, int fq, PG8_LAS unsigned char* lds, int wid, int lane) const {
;     ...
;           for (int ai = 0; ai < 2; ++ai)
; #pragma unroll
;               for (int m = 0; m < 4; ++m) { const size_t off = (size_t)(row0 + ai * HALF + m * 16) * ldc + col0;
; #pragma unroll
;                   for (int bj = 0; bj < 2; ++bj) {
; #pragma unroll
;                       for (int n = 0; n < 2; ++n) { f32x4 bs;
;                           if (BASE_F32) bs = *(const f32x4*)((const float*)base + off + bj * HALF + n * 4);
;                           else { const u32x2v hw = *(const u32x2v*)((const bf16_t*)base + off + bj * HALF + n * 4);
;                                  bs = (f32x4){__uint_as_float(hw.x << 16), __uint_as_float(hw.x & 0xffff0000u), __uint_as_float(hw.y << 16), __uint_as_float(hw.y & 0xffff0000u)}; }
;                           acc[ai][bj][m][n] = bs + gv[bj][n] * acc[ai][bj][m][n]; }
;                       if (out_h) { const f32x4 a0 = acc[ai][bj][m][0], a1 = acc[ai][bj][m][1]; u32x4 w; w.x = cvt_pk_bf16(a0[0], a0[1]); w.y = cvt_pk_bf16(a0[2], a0[3]); w.z = cvt_pk_bf16(a1[0], a1[1]); w.w = cvt_pk_bf16(a1[2], a1[3]);
;                           *(u32x4*)(out_h + off + bj * HALF) = w; } }
;                   asm volatile("" : "+v"(acc[ai][0][m][0]), "+v"(acc[ai][0][m][1]), "+v"(acc[ai][1][m][0]), "+v"(acc[ai][1][m][1]));
	v_lshlrev_b32_e32 v164, 16, v219
	v_and_b32_e32 v165, 0xffff0000, v219
	v_pk_fma_f32 v[50:51], v[78:79], v[146:147], v[48:49]
	v_pk_fma_f32 v[48:49], v[76:77], v[144:145], v[160:161]
	v_pk_fma_f32 v[54:55], v[54:55], v[142:143], v[164:165]
	v_pk_fma_f32 v[52:53], v[52:53], v[140:141], v[162:163]
	v_cvt_pk_bf16_f32 v76, v48, v49
	v_cvt_pk_bf16_f32 v77, v50, v51
	s_nop 0
	v_cvt_pk_bf16_f32 v78, v52, v53
	v_cvt_pk_bf16_f32 v79, v54, v55
	s_nop 0
	flat_store_dwordx4 v[166:167], v[76:79]
	s_nop 1
	s_nop 0
	v_lshlrev_b32_e32 v76, 16, v220
	v_and_b32_e32 v77, 0xffff0000, v220
	v_lshlrev_b32_e32 v78, 16, v221
	v_and_b32_e32 v79, 0xffff0000, v221
	v_lshlrev_b32_e32 v160, 16, v222
	v_and_b32_e32 v161, 0xffff0000, v222
	v_lshlrev_b32_e32 v162, 16, v223
	v_and_b32_e32 v163, 0xffff0000, v223
	v_pk_fma_f32 v[78:79], v[74:75], v[138:139], v[78:79]
	v_pk_fma_f32 v[76:77], v[72:73], v[136:137], v[76:77]
	v_pk_fma_f32 v[74:75], v[66:67], v[134:135], v[162:163]
	v_pk_fma_f32 v[72:73], v[64:65], v[132:133], v[160:161]
	v_cvt_pk_bf16_f32 v64, v76, v77
	v_cvt_pk_bf16_f32 v65, v78, v79
	s_nop 0
	v_cvt_pk_bf16_f32 v66, v72, v73
	v_cvt_pk_bf16_f32 v67, v74, v75
	flat_store_dwordx4 v[166:167], v[64:67] offset:256
	s_nop 1
	v_lshlrev_b32_e32 v160, 16, v224
	v_and_b32_e32 v161, 0xffff0000, v224
	v_lshlrev_b32_e32 v64, 16, v225
	v_and_b32_e32 v65, 0xffff0000, v225
	v_lshlrev_b32_e32 v162, 16, v226
	v_and_b32_e32 v163, 0xffff0000, v226
	v_lshlrev_b32_e32 v164, 16, v227
	v_and_b32_e32 v165, 0xffff0000, v227
	v_pk_fma_f32 v[66:67], v[130:131], v[146:147], v[64:65]
	v_pk_fma_f32 v[64:65], v[128:129], v[144:145], v[160:161]
	v_pk_fma_f32 v[70:71], v[70:71], v[142:143], v[164:165]
	v_pk_fma_f32 v[68:69], v[68:69], v[140:141], v[162:163]
	v_cvt_pk_bf16_f32 v128, v64, v65
	v_cvt_pk_bf16_f32 v129, v66, v67
	v_add_co_u32_e32 v164, vcc, s2, v154
	v_cvt_pk_bf16_f32 v130, v68, v69
	v_cvt_pk_bf16_f32 v131, v70, v71
	s_nop 0
	v_addc_co_u32_e32 v165, vcc, 0, v155, vcc
	flat_store_dwordx4 v[156:157], v[128:131]
	s_mov_b64 s[2:3], 0x80000
	s_nop 1
	v_lshlrev_b32_e32 v128, 16, v228
	v_and_b32_e32 v129, 0xffff0000, v228
	v_lshlrev_b32_e32 v130, 16, v229
	v_and_b32_e32 v131, 0xffff0000, v229
	v_lshlrev_b32_e32 v160, 16, v230
	v_and_b32_e32 v161, 0xffff0000, v230
	v_lshlrev_b32_e32 v162, 16, v231
	v_and_b32_e32 v163, 0xffff0000, v231
	v_pk_fma_f32 v[110:111], v[110:111], v[138:139], v[130:131]
	v_pk_fma_f32 v[108:109], v[108:109], v[136:137], v[128:129]
	v_pk_fma_f32 v[98:99], v[98:99], v[134:135], v[162:163]
	v_pk_fma_f32 v[96:97], v[96:97], v[132:133], v[160:161]
	v_cvt_pk_bf16_f32 v128, v108, v109
	v_cvt_pk_bf16_f32 v129, v110, v111
	s_nop 0
	v_cvt_pk_bf16_f32 v130, v96, v97
	v_cvt_pk_bf16_f32 v131, v98, v99
	flat_store_dwordx4 v[156:157], v[128:131] offset:256
	v_lshl_add_u64 v[156:157], v[154:155], 0, s[2:3]
	s_mov_b32 s2, 0x90000
	v_add_co_u32_e32 v166, vcc, s2, v154
	s_mov_b64 s[2:3], 0x90000
	s_nop 0
	v_addc_co_u32_e32 v167, vcc, 0, v155, vcc
	v_lshl_add_u64 v[232:233], v[232:233], 0, s[100:101]
	v_lshl_add_u64 v[234:235], v[234:235], 0, s[100:101]
	v_lshl_add_u64 v[236:237], v[236:237], 0, s[100:101]
	v_lshl_add_u64 v[238:239], v[238:239], 0, s[100:101]
	global_load_dwordx4 v[200:203], v[232:233], off
	global_load_dwordx4 v[204:207], v[232:233], off offset:256
	global_load_dwordx4 v[208:211], v[234:235], off
	global_load_dwordx4 v[212:215], v[234:235], off offset:256
	global_load_dwordx4 v[216:219], v[236:237], off
	global_load_dwordx4 v[220:223], v[236:237], off offset:256
	global_load_dwordx4 v[224:227], v[238:239], off
	global_load_dwordx4 v[228:231], v[238:239], off offset:256
	s_waitcnt vmcnt(0) lgkmcnt(0)
	v_lshlrev_b32_e32 v160, 16, v200
	v_and_b32_e32 v161, 0xffff0000, v200
	v_lshlrev_b32_e32 v128, 16, v201
	v_and_b32_e32 v129, 0xffff0000, v201
	v_lshlrev_b32_e32 v162, 16, v202
	v_and_b32_e32 v163, 0xffff0000, v202
	v_lshlrev_b32_e32 v130, 16, v203
	v_and_b32_e32 v131, 0xffff0000, v203
	v_pk_fma_f32 v[102:103], v[102:103], v[146:147], v[128:129]
	v_pk_fma_f32 v[100:101], v[100:101], v[144:145], v[160:161]
	v_pk_fma_f32 v[106:107], v[106:107], v[142:143], v[130:131]
	v_pk_fma_f32 v[104:105], v[104:105], v[140:141], v[162:163]
	v_cvt_pk_bf16_f32 v128, v100, v101
	v_cvt_pk_bf16_f32 v129, v102, v103
	s_nop 0
	v_cvt_pk_bf16_f32 v130, v104, v105
	v_cvt_pk_bf16_f32 v131, v106, v107
	s_nop 0
	flat_store_dwordx4 v[164:165], v[128:131]
	s_nop 1
	s_nop 0
	v_lshlrev_b32_e32 v128, 16, v204
	v_and_b32_e32 v129, 0xffff0000, v204
	v_lshlrev_b32_e32 v130, 16, v205
	v_and_b32_e32 v131, 0xffff0000, v205
	v_lshlrev_b32_e32 v160, 16, v206
	v_and_b32_e32 v161, 0xffff0000, v206
	v_lshlrev_b32_e32 v162, 16, v207
	v_and_b32_e32 v163, 0xffff0000, v207
	v_pk_fma_f32 v[126:127], v[126:127], v[138:139], v[130:131]
	v_pk_fma_f32 v[124:125], v[124:125], v[136:137], v[128:129]
	v_pk_fma_f32 v[114:115], v[114:115], v[134:135], v[162:163]
	v_pk_fma_f32 v[112:113], v[112:113], v[132:133], v[160:161]
	v_cvt_pk_bf16_f32 v128, v124, v125
	v_cvt_pk_bf16_f32 v129, v126, v127
	s_nop 0
	v_cvt_pk_bf16_f32 v130, v112, v113
	v_cvt_pk_bf16_f32 v131, v114, v115
	flat_store_dwordx4 v[156:157], v[128:131] offset:256
	v_lshl_add_u64 v[156:157], v[154:155], 0, s[2:3]
	s_mov_b32 s2, 0xa0000
	v_add_co_u32_e32 v164, vcc, s2, v154
	s_mov_b64 s[2:3], 0xa0000
	s_nop 0
	v_addc_co_u32_e32 v165, vcc, 0, v155, vcc
	s_nop 1
	v_lshlrev_b32_e32 v160, 16, v208
	v_and_b32_e32 v161, 0xffff0000, v208
	v_lshlrev_b32_e32 v128, 16, v209
	v_and_b32_e32 v129, 0xffff0000, v209
	v_lshlrev_b32_e32 v162, 16, v210
	v_and_b32_e32 v163, 0xffff0000, v210
	v_lshlrev_b32_e32 v130, 16, v211
	v_and_b32_e32 v131, 0xffff0000, v211
; __device__ __forceinline__ unsigned cvt_pk_bf16(float lo, float hi) { unsigned r; asm volatile("v_cvt_pk_bf16_f32 %0, %1, %2" : "=v"(r) : "v"(lo), "v"(hi)); return r; }
;     __device__ __forceinline__ void fused(f32x4 (&acc)[2][2][4][2], const Unit& un, int wr, int wc, int fr, int fq, PG8_LAS unsigned char* lds, int wid, int lane) const {
;     ...
;           for (int ai = 0; ai < 2; ++ai)
; #pragma unroll
;               for (int m = 0; m < 4; ++m) { const size_t off = (size_t)(row0 + ai * HALF + m * 16) * ldc + col0;
; #pragma unroll
;                   for (int bj = 0; bj < 2; ++bj) {
; #pragma unroll
;                       for (int n = 0; n < 2; ++n) { f32x4 bs;
;                           if (BASE_F32) bs = *(const f32x4*)((const float*)base + off + bj * HALF + n * 4);
;                           else { const u32x2v hw = *(const u32x2v*)((const bf16_t*)base + off + bj * HALF + n * 4);
;                                  bs = (f32x4){__uint_as_float(hw.x << 16), __uint_as_float(hw.x & 0xffff0000u), __uint_as_float(hw.y << 16), __uint_as_float(hw.y & 0xffff0000u)}; }
;                           acc[ai][bj][m][n] = bs + gv[bj][n] * acc[ai][bj][m][n]; }
;                       if (out_h) { const f32x4 a0 = acc[ai][bj][m][0], a1 = acc[ai][bj][m][1]; u32x4 w; w.x = cvt_pk_bf16(a0[0], a0[1]); w.y = cvt_pk_bf16(a0[2], a0[3]); w.z = cvt_pk_bf16(a1[0], a1[1]); w.w = cvt_pk_bf16(a1[2], a1[3]);
;                           *(u32x4*)(out_h + off + bj * HALF) = w; } }
;                   asm volatile("" : "+v"(acc[ai][0][m][0]), "+v"(acc[ai][0][m][1]), "+v"(acc[ai][1][m][0]), "+v"(acc[ai][1][m][1]));
;                   asm volatile("" ::: "memory"); } }
; #pragma unroll
;         for (int ai = 0; ai < 2; ++ai)
; #pragma unroll
;             for (int m = 0; m < 4; ++m) { float s = 0.f;
; #pragma unroll
;                 for (int bj = 0; bj < 2; ++bj)
; #pragma unroll
;                     for (int n = 0; n < 2; ++n) { const f32x4 x = acc[ai][bj][m][n]; s += (x[0] * x[0] + x[1] * x[1]) + (x[2] * x[2] + x[3] * x[3]); }
;                 s += __shfl_xor(s, 16); s += __shfl_xor(s, 32);
;                 if (fq == 0) P[(ai * HALF + wr * 64 + m * 16 + fr) * 4 + wc] = s; }
	v_pk_fma_f32 v[118:119], v[118:119], v[146:147], v[128:129]
	v_pk_fma_f32 v[116:117], v[116:117], v[144:145], v[160:161]
	v_pk_fma_f32 v[122:123], v[122:123], v[142:143], v[130:131]
	v_pk_fma_f32 v[120:121], v[120:121], v[140:141], v[162:163]
	v_cvt_pk_bf16_f32 v128, v116, v117
	v_cvt_pk_bf16_f32 v129, v118, v119
	s_nop 0
	v_cvt_pk_bf16_f32 v130, v120, v121
	v_cvt_pk_bf16_f32 v131, v122, v123
	s_nop 0
	flat_store_dwordx4 v[166:167], v[128:131]
	s_nop 1
	s_nop 0
	v_lshlrev_b32_e32 v128, 16, v212
	v_and_b32_e32 v129, 0xffff0000, v212
	v_lshlrev_b32_e32 v130, 16, v213
	v_and_b32_e32 v131, 0xffff0000, v213
	v_lshlrev_b32_e32 v160, 16, v214
	v_and_b32_e32 v161, 0xffff0000, v214
	v_lshlrev_b32_e32 v162, 16, v215
	v_and_b32_e32 v163, 0xffff0000, v215
	v_pk_fma_f32 v[94:95], v[94:95], v[138:139], v[130:131]
	v_pk_fma_f32 v[92:93], v[92:93], v[136:137], v[128:129]
	v_pk_fma_f32 v[90:91], v[90:91], v[134:135], v[162:163]
	v_pk_fma_f32 v[88:89], v[88:89], v[132:133], v[160:161]
	v_cvt_pk_bf16_f32 v128, v92, v93
	v_cvt_pk_bf16_f32 v129, v94, v95
	s_nop 0
	v_cvt_pk_bf16_f32 v130, v88, v89
	v_cvt_pk_bf16_f32 v131, v90, v91
	flat_store_dwordx4 v[156:157], v[128:131] offset:256
	v_lshl_add_u64 v[156:157], v[154:155], 0, s[2:3]
	s_mov_b32 s2, 0xb0000
	v_add_co_u32_e32 v166, vcc, s2, v154
	s_mov_b64 s[2:3], 0xb0000
	s_nop 0
	v_addc_co_u32_e32 v167, vcc, 0, v155, vcc
	s_nop 1
	v_lshlrev_b32_e32 v160, 16, v216
	v_and_b32_e32 v161, 0xffff0000, v216
	v_lshlrev_b32_e32 v128, 16, v217
	v_and_b32_e32 v129, 0xffff0000, v217
	v_lshlrev_b32_e32 v162, 16, v218
	v_and_b32_e32 v163, 0xffff0000, v218
	v_lshlrev_b32_e32 v130, 16, v219
	v_and_b32_e32 v131, 0xffff0000, v219
	v_pk_fma_f32 v[86:87], v[86:87], v[146:147], v[128:129]
	v_pk_fma_f32 v[84:85], v[84:85], v[144:145], v[160:161]
	v_pk_fma_f32 v[82:83], v[82:83], v[142:143], v[130:131]
	v_pk_fma_f32 v[80:81], v[80:81], v[140:141], v[162:163]
	v_cvt_pk_bf16_f32 v128, v84, v85
	v_cvt_pk_bf16_f32 v129, v86, v87
	s_nop 0
	v_cvt_pk_bf16_f32 v130, v80, v81
	v_cvt_pk_bf16_f32 v131, v82, v83
	s_nop 0
	flat_store_dwordx4 v[164:165], v[128:131]
	v_mul_f32_e32 v164, v25, v25
	v_mul_f32_e32 v165, v27, v27
	v_fmac_f32_e32 v164, v24, v24
	v_fmac_f32_e32 v165, v26, v26
	s_nop 1
	v_lshlrev_b32_e32 v128, 16, v220
	v_and_b32_e32 v129, 0xffff0000, v220
	v_lshlrev_b32_e32 v130, 16, v221
	v_and_b32_e32 v131, 0xffff0000, v221
	v_lshlrev_b32_e32 v160, 16, v222
	v_and_b32_e32 v161, 0xffff0000, v222
	v_lshlrev_b32_e32 v162, 16, v223
	v_and_b32_e32 v163, 0xffff0000, v223
	v_pk_fma_f32 v[46:47], v[46:47], v[138:139], v[130:131]
	v_pk_fma_f32 v[44:45], v[44:45], v[136:137], v[128:129]
	v_pk_fma_f32 v[42:43], v[42:43], v[134:135], v[162:163]
	v_pk_fma_f32 v[40:41], v[40:41], v[132:133], v[160:161]
	v_cvt_pk_bf16_f32 v128, v44, v45
	v_cvt_pk_bf16_f32 v129, v46, v47
	v_lshl_add_u64 v[160:161], v[154:155], 0, s[2:3]
	v_cvt_pk_bf16_f32 v130, v40, v41
	v_cvt_pk_bf16_f32 v131, v42, v43
	flat_store_dwordx4 v[156:157], v[128:131] offset:256
	v_mul_f32_e32 v162, v33, v33
	v_mul_f32_e32 v163, v35, v35
	v_fmac_f32_e32 v162, v32, v32
	v_fmac_f32_e32 v163, v34, v34
	s_lshl_b32 s2, s9, 2
	s_add_i32 s2, s2, 0
	s_nop 1
	v_lshlrev_b32_e32 v154, 16, v224
	v_and_b32_e32 v155, 0xffff0000, v224
	v_lshlrev_b32_e32 v128, 16, v225
	v_and_b32_e32 v129, 0xffff0000, v225
	v_lshlrev_b32_e32 v156, 16, v226
	v_and_b32_e32 v157, 0xffff0000, v226
	v_lshlrev_b32_e32 v130, 16, v227
	v_and_b32_e32 v131, 0xffff0000, v227
	v_pk_fma_f32 v[38:39], v[38:39], v[146:147], v[128:129]
	v_pk_fma_f32 v[36:37], v[36:37], v[144:145], v[154:155]
	v_pk_fma_f32 v[30:31], v[30:31], v[142:143], v[130:131]
	v_pk_fma_f32 v[28:29], v[28:29], v[140:141], v[156:157]
	v_cvt_pk_bf16_f32 v142, v36, v37
	v_cvt_pk_bf16_f32 v143, v38, v39
	v_mbcnt_lo_u32_b32 v128, -1, 0
	v_cvt_pk_bf16_f32 v144, v28, v29
	v_cvt_pk_bf16_f32 v145, v30, v31
	v_mbcnt_hi_u32_b32 v129, -1, v128
	v_mul_f32_e32 v140, v9, v9
	v_mul_f32_e32 v141, v11, v11
	v_mul_f32_e32 v146, v13, v13
	v_mul_f32_e32 v147, v15, v15
	v_and_b32_e32 v130, 64, v129
	v_fmac_f32_e32 v140, v8, v8
	v_fmac_f32_e32 v141, v10, v10
	v_fmac_f32_e32 v146, v12, v12
	v_fmac_f32_e32 v147, v14, v14
	v_xor_b32_e32 v128, 16, v129
	v_add_u32_e32 v130, 64, v130
	v_add_f32_e32 v140, v140, v141
	v_add_f32_e32 v141, v146, v147
	v_cmp_lt_i32_e32 vcc, v128, v130
	v_add_f32_e32 v146, v162, v163
	v_add_f32_e32 v140, v140, v141
	v_cndmask_b32_e32 v128, v129, v128, vcc
	v_add_f32_e32 v147, v164, v165
	v_add_f32_e32 v140, v146, v140
	v_lshlrev_b32_e32 v128, 2, v128
	v_add_f32_e32 v140, v147, v140
	ds_bpermute_b32 v141, v128, v140
	v_xor_b32_e32 v131, 32, v129
	v_cmp_lt_i32_e32 vcc, v131, v130
	flat_store_dwordx4 v[166:167], v[142:145]
	v_and_b32_e32 v130, 63, v158
	v_cndmask_b32_e32 v129, v129, v131, vcc
	v_lshlrev_b32_e32 v129, 2, v129
	s_waitcnt lgkmcnt(0)
	v_add_f32_e32 v140, v140, v141
	ds_bpermute_b32 v141, v129, v140
	v_cmp_gt_u32_e32 vcc, 16, v130
	s_waitcnt vmcnt(0)
	v_lshlrev_b32_e32 v142, 16, v228
	v_and_b32_e32 v143, 0xffff0000, v228
	v_lshlrev_b32_e32 v144, 16, v229
	v_and_b32_e32 v145, 0xffff0000, v229
	v_lshlrev_b32_e32 v146, 16, v230
	v_and_b32_e32 v147, 0xffff0000, v230
	v_lshlrev_b32_e32 v154, 16, v231
	v_and_b32_e32 v155, 0xffff0000, v231
	v_pk_fma_f32 v[6:7], v[6:7], v[138:139], v[144:145]
	v_pk_fma_f32 v[4:5], v[4:5], v[136:137], v[142:143]
	v_pk_fma_f32 v[2:3], v[2:3], v[134:135], v[154:155]
	v_pk_fma_f32 v[0:1], v[0:1], v[132:133], v[146:147]
	v_cvt_pk_bf16_f32 v132, v4, v5
	v_cvt_pk_bf16_f32 v133, v6, v7
	v_or_b32_e32 v144, s8, v159
	v_cvt_pk_bf16_f32 v134, v0, v1
	v_cvt_pk_bf16_f32 v135, v2, v3
	flat_store_dwordx4 v[160:161], v[132:135] offset:256
	v_lshl_add_u32 v131, v144, 4, s2
	s_and_saveexec_b64 s[2:3], vcc
	v_readlane_b32 s96, v254, 47
	s_cbranch_execz .LBB0_2734
	s_waitcnt lgkmcnt(0)
	v_add_f32_e32 v132, v140, v141
	ds_write_b32 v131, v132

; __device__ __forceinline__ unsigned cvt_pk_bf16(float lo, float hi) { unsigned r; asm volatile("v_cvt_pk_bf16_f32 %0, %1, %2" : "=v"(r) : "v"(lo), "v"(hi)); return r; }
;     __device__ __forceinline__ void fused(f32x4 (&acc)[2][2][4][2], const Unit& un, int wr, int wc, int fr, int fq, PG8_LAS unsigned char* lds, int wid, int lane) const {
;     ...
;         const int row0 = un.pm * BM + wr * 64 + fr, col0 = un.pn * BM + wc * 32 + 8 * fq;
;         const size_t boff = (size_t)(un.pm >> 3) * bstride + col0;
;         { f32x4 gv[2][2];
; #pragma unroll
;           for (int bj = 0; bj < 2; ++bj)
; #pragma unroll
;               for (int n = 0; n < 2; ++n) gv[bj][n] = *(const f32x4*)(gate + boff + bj * HALF + n * 4);
; #pragma unroll
;           for (int ai = 0; ai < 2; ++ai)
; #pragma unroll
;               for (int m = 0; m < 4; ++m) { const size_t off = (size_t)(row0 + ai * HALF + m * 16) * ldc + col0;
; #pragma unroll
;                   for (int bj = 0; bj < 2; ++bj) {
; #pragma unroll
;                       for (int n = 0; n < 2; ++n) { f32x4 bs;
;                           if (BASE_F32) bs = *(const f32x4*)((const float*)base + off + bj * HALF + n * 4);
;                           else { const u32x2v hw = *(const u32x2v*)((const bf16_t*)base + off + bj * HALF + n * 4);
;                                  bs = (f32x4){__uint_as_float(hw.x << 16), __uint_as_float(hw.x & 0xffff0000u), __uint_as_float(hw.y << 16), __uint_as_float(hw.y & 0xffff0000u)}; }
;                           acc[ai][bj][m][n] = bs + gv[bj][n] * acc[ai][bj][m][n]; }
;                       if (out_h) { const f32x4 a0 = acc[ai][bj][m][0], a1 = acc[ai][bj][m][1]; u32x4 w; w.x = cvt_pk_bf16(a0[0], a0[1]); w.y = cvt_pk_bf16(a0[2], a0[3]); w.z = cvt_pk_bf16(a1[0], a1[1]); w.w = cvt_pk_bf16(a1[2], a1[3]);
;                           *(u32x4*)(out_h + off + bj * HALF) = w; } }
;                   asm volatile("" : "+v"(acc[ai][0][m][0]), "+v"(acc[ai][0][m][1]), "+v"(acc[ai][1][m][0]), "+v"(acc[ai][1][m][1]));
.LBB0_2917:
	v_mov_b32_e32 v32, 0
	s_barrier
	s_lshl_b32 s6, s9, 5
	v_mbcnt_lo_u32_b32 v32, -1, v32
	s_add_u32 s2, s44, 0x1a600000
	v_mbcnt_hi_u32_b32 v32, -1, v32
	s_addc_u32 s3, s45, 0
	v_or_b32_e32 v158, s33, v32
	s_lshl_b32 s7, s4, 8
	s_lshl_b32 s14, s46, 8
	s_or_b32 s6, s7, s6
	v_lshrrev_b32_e32 v32, 1, v158
	v_and_b32_e32 v159, 15, v158
	s_add_i32 s15, s14, s8
	v_and_or_b32 v152, v32, 24, s6
	s_ashr_i32 s6, s46, 3
	v_ashrrev_i32_e32 v153, 31, v152
	v_mov_b32_e32 v32, 0x3000
	v_or_b32_e32 v156, s15, v159
	v_mad_i64_i32 v[32:33], s[6:7], s6, v32, v[152:153]
	v_ashrrev_i32_e32 v157, 31, v156
	v_lshl_add_u64 v[150:151], v[32:33], 2, s[44:45]
	v_lshlrev_b64 v[32:33], 12, v[156:157]
	v_lshl_add_u64 v[32:33], s[2:3], 0, v[32:33]
	v_lshlrev_b64 v[148:149], 1, v[152:153]
	s_mov_b32 s15, 0x16a000
	v_lshl_add_u64 v[154:155], v[32:33], 0, v[148:149]
	v_add_co_u32_e32 v132, vcc, s15, v150
	s_nop 0
	v_addc_co_u32_e32 v133, vcc, 0, v151, vcc
	s_mov_b64 s[6:7], 0x16a000
	flat_load_dwordx4 v[144:147], v[132:133]
	v_lshl_add_u64 v[132:133], v[150:151], 0, s[6:7]
	flat_load_dwordx4 v[140:143], v[132:133] offset:16
	flat_load_dwordx4 v[136:139], v[132:133] offset:512
	s_nop 0
	flat_load_dwordx4 v[132:135], v[132:133] offset:528
	v_or_b32_e32 v164, 16, v156
	v_ashrrev_i32_e32 v165, 31, v164
	v_lshlrev_b64 v[164:165], 12, v[164:165]
	v_lshl_add_u64 v[164:165], s[2:3], 0, v[164:165]
	v_lshl_add_u64 v[164:165], v[164:165], 0, v[148:149]
	s_mov_b64 s[98:99], 0x10000
	s_mov_b64 s[100:101], 0x80000
	v_lshl_add_u64 v[232:233], v[154:155], 0, 0
	v_lshl_add_u64 v[234:235], v[232:233], 0, s[98:99]
	v_lshl_add_u64 v[236:237], v[234:235], 0, s[98:99]
	v_lshl_add_u64 v[238:239], v[236:237], 0, s[98:99]
	global_load_dwordx4 v[200:203], v[232:233], off
	global_load_dwordx4 v[204:207], v[232:233], off offset:256
	global_load_dwordx4 v[208:211], v[234:235], off
	global_load_dwordx4 v[212:215], v[234:235], off offset:256
	global_load_dwordx4 v[216:219], v[236:237], off
	global_load_dwordx4 v[220:223], v[236:237], off offset:256
	global_load_dwordx4 v[224:227], v[238:239], off
	global_load_dwordx4 v[228:231], v[238:239], off offset:256
	s_waitcnt vmcnt(0) lgkmcnt(0)
	v_lshlrev_b32_e32 v160, 16, v200
	v_and_b32_e32 v161, 0xffff0000, v200
	v_lshlrev_b32_e32 v32, 16, v201
	v_and_b32_e32 v33, 0xffff0000, v201
	v_lshlrev_b32_e32 v162, 16, v202
	v_and_b32_e32 v163, 0xffff0000, v202
	v_lshlrev_b32_e32 v34, 16, v203
	v_and_b32_e32 v35, 0xffff0000, v203
	v_pk_fma_f32 v[10:11], v[10:11], v[146:147], v[32:33]
	v_pk_fma_f32 v[8:9], v[8:9], v[144:145], v[160:161]
	v_pk_fma_f32 v[14:15], v[14:15], v[142:143], v[34:35]
	v_pk_fma_f32 v[12:13], v[12:13], v[140:141], v[162:163]
	v_cvt_pk_bf16_f32 v32, v8, v9
	v_cvt_pk_bf16_f32 v33, v10, v11
	s_nop 0
	v_cvt_pk_bf16_f32 v34, v12, v13
	v_cvt_pk_bf16_f32 v35, v14, v15
	s_nop 0
	flat_store_dwordx4 v[154:155], v[32:35]
	s_nop 1
	s_nop 0
	v_lshlrev_b32_e32 v32, 16, v204
	v_and_b32_e32 v33, 0xffff0000, v204
	v_lshlrev_b32_e32 v34, 16, v205
	v_and_b32_e32 v35, 0xffff0000, v205
	v_lshlrev_b32_e32 v160, 16, v206
	v_and_b32_e32 v161, 0xffff0000, v206
	v_lshlrev_b32_e32 v162, 16, v207
	v_and_b32_e32 v163, 0xffff0000, v207
	v_pk_fma_f32 v[34:35], v[30:31], v[138:139], v[34:35]
	v_pk_fma_f32 v[32:33], v[28:29], v[136:137], v[32:33]
	v_pk_fma_f32 v[30:31], v[18:19], v[134:135], v[162:163]
	v_pk_fma_f32 v[28:29], v[16:17], v[132:133], v[160:161]
	v_cvt_pk_bf16_f32 v16, v32, v33
	v_cvt_pk_bf16_f32 v17, v34, v35
	s_nop 0
	v_cvt_pk_bf16_f32 v18, v28, v29
	v_cvt_pk_bf16_f32 v19, v30, v31
	flat_store_dwordx4 v[154:155], v[16:19] offset:256
	s_nop 1
	v_lshlrev_b32_e32 v160, 16, v208
	v_and_b32_e32 v161, 0xffff0000, v208
	v_lshlrev_b32_e32 v16, 16, v209
	v_and_b32_e32 v17, 0xffff0000, v209
	v_lshlrev_b32_e32 v162, 16, v210
	v_and_b32_e32 v163, 0xffff0000, v210
	v_lshlrev_b32_e32 v166, 16, v211
	v_and_b32_e32 v167, 0xffff0000, v211
	v_pk_fma_f32 v[18:19], v[62:63], v[146:147], v[16:17]
	v_pk_fma_f32 v[16:17], v[60:61], v[144:145], v[160:161]
	v_pk_fma_f32 v[22:23], v[22:23], v[142:143], v[166:167]
	v_pk_fma_f32 v[20:21], v[20:21], v[140:141], v[162:163]
	v_cvt_pk_bf16_f32 v60, v16, v17
	v_cvt_pk_bf16_f32 v61, v18, v19
	v_or_b32_e32 v166, 32, v156
	v_cvt_pk_bf16_f32 v62, v20, v21
	v_cvt_pk_bf16_f32 v63, v22, v23
	v_ashrrev_i32_e32 v167, 31, v166
	v_lshlrev_b64 v[166:167], 12, v[166:167]
	flat_store_dwordx4 v[164:165], v[60:63]
	v_lshl_add_u64 v[166:167], s[2:3], 0, v[166:167]
	v_lshl_add_u64 v[166:167], v[166:167], 0, v[148:149]
	v_or_b32_e32 v156, 48, v156
	v_ashrrev_i32_e32 v157, 31, v156
	v_lshlrev_b64 v[156:157], 12, v[156:157]
	v_lshl_add_u64 v[156:157], s[2:3], 0, v[156:157]
	v_lshl_add_u64 v[156:157], v[156:157], 0, v[148:149]
	s_mov_b32 s2, 0x80000
	s_nop 1
	v_lshlrev_b32_e32 v60, 16, v212
	v_and_b32_e32 v61, 0xffff0000, v212
	v_lshlrev_b32_e32 v62, 16, v213
	v_and_b32_e32 v63, 0xffff0000, v213
	v_lshlrev_b32_e32 v160, 16, v214
	v_and_b32_e32 v161, 0xffff0000, v214
	v_lshlrev_b32_e32 v162, 16, v215
	v_and_b32_e32 v163, 0xffff0000, v215
	v_pk_fma_f32 v[62:63], v[58:59], v[138:139], v[62:63]
	v_pk_fma_f32 v[60:61], v[56:57], v[136:137], v[60:61]
	v_pk_fma_f32 v[58:59], v[50:51], v[134:135], v[162:163]
	v_pk_fma_f32 v[56:57], v[48:49], v[132:133], v[160:161]
	v_cvt_pk_bf16_f32 v48, v60, v61
	v_cvt_pk_bf16_f32 v49, v62, v63
	s_nop 0
	v_cvt_pk_bf16_f32 v50, v56, v57
	v_cvt_pk_bf16_f32 v51, v58, v59
	flat_store_dwordx4 v[164:165], v[48:51] offset:256
	s_nop 1
	v_lshlrev_b32_e32 v160, 16, v216
	v_and_b32_e32 v161, 0xffff0000, v216
	v_lshlrev_b32_e32 v48, 16, v217
	v_and_b32_e32 v49, 0xffff0000, v217
	v_lshlrev_b32_e32 v162, 16, v218
	v_and_b32_e32 v163, 0xffff0000, v218
; __device__ __forceinline__ unsigned cvt_pk_bf16(float lo, float hi) { unsigned r; asm volatile("v_cvt_pk_bf16_f32 %0, %1, %2" : "=v"(r) : "v"(lo), "v"(hi)); return r; }
;     __device__ __forceinline__ void fused(f32x4 (&acc)[2][2][4][2], const Unit& un, int wr, int wc, int fr, int fq, PG8_LAS unsigned char* lds, int wid, int lane) const {
;     ...
;           for (int ai = 0; ai < 2; ++ai)
; #pragma unroll
;               for (int m = 0; m < 4; ++m) { const size_t off = (size_t)(row0 + ai * HALF + m * 16) * ldc + col0;
; #pragma unroll
;                   for (int bj = 0; bj < 2; ++bj) {
; #pragma unroll
;                       for (int n = 0; n < 2; ++n) { f32x4 bs;
;                           if (BASE_F32) bs = *(const f32x4*)((const float*)base + off + bj * HALF + n * 4);
;                           else { const u32x2v hw = *(const u32x2v*)((const bf16_t*)base + off + bj * HALF + n * 4);
;                                  bs = (f32x4){__uint_as_float(hw.x << 16), __uint_as_float(hw.x & 0xffff0000u), __uint_as_float(hw.y << 16), __uint_as_float(hw.y & 0xffff0000u)}; }
;                           acc[ai][bj][m][n] = bs + gv[bj][n] * acc[ai][bj][m][n]; }
;                       if (out_h) { const f32x4 a0 = acc[ai][bj][m][0], a1 = acc[ai][bj][m][1]; u32x4 w; w.x = cvt_pk_bf16(a0[0], a0[1]); w.y = cvt_pk_bf16(a0[2], a0[3]); w.z = cvt_pk_bf16(a1[0], a1[1]); w.w = cvt_pk_bf16(a1[2], a1[3]);
;                           *(u32x4*)(out_h + off + bj * HALF) = w; } }
;                   asm volatile("" : "+v"(acc[ai][0][m][0]), "+v"(acc[ai][0][m][1]), "+v"(acc[ai][1][m][0]), "+v"(acc[ai][1][m][1]));
	v_lshlrev_b32_e32 v164, 16, v219
	v_and_b32_e32 v165, 0xffff0000, v219
	v_pk_fma_f32 v[50:51], v[78:79], v[146:147], v[48:49]
	v_pk_fma_f32 v[48:49], v[76:77], v[144:145], v[160:161]
	v_pk_fma_f32 v[54:55], v[54:55], v[142:143], v[164:165]
	v_pk_fma_f32 v[52:53], v[52:53], v[140:141], v[162:163]
	v_cvt_pk_bf16_f32 v76, v48, v49
	v_cvt_pk_bf16_f32 v77, v50, v51
	s_nop 0
	v_cvt_pk_bf16_f32 v78, v52, v53
	v_cvt_pk_bf16_f32 v79, v54, v55
	s_nop 0
	flat_store_dwordx4 v[166:167], v[76:79]
	s_nop 1
	s_nop 0
	v_lshlrev_b32_e32 v76, 16, v220
	v_and_b32_e32 v77, 0xffff0000, v220
	v_lshlrev_b32_e32 v78, 16, v221
	v_and_b32_e32 v79, 0xffff0000, v221
	v_lshlrev_b32_e32 v160, 16, v222
	v_and_b32_e32 v161, 0xffff0000, v222
	v_lshlrev_b32_e32 v162, 16, v223
	v_and_b32_e32 v163, 0xffff0000, v223
	v_pk_fma_f32 v[78:79], v[74:75], v[138:139], v[78:79]
	v_pk_fma_f32 v[76:77], v[72:73], v[136:137], v[76:77]
	v_pk_fma_f32 v[74:75], v[66:67], v[134:135], v[162:163]
	v_pk_fma_f32 v[72:73], v[64:65], v[132:133], v[160:161]
	v_cvt_pk_bf16_f32 v64, v76, v77
	v_cvt_pk_bf16_f32 v65, v78, v79
	s_nop 0
	v_cvt_pk_bf16_f32 v66, v72, v73
	v_cvt_pk_bf16_f32 v67, v74, v75
	flat_store_dwordx4 v[166:167], v[64:67] offset:256
	s_nop 1
	v_lshlrev_b32_e32 v160, 16, v224
	v_and_b32_e32 v161, 0xffff0000, v224
	v_lshlrev_b32_e32 v64, 16, v225
	v_and_b32_e32 v65, 0xffff0000, v225
	v_lshlrev_b32_e32 v162, 16, v226
	v_and_b32_e32 v163, 0xffff0000, v226
	v_lshlrev_b32_e32 v164, 16, v227
	v_and_b32_e32 v165, 0xffff0000, v227
	v_pk_fma_f32 v[66:67], v[130:131], v[146:147], v[64:65]
	v_pk_fma_f32 v[64:65], v[128:129], v[144:145], v[160:161]
	v_pk_fma_f32 v[70:71], v[70:71], v[142:143], v[164:165]
	v_pk_fma_f32 v[68:69], v[68:69], v[140:141], v[162:163]
	v_cvt_pk_bf16_f32 v128, v64, v65
	v_cvt_pk_bf16_f32 v129, v66, v67
	v_add_co_u32_e32 v164, vcc, s2, v154
	v_cvt_pk_bf16_f32 v130, v68, v69
	v_cvt_pk_bf16_f32 v131, v70, v71
	s_nop 0
	v_addc_co_u32_e32 v165, vcc, 0, v155, vcc
	flat_store_dwordx4 v[156:157], v[128:131]
	s_mov_b64 s[2:3], 0x80000
	s_nop 1
	v_lshlrev_b32_e32 v128, 16, v228
	v_and_b32_e32 v129, 0xffff0000, v228
	v_lshlrev_b32_e32 v130, 16, v229
	v_and_b32_e32 v131, 0xffff0000, v229
	v_lshlrev_b32_e32 v160, 16, v230
	v_and_b32_e32 v161, 0xffff0000, v230
	v_lshlrev_b32_e32 v162, 16, v231
	v_and_b32_e32 v163, 0xffff0000, v231
	v_pk_fma_f32 v[110:111], v[110:111], v[138:139], v[130:131]
	v_pk_fma_f32 v[108:109], v[108:109], v[136:137], v[128:129]
	v_pk_fma_f32 v[98:99], v[98:99], v[134:135], v[162:163]
	v_pk_fma_f32 v[96:97], v[96:97], v[132:133], v[160:161]
	v_cvt_pk_bf16_f32 v128, v108, v109
	v_cvt_pk_bf16_f32 v129, v110, v111
	s_nop 0
	v_cvt_pk_bf16_f32 v130, v96, v97
	v_cvt_pk_bf16_f32 v131, v98, v99
	flat_store_dwordx4 v[156:157], v[128:131] offset:256
	v_lshl_add_u64 v[156:157], v[154:155], 0, s[2:3]
	s_mov_b32 s2, 0x90000
	v_add_co_u32_e32 v166, vcc, s2, v154
	s_mov_b64 s[2:3], 0x90000
	s_nop 0
	v_addc_co_u32_e32 v167, vcc, 0, v155, vcc
	v_lshl_add_u64 v[232:233], v[232:233], 0, s[100:101]
	v_lshl_add_u64 v[234:235], v[234:235], 0, s[100:101]
	v_lshl_add_u64 v[236:237], v[236:237], 0, s[100:101]
	v_lshl_add_u64 v[238:239], v[238:239], 0, s[100:101]
	global_load_dwordx4 v[200:203], v[232:233], off
	global_load_dwordx4 v[204:207], v[232:233], off offset:256
	global_load_dwordx4 v[208:211], v[234:235], off
	global_load_dwordx4 v[212:215], v[234:235], off offset:256
	global_load_dwordx4 v[216:219], v[236:237], off
	global_load_dwordx4 v[220:223], v[236:237], off offset:256
	global_load_dwordx4 v[224:227], v[238:239], off
	global_load_dwordx4 v[228:231], v[238:239], off offset:256
	s_waitcnt vmcnt(0) lgkmcnt(0)
	v_lshlrev_b32_e32 v160, 16, v200
	v_and_b32_e32 v161, 0xffff0000, v200
	v_lshlrev_b32_e32 v128, 16, v201
	v_and_b32_e32 v129, 0xffff0000, v201
	v_lshlrev_b32_e32 v162, 16, v202
	v_and_b32_e32 v163, 0xffff0000, v202
	v_lshlrev_b32_e32 v130, 16, v203
	v_and_b32_e32 v131, 0xffff0000, v203
	v_pk_fma_f32 v[102:103], v[102:103], v[146:147], v[128:129]
	v_pk_fma_f32 v[100:101], v[100:101], v[144:145], v[160:161]
	v_pk_fma_f32 v[106:107], v[106:107], v[142:143], v[130:131]
	v_pk_fma_f32 v[104:105], v[104:105], v[140:141], v[162:163]
	v_cvt_pk_bf16_f32 v128, v100, v101
	v_cvt_pk_bf16_f32 v129, v102, v103
	s_nop 0
	v_cvt_pk_bf16_f32 v130, v104, v105
	v_cvt_pk_bf16_f32 v131, v106, v107
	s_nop 0
	flat_store_dwordx4 v[164:165], v[128:131]
	s_nop 1
	s_nop 0
	v_lshlrev_b32_e32 v128, 16, v204
	v_and_b32_e32 v129, 0xffff0000, v204
	v_lshlrev_b32_e32 v130, 16, v205
	v_and_b32_e32 v131, 0xffff0000, v205
	v_lshlrev_b32_e32 v160, 16, v206
	v_and_b32_e32 v161, 0xffff0000, v206
	v_lshlrev_b32_e32 v162, 16, v207
	v_and_b32_e32 v163, 0xffff0000, v207
	v_pk_fma_f32 v[126:127], v[126:127], v[138:139], v[130:131]
	v_pk_fma_f32 v[124:125], v[124:125], v[136:137], v[128:129]
	v_pk_fma_f32 v[114:115], v[114:115], v[134:135], v[162:163]
	v_pk_fma_f32 v[112:113], v[112:113], v[132:133], v[160:161]
	v_cvt_pk_bf16_f32 v128, v124, v125
	v_cvt_pk_bf16_f32 v129, v126, v127
	s_nop 0
	v_cvt_pk_bf16_f32 v130, v112, v113
	v_cvt_pk_bf16_f32 v131, v114, v115
	flat_store_dwordx4 v[156:157], v[128:131] offset:256
	v_lshl_add_u64 v[156:157], v[154:155], 0, s[2:3]
	s_mov_b32 s2, 0xa0000
	v_add_co_u32_e32 v164, vcc, s2, v154
	s_mov_b64 s[2:3], 0xa0000
	s_nop 0
	v_addc_co_u32_e32 v165, vcc, 0, v155, vcc
	s_nop 1
	v_lshlrev_b32_e32 v160, 16, v208
	v_and_b32_e32 v161, 0xffff0000, v208
	v_lshlrev_b32_e32 v128, 16, v209
	v_and_b32_e32 v129, 0xffff0000, v209
	v_lshlrev_b32_e32 v162, 16, v210
	v_and_b32_e32 v163, 0xffff0000, v210
	v_lshlrev_b32_e32 v130, 16, v211
	v_and_b32_e32 v131, 0xffff0000, v211
; __device__ __forceinline__ unsigned cvt_pk_bf16(float lo, float hi) { unsigned r; asm volatile("v_cvt_pk_bf16_f32 %0, %1, %2" : "=v"(r) : "v"(lo), "v"(hi)); return r; }
;     __device__ __forceinline__ void fused(f32x4 (&acc)[2][2][4][2], const Unit& un, int wr, int wc, int fr, int fq, PG8_LAS unsigned char* lds, int wid, int lane) const {
;     ...
;           for (int ai = 0; ai < 2; ++ai)
; #pragma unroll
;               for (int m = 0; m < 4; ++m) { const size_t off = (size_t)(row0 + ai * HALF + m * 16) * ldc + col0;
; #pragma unroll
;                   for (int bj = 0; bj < 2; ++bj) {
; #pragma unroll
;                       for (int n = 0; n < 2; ++n) { f32x4 bs;
;                           if (BASE_F32) bs = *(const f32x4*)((const float*)base + off + bj * HALF + n * 4);
;                           else { const u32x2v hw = *(const u32x2v*)((const bf16_t*)base + off + bj * HALF + n * 4);
;                                  bs = (f32x4){__uint_as_float(hw.x << 16), __uint_as_float(hw.x & 0xffff0000u), __uint_as_float(hw.y << 16), __uint_as_float(hw.y & 0xffff0000u)}; }
;                           acc[ai][bj][m][n] = bs + gv[bj][n] * acc[ai][bj][m][n]; }
;                       if (out_h) { const f32x4 a0 = acc[ai][bj][m][0], a1 = acc[ai][bj][m][1]; u32x4 w; w.x = cvt_pk_bf16(a0[0], a0[1]); w.y = cvt_pk_bf16(a0[2], a0[3]); w.z = cvt_pk_bf16(a1[0], a1[1]); w.w = cvt_pk_bf16(a1[2], a1[3]);
;                           *(u32x4*)(out_h + off + bj * HALF) = w; } }
;                   asm volatile("" : "+v"(acc[ai][0][m][0]), "+v"(acc[ai][0][m][1]), "+v"(acc[ai][1][m][0]), "+v"(acc[ai][1][m][1]));
;                   asm volatile("" ::: "memory"); } }
; #pragma unroll
;         for (int ai = 0; ai < 2; ++ai)
; #pragma unroll
;             for (int m = 0; m < 4; ++m) { float s = 0.f;
; #pragma unroll
;                 for (int bj = 0; bj < 2; ++bj)
; #pragma unroll
;                     for (int n = 0; n < 2; ++n) { const f32x4 x = acc[ai][bj][m][n]; s += (x[0] * x[0] + x[1] * x[1]) + (x[2] * x[2] + x[3] * x[3]); }
;                 s += __shfl_xor(s, 16); s += __shfl_xor(s, 32);
;                 if (fq == 0) P[(ai * HALF + wr * 64 + m * 16 + fr) * 4 + wc] = s; }
	v_pk_fma_f32 v[118:119], v[118:119], v[146:147], v[128:129]
	v_pk_fma_f32 v[116:117], v[116:117], v[144:145], v[160:161]
	v_pk_fma_f32 v[122:123], v[122:123], v[142:143], v[130:131]
	v_pk_fma_f32 v[120:121], v[120:121], v[140:141], v[162:163]
	v_cvt_pk_bf16_f32 v128, v116, v117
	v_cvt_pk_bf16_f32 v129, v118, v119
	s_nop 0
	v_cvt_pk_bf16_f32 v130, v120, v121
	v_cvt_pk_bf16_f32 v131, v122, v123
	s_nop 0
	flat_store_dwordx4 v[166:167], v[128:131]
	s_nop 1
	s_nop 0
	v_lshlrev_b32_e32 v128, 16, v212
	v_and_b32_e32 v129, 0xffff0000, v212
	v_lshlrev_b32_e32 v130, 16, v213
	v_and_b32_e32 v131, 0xffff0000, v213
	v_lshlrev_b32_e32 v160, 16, v214
	v_and_b32_e32 v161, 0xffff0000, v214
	v_lshlrev_b32_e32 v162, 16, v215
	v_and_b32_e32 v163, 0xffff0000, v215
	v_pk_fma_f32 v[94:95], v[94:95], v[138:139], v[130:131]
	v_pk_fma_f32 v[92:93], v[92:93], v[136:137], v[128:129]
	v_pk_fma_f32 v[90:91], v[90:91], v[134:135], v[162:163]
	v_pk_fma_f32 v[88:89], v[88:89], v[132:133], v[160:161]
	v_cvt_pk_bf16_f32 v128, v92, v93
	v_cvt_pk_bf16_f32 v129, v94, v95
	s_nop 0
	v_cvt_pk_bf16_f32 v130, v88, v89
	v_cvt_pk_bf16_f32 v131, v90, v91
	flat_store_dwordx4 v[156:157], v[128:131] offset:256
	v_lshl_add_u64 v[156:157], v[154:155], 0, s[2:3]
	s_mov_b32 s2, 0xb0000
	v_add_co_u32_e32 v166, vcc, s2, v154
	s_mov_b64 s[2:3], 0xb0000
	s_nop 0
	v_addc_co_u32_e32 v167, vcc, 0, v155, vcc
	s_nop 1
	v_lshlrev_b32_e32 v160, 16, v216
	v_and_b32_e32 v161, 0xffff0000, v216
	v_lshlrev_b32_e32 v128, 16, v217
	v_and_b32_e32 v129, 0xffff0000, v217
	v_lshlrev_b32_e32 v162, 16, v218
	v_and_b32_e32 v163, 0xffff0000, v218
	v_lshlrev_b32_e32 v130, 16, v219
	v_and_b32_e32 v131, 0xffff0000, v219
	v_pk_fma_f32 v[86:87], v[86:87], v[146:147], v[128:129]
	v_pk_fma_f32 v[84:85], v[84:85], v[144:145], v[160:161]
	v_pk_fma_f32 v[82:83], v[82:83], v[142:143], v[130:131]
	v_pk_fma_f32 v[80:81], v[80:81], v[140:141], v[162:163]
	v_cvt_pk_bf16_f32 v128, v84, v85
	v_cvt_pk_bf16_f32 v129, v86, v87
	s_nop 0
	v_cvt_pk_bf16_f32 v130, v80, v81
	v_cvt_pk_bf16_f32 v131, v82, v83
	s_nop 0
	flat_store_dwordx4 v[164:165], v[128:131]
	v_mul_f32_e32 v164, v29, v29
	v_mul_f32_e32 v165, v31, v31
	v_fmac_f32_e32 v164, v28, v28
	v_fmac_f32_e32 v165, v30, v30
	s_nop 1
	v_lshlrev_b32_e32 v128, 16, v220
	v_and_b32_e32 v129, 0xffff0000, v220
	v_lshlrev_b32_e32 v130, 16, v221
	v_and_b32_e32 v131, 0xffff0000, v221
	v_lshlrev_b32_e32 v160, 16, v222
	v_and_b32_e32 v161, 0xffff0000, v222
	v_lshlrev_b32_e32 v162, 16, v223
	v_and_b32_e32 v163, 0xffff0000, v223
	v_pk_fma_f32 v[46:47], v[46:47], v[138:139], v[130:131]
	v_pk_fma_f32 v[44:45], v[44:45], v[136:137], v[128:129]
	v_pk_fma_f32 v[42:43], v[42:43], v[134:135], v[162:163]
	v_pk_fma_f32 v[40:41], v[40:41], v[132:133], v[160:161]
	v_cvt_pk_bf16_f32 v128, v44, v45
	v_cvt_pk_bf16_f32 v129, v46, v47
	v_lshl_add_u64 v[160:161], v[154:155], 0, s[2:3]
	v_cvt_pk_bf16_f32 v130, v40, v41
	v_cvt_pk_bf16_f32 v131, v42, v43
	flat_store_dwordx4 v[156:157], v[128:131] offset:256
	v_mul_f32_e32 v162, v33, v33
	v_mul_f32_e32 v163, v35, v35
	v_fmac_f32_e32 v162, v32, v32
	v_fmac_f32_e32 v163, v34, v34
	s_lshl_b32 s2, s9, 2
	s_add_i32 s2, s2, 0
	s_nop 1
	v_lshlrev_b32_e32 v154, 16, v224
	v_and_b32_e32 v155, 0xffff0000, v224
	v_lshlrev_b32_e32 v128, 16, v225
	v_and_b32_e32 v129, 0xffff0000, v225
	v_lshlrev_b32_e32 v156, 16, v226
	v_and_b32_e32 v157, 0xffff0000, v226
	v_lshlrev_b32_e32 v130, 16, v227
	v_and_b32_e32 v131, 0xffff0000, v227
	v_pk_fma_f32 v[38:39], v[38:39], v[146:147], v[128:129]
	v_pk_fma_f32 v[36:37], v[36:37], v[144:145], v[154:155]
	v_pk_fma_f32 v[26:27], v[26:27], v[142:143], v[130:131]
	v_pk_fma_f32 v[24:25], v[24:25], v[140:141], v[156:157]
	v_cvt_pk_bf16_f32 v142, v36, v37
	v_cvt_pk_bf16_f32 v143, v38, v39
	v_mbcnt_lo_u32_b32 v128, -1, 0
	v_cvt_pk_bf16_f32 v144, v24, v25
	v_cvt_pk_bf16_f32 v145, v26, v27
	v_mbcnt_hi_u32_b32 v129, -1, v128
	v_mul_f32_e32 v140, v9, v9
	v_mul_f32_e32 v141, v11, v11
	v_mul_f32_e32 v146, v13, v13
	v_mul_f32_e32 v147, v15, v15
	v_and_b32_e32 v130, 64, v129
	v_fmac_f32_e32 v140, v8, v8
	v_fmac_f32_e32 v141, v10, v10
	v_fmac_f32_e32 v146, v12, v12
	v_fmac_f32_e32 v147, v14, v14
	v_xor_b32_e32 v128, 16, v129
	v_add_u32_e32 v130, 64, v130
	v_add_f32_e32 v140, v140, v141
	v_add_f32_e32 v141, v146, v147
	v_cmp_lt_i32_e32 vcc, v128, v130
	v_add_f32_e32 v146, v162, v163
	v_add_f32_e32 v140, v140, v141
	v_cndmask_b32_e32 v128, v129, v128, vcc
	v_add_f32_e32 v147, v164, v165
	v_add_f32_e32 v140, v146, v140
	v_lshlrev_b32_e32 v128, 2, v128
	v_add_f32_e32 v140, v147, v140
	ds_bpermute_b32 v141, v128, v140
	v_xor_b32_e32 v131, 32, v129
	v_cmp_lt_i32_e32 vcc, v131, v130
	flat_store_dwordx4 v[166:167], v[142:145]
	v_and_b32_e32 v130, 63, v158
	v_cndmask_b32_e32 v129, v129, v131, vcc
	v_lshlrev_b32_e32 v129, 2, v129
	s_waitcnt lgkmcnt(0)
	v_add_f32_e32 v140, v140, v141
	ds_bpermute_b32 v141, v129, v140
	v_cmp_gt_u32_e32 vcc, 16, v130
	s_waitcnt vmcnt(0)
	v_lshlrev_b32_e32 v142, 16, v228
	v_and_b32_e32 v143, 0xffff0000, v228
	v_lshlrev_b32_e32 v144, 16, v229
	v_and_b32_e32 v145, 0xffff0000, v229
	v_lshlrev_b32_e32 v146, 16, v230
	v_and_b32_e32 v147, 0xffff0000, v230
	v_lshlrev_b32_e32 v154, 16, v231
	v_and_b32_e32 v155, 0xffff0000, v231
	v_pk_fma_f32 v[6:7], v[6:7], v[138:139], v[144:145]
	v_pk_fma_f32 v[4:5], v[4:5], v[136:137], v[142:143]
	v_pk_fma_f32 v[2:3], v[2:3], v[134:135], v[154:155]
	v_pk_fma_f32 v[0:1], v[0:1], v[132:133], v[146:147]
	v_cvt_pk_bf16_f32 v132, v4, v5
	v_cvt_pk_bf16_f32 v133, v6, v7
	v_or_b32_e32 v144, s8, v159
	v_cvt_pk_bf16_f32 v134, v0, v1
	v_cvt_pk_bf16_f32 v135, v2, v3
	flat_store_dwordx4 v[160:161], v[132:135] offset:256
	v_lshl_add_u32 v131, v144, 4, s2
	s_and_saveexec_b64 s[2:3], vcc
	v_readlane_b32 s96, v254, 47
	s_cbranch_execz .LBB0_2919
	s_waitcnt lgkmcnt(0)
	v_add_f32_e32 v132, v140, v141
	ds_write_b32 v131, v132

; __device__ __forceinline__ unsigned cvt_pk_bf16(float lo, float hi) { unsigned r; asm volatile("v_cvt_pk_bf16_f32 %0, %1, %2" : "=v"(r) : "v"(lo), "v"(hi)); return r; }
;     __device__ __forceinline__ void fused(f32x4 (&acc)[2][2][4][2], const Unit& un, int wr, int wc, int fr, int fq, PG8_LAS unsigned char* lds, int wid, int lane) const {
;     ...
;         const int row0 = un.pm * BM + wr * 64 + fr, col0 = un.pn * BM + wc * 32 + 8 * fq;
;         const size_t boff = (size_t)(un.pm >> 3) * bstride + col0;
;         { f32x4 gv[2][2];
; #pragma unroll
;           for (int bj = 0; bj < 2; ++bj)
; #pragma unroll
;               for (int n = 0; n < 2; ++n) gv[bj][n] = *(const f32x4*)(gate + boff + bj * HALF + n * 4);
; #pragma unroll
;           for (int ai = 0; ai < 2; ++ai)
; #pragma unroll
;               for (int m = 0; m < 4; ++m) { const size_t off = (size_t)(row0 + ai * HALF + m * 16) * ldc + col0;
; #pragma unroll
;                   for (int bj = 0; bj < 2; ++bj) {
; #pragma unroll
;                       for (int n = 0; n < 2; ++n) { f32x4 bs;
;                           if (BASE_F32) bs = *(const f32x4*)((const float*)base + off + bj * HALF + n * 4);
;                           else { const u32x2v hw = *(const u32x2v*)((const bf16_t*)base + off + bj * HALF + n * 4);
;                                  bs = (f32x4){__uint_as_float(hw.x << 16), __uint_as_float(hw.x & 0xffff0000u), __uint_as_float(hw.y << 16), __uint_as_float(hw.y & 0xffff0000u)}; }
;                           acc[ai][bj][m][n] = bs + gv[bj][n] * acc[ai][bj][m][n]; }
;                       if (out_h) { const f32x4 a0 = acc[ai][bj][m][0], a1 = acc[ai][bj][m][1]; u32x4 w; w.x = cvt_pk_bf16(a0[0], a0[1]); w.y = cvt_pk_bf16(a0[2], a0[3]); w.z = cvt_pk_bf16(a1[0], a1[1]); w.w = cvt_pk_bf16(a1[2], a1[3]);
;                           *(u32x4*)(out_h + off + bj * HALF) = w; } }
;                   asm volatile("" : "+v"(acc[ai][0][m][0]), "+v"(acc[ai][0][m][1]), "+v"(acc[ai][1][m][0]), "+v"(acc[ai][1][m][1]));
.LBB0_3611:
	v_mov_b32_e32 v32, 0
	s_barrier
	s_lshl_b32 s4, s26, 5
	v_mbcnt_lo_u32_b32 v32, -1, v32
	s_add_u32 s0, s8, 0x1a600000
	v_mbcnt_hi_u32_b32 v32, -1, v32
	s_addc_u32 s1, s9, 0
	v_or_b32_e32 v158, s33, v32
	s_lshl_b32 s5, s2, 8
	s_lshl_b32 s27, s12, 8
	s_or_b32 s4, s5, s4
	v_lshrrev_b32_e32 v32, 1, v158
	v_and_b32_e32 v159, 15, v158
	s_add_i32 s14, s27, s13
	v_and_or_b32 v152, v32, 24, s4
	s_ashr_i32 s4, s12, 3
	v_ashrrev_i32_e32 v153, 31, v152
	v_mov_b32_e32 v32, 0x3000
	v_or_b32_e32 v156, s14, v159
	v_mad_i64_i32 v[32:33], s[4:5], s4, v32, v[152:153]
	v_ashrrev_i32_e32 v157, 31, v156
	v_lshl_add_u64 v[150:151], v[32:33], 2, s[8:9]
	v_lshlrev_b64 v[32:33], 12, v[156:157]
	v_lshl_add_u64 v[32:33], s[0:1], 0, v[32:33]
	v_lshlrev_b64 v[148:149], 1, v[152:153]
	s_mov_b32 s14, 0x194000
	v_lshl_add_u64 v[154:155], v[32:33], 0, v[148:149]
	v_add_co_u32_e32 v132, vcc, s14, v150
	s_nop 0
	v_addc_co_u32_e32 v133, vcc, 0, v151, vcc
	s_mov_b64 s[4:5], 0x194000
	flat_load_dwordx4 v[144:147], v[132:133]
	v_lshl_add_u64 v[132:133], v[150:151], 0, s[4:5]
	flat_load_dwordx4 v[140:143], v[132:133] offset:16
	flat_load_dwordx4 v[136:139], v[132:133] offset:512
	s_nop 0
	flat_load_dwordx4 v[132:135], v[132:133] offset:528
	v_or_b32_e32 v164, 16, v156
	v_ashrrev_i32_e32 v165, 31, v164
	v_lshlrev_b64 v[164:165], 12, v[164:165]
	v_lshl_add_u64 v[164:165], s[0:1], 0, v[164:165]
	v_lshl_add_u64 v[164:165], v[164:165], 0, v[148:149]
	s_mov_b64 s[98:99], 0x10000
	s_mov_b64 s[100:101], 0x80000
	v_lshl_add_u64 v[232:233], v[154:155], 0, 0
	v_lshl_add_u64 v[234:235], v[232:233], 0, s[98:99]
	v_lshl_add_u64 v[236:237], v[234:235], 0, s[98:99]
	v_lshl_add_u64 v[238:239], v[236:237], 0, s[98:99]
	global_load_dwordx4 v[200:203], v[232:233], off
	global_load_dwordx4 v[204:207], v[232:233], off offset:256
	global_load_dwordx4 v[208:211], v[234:235], off
	global_load_dwordx4 v[212:215], v[234:235], off offset:256
	global_load_dwordx4 v[216:219], v[236:237], off
	global_load_dwordx4 v[220:223], v[236:237], off offset:256
	global_load_dwordx4 v[224:227], v[238:239], off
	global_load_dwordx4 v[228:231], v[238:239], off offset:256
	s_waitcnt vmcnt(0) lgkmcnt(0)
	v_lshlrev_b32_e32 v160, 16, v200
	v_and_b32_e32 v161, 0xffff0000, v200
	v_lshlrev_b32_e32 v32, 16, v201
	v_and_b32_e32 v33, 0xffff0000, v201
	v_lshlrev_b32_e32 v162, 16, v202
	v_and_b32_e32 v163, 0xffff0000, v202
	v_lshlrev_b32_e32 v34, 16, v203
	v_and_b32_e32 v35, 0xffff0000, v203
	v_pk_fma_f32 v[10:11], v[10:11], v[146:147], v[32:33]
	v_pk_fma_f32 v[8:9], v[8:9], v[144:145], v[160:161]
	v_pk_fma_f32 v[14:15], v[14:15], v[142:143], v[34:35]
	v_pk_fma_f32 v[12:13], v[12:13], v[140:141], v[162:163]
	v_cvt_pk_bf16_f32 v32, v8, v9
	v_cvt_pk_bf16_f32 v33, v10, v11
	s_nop 0
	v_cvt_pk_bf16_f32 v34, v12, v13
	v_cvt_pk_bf16_f32 v35, v14, v15
	s_nop 0
	flat_store_dwordx4 v[154:155], v[32:35]
	s_nop 1
	s_nop 0
	v_lshlrev_b32_e32 v32, 16, v204
	v_and_b32_e32 v33, 0xffff0000, v204
	v_lshlrev_b32_e32 v34, 16, v205
	v_and_b32_e32 v35, 0xffff0000, v205
	v_lshlrev_b32_e32 v160, 16, v206
	v_and_b32_e32 v161, 0xffff0000, v206
	v_lshlrev_b32_e32 v162, 16, v207
	v_and_b32_e32 v163, 0xffff0000, v207
	v_pk_fma_f32 v[34:35], v[26:27], v[138:139], v[34:35]
	v_pk_fma_f32 v[32:33], v[24:25], v[136:137], v[32:33]
	v_pk_fma_f32 v[26:27], v[18:19], v[134:135], v[162:163]
	v_pk_fma_f32 v[24:25], v[16:17], v[132:133], v[160:161]
	v_cvt_pk_bf16_f32 v16, v32, v33
	v_cvt_pk_bf16_f32 v17, v34, v35
	s_nop 0
	v_cvt_pk_bf16_f32 v18, v24, v25
	v_cvt_pk_bf16_f32 v19, v26, v27
	flat_store_dwordx4 v[154:155], v[16:19] offset:256
	s_nop 1
	v_lshlrev_b32_e32 v160, 16, v208
	v_and_b32_e32 v161, 0xffff0000, v208
	v_lshlrev_b32_e32 v16, 16, v209
	v_and_b32_e32 v17, 0xffff0000, v209
	v_lshlrev_b32_e32 v162, 16, v210
	v_and_b32_e32 v163, 0xffff0000, v210
	v_lshlrev_b32_e32 v166, 16, v211
	v_and_b32_e32 v167, 0xffff0000, v211
	v_pk_fma_f32 v[18:19], v[62:63], v[146:147], v[16:17]
	v_pk_fma_f32 v[16:17], v[60:61], v[144:145], v[160:161]
	v_pk_fma_f32 v[22:23], v[22:23], v[142:143], v[166:167]
	v_pk_fma_f32 v[20:21], v[20:21], v[140:141], v[162:163]
	v_cvt_pk_bf16_f32 v60, v16, v17
	v_cvt_pk_bf16_f32 v61, v18, v19
	v_or_b32_e32 v166, 32, v156
	v_cvt_pk_bf16_f32 v62, v20, v21
	v_cvt_pk_bf16_f32 v63, v22, v23
	v_ashrrev_i32_e32 v167, 31, v166
	v_lshlrev_b64 v[166:167], 12, v[166:167]
	flat_store_dwordx4 v[164:165], v[60:63]
	v_lshl_add_u64 v[166:167], s[0:1], 0, v[166:167]
	v_lshl_add_u64 v[166:167], v[166:167], 0, v[148:149]
	v_or_b32_e32 v156, 48, v156
	v_ashrrev_i32_e32 v157, 31, v156
	v_lshlrev_b64 v[156:157], 12, v[156:157]
	v_lshl_add_u64 v[156:157], s[0:1], 0, v[156:157]
	v_lshl_add_u64 v[156:157], v[156:157], 0, v[148:149]
	s_mov_b32 s0, 0x80000
	s_nop 1
	v_lshlrev_b32_e32 v60, 16, v212
	v_and_b32_e32 v61, 0xffff0000, v212
	v_lshlrev_b32_e32 v62, 16, v213
	v_and_b32_e32 v63, 0xffff0000, v213
	v_lshlrev_b32_e32 v160, 16, v214
	v_and_b32_e32 v161, 0xffff0000, v214
	v_lshlrev_b32_e32 v162, 16, v215
	v_and_b32_e32 v163, 0xffff0000, v215
	v_pk_fma_f32 v[62:63], v[58:59], v[138:139], v[62:63]
	v_pk_fma_f32 v[60:61], v[56:57], v[136:137], v[60:61]
	v_pk_fma_f32 v[58:59], v[50:51], v[134:135], v[162:163]
	v_pk_fma_f32 v[56:57], v[48:49], v[132:133], v[160:161]
	v_cvt_pk_bf16_f32 v48, v60, v61
	v_cvt_pk_bf16_f32 v49, v62, v63
	s_nop 0
	v_cvt_pk_bf16_f32 v50, v56, v57
	v_cvt_pk_bf16_f32 v51, v58, v59
	flat_store_dwordx4 v[164:165], v[48:51] offset:256
	s_nop 1
	v_lshlrev_b32_e32 v160, 16, v216
	v_and_b32_e32 v161, 0xffff0000, v216
	v_lshlrev_b32_e32 v48, 16, v217
	v_and_b32_e32 v49, 0xffff0000, v217
	v_lshlrev_b32_e32 v162, 16, v218
	v_and_b32_e32 v163, 0xffff0000, v218
; __device__ __forceinline__ unsigned cvt_pk_bf16(float lo, float hi) { unsigned r; asm volatile("v_cvt_pk_bf16_f32 %0, %1, %2" : "=v"(r) : "v"(lo), "v"(hi)); return r; }
;     __device__ __forceinline__ void fused(f32x4 (&acc)[2][2][4][2], const Unit& un, int wr, int wc, int fr, int fq, PG8_LAS unsigned char* lds, int wid, int lane) const {
;     ...
;           for (int ai = 0; ai < 2; ++ai)
; #pragma unroll
;               for (int m = 0; m < 4; ++m) { const size_t off = (size_t)(row0 + ai * HALF + m * 16) * ldc + col0;
; #pragma unroll
;                   for (int bj = 0; bj < 2; ++bj) {
; #pragma unroll
;                       for (int n = 0; n < 2; ++n) { f32x4 bs;
;                           if (BASE_F32) bs = *(const f32x4*)((const float*)base + off + bj * HALF + n * 4);
;                           else { const u32x2v hw = *(const u32x2v*)((const bf16_t*)base + off + bj * HALF + n * 4);
;                                  bs = (f32x4){__uint_as_float(hw.x << 16), __uint_as_float(hw.x & 0xffff0000u), __uint_as_float(hw.y << 16), __uint_as_float(hw.y & 0xffff0000u)}; }
;                           acc[ai][bj][m][n] = bs + gv[bj][n] * acc[ai][bj][m][n]; }
;                       if (out_h) { const f32x4 a0 = acc[ai][bj][m][0], a1 = acc[ai][bj][m][1]; u32x4 w; w.x = cvt_pk_bf16(a0[0], a0[1]); w.y = cvt_pk_bf16(a0[2], a0[3]); w.z = cvt_pk_bf16(a1[0], a1[1]); w.w = cvt_pk_bf16(a1[2], a1[3]);
;                           *(u32x4*)(out_h + off + bj * HALF) = w; } }
;                   asm volatile("" : "+v"(acc[ai][0][m][0]), "+v"(acc[ai][0][m][1]), "+v"(acc[ai][1][m][0]), "+v"(acc[ai][1][m][1]));
	v_lshlrev_b32_e32 v164, 16, v219
	v_and_b32_e32 v165, 0xffff0000, v219
	v_pk_fma_f32 v[50:51], v[78:79], v[146:147], v[48:49]
	v_pk_fma_f32 v[48:49], v[76:77], v[144:145], v[160:161]
	v_pk_fma_f32 v[54:55], v[54:55], v[142:143], v[164:165]
	v_pk_fma_f32 v[52:53], v[52:53], v[140:141], v[162:163]
	v_cvt_pk_bf16_f32 v76, v48, v49
	v_cvt_pk_bf16_f32 v77, v50, v51
	s_nop 0
	v_cvt_pk_bf16_f32 v78, v52, v53
	v_cvt_pk_bf16_f32 v79, v54, v55
	s_nop 0
	flat_store_dwordx4 v[166:167], v[76:79]
	s_nop 1
	s_nop 0
	v_lshlrev_b32_e32 v76, 16, v220
	v_and_b32_e32 v77, 0xffff0000, v220
	v_lshlrev_b32_e32 v78, 16, v221
	v_and_b32_e32 v79, 0xffff0000, v221
	v_lshlrev_b32_e32 v160, 16, v222
	v_and_b32_e32 v161, 0xffff0000, v222
	v_lshlrev_b32_e32 v162, 16, v223
	v_and_b32_e32 v163, 0xffff0000, v223
	v_pk_fma_f32 v[78:79], v[74:75], v[138:139], v[78:79]
	v_pk_fma_f32 v[76:77], v[72:73], v[136:137], v[76:77]
	v_pk_fma_f32 v[74:75], v[66:67], v[134:135], v[162:163]
	v_pk_fma_f32 v[72:73], v[64:65], v[132:133], v[160:161]
	v_cvt_pk_bf16_f32 v64, v76, v77
	v_cvt_pk_bf16_f32 v65, v78, v79
	s_nop 0
	v_cvt_pk_bf16_f32 v66, v72, v73
	v_cvt_pk_bf16_f32 v67, v74, v75
	flat_store_dwordx4 v[166:167], v[64:67] offset:256
	s_nop 1
	v_lshlrev_b32_e32 v160, 16, v224
	v_and_b32_e32 v161, 0xffff0000, v224
	v_lshlrev_b32_e32 v64, 16, v225
	v_and_b32_e32 v65, 0xffff0000, v225
	v_lshlrev_b32_e32 v162, 16, v226
	v_and_b32_e32 v163, 0xffff0000, v226
	v_lshlrev_b32_e32 v164, 16, v227
	v_and_b32_e32 v165, 0xffff0000, v227
	v_pk_fma_f32 v[66:67], v[130:131], v[146:147], v[64:65]
	v_pk_fma_f32 v[64:65], v[128:129], v[144:145], v[160:161]
	v_pk_fma_f32 v[70:71], v[70:71], v[142:143], v[164:165]
	v_pk_fma_f32 v[68:69], v[68:69], v[140:141], v[162:163]
	v_cvt_pk_bf16_f32 v128, v64, v65
	v_cvt_pk_bf16_f32 v129, v66, v67
	v_add_co_u32_e32 v164, vcc, s0, v154
	v_cvt_pk_bf16_f32 v130, v68, v69
	v_cvt_pk_bf16_f32 v131, v70, v71
	s_nop 0
	v_addc_co_u32_e32 v165, vcc, 0, v155, vcc
	flat_store_dwordx4 v[156:157], v[128:131]
	s_mov_b64 s[0:1], 0x80000
	s_nop 1
	v_lshlrev_b32_e32 v128, 16, v228
	v_and_b32_e32 v129, 0xffff0000, v228
	v_lshlrev_b32_e32 v130, 16, v229
	v_and_b32_e32 v131, 0xffff0000, v229
	v_lshlrev_b32_e32 v160, 16, v230
	v_and_b32_e32 v161, 0xffff0000, v230
	v_lshlrev_b32_e32 v162, 16, v231
	v_and_b32_e32 v163, 0xffff0000, v231
	v_pk_fma_f32 v[110:111], v[110:111], v[138:139], v[130:131]
	v_pk_fma_f32 v[108:109], v[108:109], v[136:137], v[128:129]
	v_pk_fma_f32 v[98:99], v[98:99], v[134:135], v[162:163]
	v_pk_fma_f32 v[96:97], v[96:97], v[132:133], v[160:161]
	v_cvt_pk_bf16_f32 v128, v108, v109
	v_cvt_pk_bf16_f32 v129, v110, v111
	s_nop 0
	v_cvt_pk_bf16_f32 v130, v96, v97
	v_cvt_pk_bf16_f32 v131, v98, v99
	flat_store_dwordx4 v[156:157], v[128:131] offset:256
	v_lshl_add_u64 v[156:157], v[154:155], 0, s[0:1]
	s_mov_b32 s0, 0x90000
	v_add_co_u32_e32 v166, vcc, s0, v154
	s_mov_b64 s[0:1], 0x90000
	s_nop 0
	v_addc_co_u32_e32 v167, vcc, 0, v155, vcc
	v_lshl_add_u64 v[232:233], v[232:233], 0, s[100:101]
	v_lshl_add_u64 v[234:235], v[234:235], 0, s[100:101]
	v_lshl_add_u64 v[236:237], v[236:237], 0, s[100:101]
	v_lshl_add_u64 v[238:239], v[238:239], 0, s[100:101]
	global_load_dwordx4 v[200:203], v[232:233], off
	global_load_dwordx4 v[204:207], v[232:233], off offset:256
	global_load_dwordx4 v[208:211], v[234:235], off
	global_load_dwordx4 v[212:215], v[234:235], off offset:256
	global_load_dwordx4 v[216:219], v[236:237], off
	global_load_dwordx4 v[220:223], v[236:237], off offset:256
	global_load_dwordx4 v[224:227], v[238:239], off
	global_load_dwordx4 v[228:231], v[238:239], off offset:256
	s_waitcnt vmcnt(0) lgkmcnt(0)
	v_lshlrev_b32_e32 v160, 16, v200
	v_and_b32_e32 v161, 0xffff0000, v200
	v_lshlrev_b32_e32 v128, 16, v201
	v_and_b32_e32 v129, 0xffff0000, v201
	v_lshlrev_b32_e32 v162, 16, v202
	v_and_b32_e32 v163, 0xffff0000, v202
	v_lshlrev_b32_e32 v130, 16, v203
	v_and_b32_e32 v131, 0xffff0000, v203
	v_pk_fma_f32 v[102:103], v[102:103], v[146:147], v[128:129]
	v_pk_fma_f32 v[100:101], v[100:101], v[144:145], v[160:161]
	v_pk_fma_f32 v[106:107], v[106:107], v[142:143], v[130:131]
	v_pk_fma_f32 v[104:105], v[104:105], v[140:141], v[162:163]
	v_cvt_pk_bf16_f32 v128, v100, v101
	v_cvt_pk_bf16_f32 v129, v102, v103
	s_nop 0
	v_cvt_pk_bf16_f32 v130, v104, v105
	v_cvt_pk_bf16_f32 v131, v106, v107
	s_nop 0
	flat_store_dwordx4 v[164:165], v[128:131]
	s_nop 1
	s_nop 0
	v_lshlrev_b32_e32 v128, 16, v204
	v_and_b32_e32 v129, 0xffff0000, v204
	v_lshlrev_b32_e32 v130, 16, v205
	v_and_b32_e32 v131, 0xffff0000, v205
	v_lshlrev_b32_e32 v160, 16, v206
	v_and_b32_e32 v161, 0xffff0000, v206
	v_lshlrev_b32_e32 v162, 16, v207
	v_and_b32_e32 v163, 0xffff0000, v207
	v_pk_fma_f32 v[126:127], v[126:127], v[138:139], v[130:131]
	v_pk_fma_f32 v[124:125], v[124:125], v[136:137], v[128:129]
	v_pk_fma_f32 v[114:115], v[114:115], v[134:135], v[162:163]
	v_pk_fma_f32 v[112:113], v[112:113], v[132:133], v[160:161]
	v_cvt_pk_bf16_f32 v128, v124, v125
	v_cvt_pk_bf16_f32 v129, v126, v127
	s_nop 0
	v_cvt_pk_bf16_f32 v130, v112, v113
	v_cvt_pk_bf16_f32 v131, v114, v115
	flat_store_dwordx4 v[156:157], v[128:131] offset:256
	v_lshl_add_u64 v[156:157], v[154:155], 0, s[0:1]
	s_mov_b32 s0, 0xa0000
	v_add_co_u32_e32 v164, vcc, s0, v154
	s_mov_b64 s[0:1], 0xa0000
	s_nop 0
	v_addc_co_u32_e32 v165, vcc, 0, v155, vcc
	s_nop 1
	v_lshlrev_b32_e32 v160, 16, v208
	v_and_b32_e32 v161, 0xffff0000, v208
	v_lshlrev_b32_e32 v128, 16, v209
	v_and_b32_e32 v129, 0xffff0000, v209
	v_lshlrev_b32_e32 v162, 16, v210
	v_and_b32_e32 v163, 0xffff0000, v210
	v_lshlrev_b32_e32 v130, 16, v211
	v_and_b32_e32 v131, 0xffff0000, v211
; __device__ __forceinline__ unsigned cvt_pk_bf16(float lo, float hi) { unsigned r; asm volatile("v_cvt_pk_bf16_f32 %0, %1, %2" : "=v"(r) : "v"(lo), "v"(hi)); return r; }
;     __device__ __forceinline__ void fused(f32x4 (&acc)[2][2][4][2], const Unit& un, int wr, int wc, int fr, int fq, PG8_LAS unsigned char* lds, int wid, int lane) const {
;     ...
;           for (int ai = 0; ai < 2; ++ai)
; #pragma unroll
;               for (int m = 0; m < 4; ++m) { const size_t off = (size_t)(row0 + ai * HALF + m * 16) * ldc + col0;
; #pragma unroll
;                   for (int bj = 0; bj < 2; ++bj) {
; #pragma unroll
;                       for (int n = 0; n < 2; ++n) { f32x4 bs;
;                           if (BASE_F32) bs = *(const f32x4*)((const float*)base + off + bj * HALF + n * 4);
;                           else { const u32x2v hw = *(const u32x2v*)((const bf16_t*)base + off + bj * HALF + n * 4);
;                                  bs = (f32x4){__uint_as_float(hw.x << 16), __uint_as_float(hw.x & 0xffff0000u), __uint_as_float(hw.y << 16), __uint_as_float(hw.y & 0xffff0000u)}; }
;                           acc[ai][bj][m][n] = bs + gv[bj][n] * acc[ai][bj][m][n]; }
;                       if (out_h) { const f32x4 a0 = acc[ai][bj][m][0], a1 = acc[ai][bj][m][1]; u32x4 w; w.x = cvt_pk_bf16(a0[0], a0[1]); w.y = cvt_pk_bf16(a0[2], a0[3]); w.z = cvt_pk_bf16(a1[0], a1[1]); w.w = cvt_pk_bf16(a1[2], a1[3]);
;                           *(u32x4*)(out_h + off + bj * HALF) = w; } }
;                   asm volatile("" : "+v"(acc[ai][0][m][0]), "+v"(acc[ai][0][m][1]), "+v"(acc[ai][1][m][0]), "+v"(acc[ai][1][m][1]));
;                   asm volatile("" ::: "memory"); } }
; #pragma unroll
;         for (int ai = 0; ai < 2; ++ai)
; #pragma unroll
;             for (int m = 0; m < 4; ++m) { float s = 0.f;
; #pragma unroll
;                 for (int bj = 0; bj < 2; ++bj)
; #pragma unroll
;                     for (int n = 0; n < 2; ++n) { const f32x4 x = acc[ai][bj][m][n]; s += (x[0] * x[0] + x[1] * x[1]) + (x[2] * x[2] + x[3] * x[3]); }
;                 s += __shfl_xor(s, 16); s += __shfl_xor(s, 32);
;                 if (fq == 0) P[(ai * HALF + wr * 64 + m * 16 + fr) * 4 + wc] = s; }
	v_pk_fma_f32 v[118:119], v[118:119], v[146:147], v[128:129]
	v_pk_fma_f32 v[116:117], v[116:117], v[144:145], v[160:161]
	v_pk_fma_f32 v[122:123], v[122:123], v[142:143], v[130:131]
	v_pk_fma_f32 v[120:121], v[120:121], v[140:141], v[162:163]
	v_cvt_pk_bf16_f32 v128, v116, v117
	v_cvt_pk_bf16_f32 v129, v118, v119
	s_nop 0
	v_cvt_pk_bf16_f32 v130, v120, v121
	v_cvt_pk_bf16_f32 v131, v122, v123
	s_nop 0
	flat_store_dwordx4 v[166:167], v[128:131]
	s_nop 1
	s_nop 0
	v_lshlrev_b32_e32 v128, 16, v212
	v_and_b32_e32 v129, 0xffff0000, v212
	v_lshlrev_b32_e32 v130, 16, v213
	v_and_b32_e32 v131, 0xffff0000, v213
	v_lshlrev_b32_e32 v160, 16, v214
	v_and_b32_e32 v161, 0xffff0000, v214
	v_lshlrev_b32_e32 v162, 16, v215
	v_and_b32_e32 v163, 0xffff0000, v215
	v_pk_fma_f32 v[94:95], v[94:95], v[138:139], v[130:131]
	v_pk_fma_f32 v[92:93], v[92:93], v[136:137], v[128:129]
	v_pk_fma_f32 v[90:91], v[90:91], v[134:135], v[162:163]
	v_pk_fma_f32 v[88:89], v[88:89], v[132:133], v[160:161]
	v_cvt_pk_bf16_f32 v128, v92, v93
	v_cvt_pk_bf16_f32 v129, v94, v95
	s_nop 0
	v_cvt_pk_bf16_f32 v130, v88, v89
	v_cvt_pk_bf16_f32 v131, v90, v91
	flat_store_dwordx4 v[156:157], v[128:131] offset:256
	v_lshl_add_u64 v[156:157], v[154:155], 0, s[0:1]
	s_mov_b32 s0, 0xb0000
	v_add_co_u32_e32 v166, vcc, s0, v154
	s_mov_b64 s[0:1], 0xb0000
	s_nop 0
	v_addc_co_u32_e32 v167, vcc, 0, v155, vcc
	s_nop 1
	v_lshlrev_b32_e32 v160, 16, v216
	v_and_b32_e32 v161, 0xffff0000, v216
	v_lshlrev_b32_e32 v128, 16, v217
	v_and_b32_e32 v129, 0xffff0000, v217
	v_lshlrev_b32_e32 v162, 16, v218
	v_and_b32_e32 v163, 0xffff0000, v218
	v_lshlrev_b32_e32 v130, 16, v219
	v_and_b32_e32 v131, 0xffff0000, v219
	v_pk_fma_f32 v[86:87], v[86:87], v[146:147], v[128:129]
	v_pk_fma_f32 v[84:85], v[84:85], v[144:145], v[160:161]
	v_pk_fma_f32 v[82:83], v[82:83], v[142:143], v[130:131]
	v_pk_fma_f32 v[80:81], v[80:81], v[140:141], v[162:163]
	v_cvt_pk_bf16_f32 v128, v84, v85
	v_cvt_pk_bf16_f32 v129, v86, v87
	s_nop 0
	v_cvt_pk_bf16_f32 v130, v80, v81
	v_cvt_pk_bf16_f32 v131, v82, v83
	s_nop 0
	flat_store_dwordx4 v[164:165], v[128:131]
	v_mul_f32_e32 v164, v25, v25
	v_mul_f32_e32 v165, v27, v27
	v_fmac_f32_e32 v164, v24, v24
	v_fmac_f32_e32 v165, v26, v26
	s_nop 1
	v_lshlrev_b32_e32 v128, 16, v220
	v_and_b32_e32 v129, 0xffff0000, v220
	v_lshlrev_b32_e32 v130, 16, v221
	v_and_b32_e32 v131, 0xffff0000, v221
	v_lshlrev_b32_e32 v160, 16, v222
	v_and_b32_e32 v161, 0xffff0000, v222
	v_lshlrev_b32_e32 v162, 16, v223
	v_and_b32_e32 v163, 0xffff0000, v223
	v_pk_fma_f32 v[46:47], v[46:47], v[138:139], v[130:131]
	v_pk_fma_f32 v[44:45], v[44:45], v[136:137], v[128:129]
	v_pk_fma_f32 v[42:43], v[42:43], v[134:135], v[162:163]
	v_pk_fma_f32 v[40:41], v[40:41], v[132:133], v[160:161]
	v_cvt_pk_bf16_f32 v128, v44, v45
	v_cvt_pk_bf16_f32 v129, v46, v47
	v_lshl_add_u64 v[160:161], v[154:155], 0, s[0:1]
	v_cvt_pk_bf16_f32 v130, v40, v41
	v_cvt_pk_bf16_f32 v131, v42, v43
	flat_store_dwordx4 v[156:157], v[128:131] offset:256
	v_mul_f32_e32 v162, v33, v33
	v_mul_f32_e32 v163, v35, v35
	v_fmac_f32_e32 v162, v32, v32
	v_fmac_f32_e32 v163, v34, v34
	s_lshl_b32 s0, s26, 2
	s_add_i32 s0, s0, 0
	s_nop 1
	v_lshlrev_b32_e32 v154, 16, v224
	v_and_b32_e32 v155, 0xffff0000, v224
	v_lshlrev_b32_e32 v128, 16, v225
	v_and_b32_e32 v129, 0xffff0000, v225
	v_lshlrev_b32_e32 v156, 16, v226
	v_and_b32_e32 v157, 0xffff0000, v226
	v_lshlrev_b32_e32 v130, 16, v227
	v_and_b32_e32 v131, 0xffff0000, v227
	v_pk_fma_f32 v[38:39], v[38:39], v[146:147], v[128:129]
	v_pk_fma_f32 v[36:37], v[36:37], v[144:145], v[154:155]
	v_pk_fma_f32 v[30:31], v[30:31], v[142:143], v[130:131]
	v_pk_fma_f32 v[28:29], v[28:29], v[140:141], v[156:157]
	v_cvt_pk_bf16_f32 v142, v36, v37
	v_cvt_pk_bf16_f32 v143, v38, v39
	v_mbcnt_lo_u32_b32 v128, -1, 0
	v_cvt_pk_bf16_f32 v144, v28, v29
	v_cvt_pk_bf16_f32 v145, v30, v31
	v_mbcnt_hi_u32_b32 v129, -1, v128
	v_mul_f32_e32 v140, v9, v9
	v_mul_f32_e32 v141, v11, v11
	v_mul_f32_e32 v146, v13, v13
	v_mul_f32_e32 v147, v15, v15
	v_and_b32_e32 v130, 64, v129
	v_fmac_f32_e32 v140, v8, v8
	v_fmac_f32_e32 v141, v10, v10
	v_fmac_f32_e32 v146, v12, v12
	v_fmac_f32_e32 v147, v14, v14
	v_xor_b32_e32 v128, 16, v129
	v_add_u32_e32 v130, 64, v130
	v_add_f32_e32 v140, v140, v141
	v_add_f32_e32 v141, v146, v147
	v_cmp_lt_i32_e32 vcc, v128, v130
	v_add_f32_e32 v146, v162, v163
	v_add_f32_e32 v140, v140, v141
	v_cndmask_b32_e32 v128, v129, v128, vcc
	v_add_f32_e32 v147, v164, v165
	v_add_f32_e32 v140, v146, v140
	v_lshlrev_b32_e32 v128, 2, v128
	v_add_f32_e32 v140, v147, v140
	ds_bpermute_b32 v141, v128, v140
	v_xor_b32_e32 v131, 32, v129
	v_cmp_lt_i32_e32 vcc, v131, v130
	flat_store_dwordx4 v[166:167], v[142:145]
	v_and_b32_e32 v130, 63, v158
	v_cndmask_b32_e32 v129, v129, v131, vcc
	v_lshlrev_b32_e32 v129, 2, v129
	s_waitcnt lgkmcnt(0)
	v_add_f32_e32 v140, v140, v141
	ds_bpermute_b32 v141, v129, v140
	v_cmp_gt_u32_e32 vcc, 16, v130
	s_waitcnt vmcnt(0)
	v_lshlrev_b32_e32 v142, 16, v228
	v_and_b32_e32 v143, 0xffff0000, v228
	v_lshlrev_b32_e32 v144, 16, v229
	v_and_b32_e32 v145, 0xffff0000, v229
	v_lshlrev_b32_e32 v146, 16, v230
	v_and_b32_e32 v147, 0xffff0000, v230
	v_lshlrev_b32_e32 v154, 16, v231
	v_and_b32_e32 v155, 0xffff0000, v231
	v_pk_fma_f32 v[6:7], v[6:7], v[138:139], v[144:145]
	v_pk_fma_f32 v[4:5], v[4:5], v[136:137], v[142:143]
	v_pk_fma_f32 v[2:3], v[2:3], v[134:135], v[154:155]
	v_pk_fma_f32 v[0:1], v[0:1], v[132:133], v[146:147]
	v_cvt_pk_bf16_f32 v132, v4, v5
	v_cvt_pk_bf16_f32 v133, v6, v7
	v_or_b32_e32 v144, s13, v159
	v_cvt_pk_bf16_f32 v134, v0, v1
	v_cvt_pk_bf16_f32 v135, v2, v3
	flat_store_dwordx4 v[160:161], v[132:135] offset:256
	v_lshl_add_u32 v131, v144, 4, s0
	s_and_saveexec_b64 s[0:1], vcc
	v_readlane_b32 s96, v254, 47
	s_cbranch_execz .LBB0_3613
	s_waitcnt lgkmcnt(0)
	v_add_f32_e32 v132, v140, v141
	ds_write_b32 v131, v132

;     __device__ __forceinline__ void fused(f32x4 (&acc)[2][2][4][2], const Unit& un, int wr, int wc, int fr, int fq, PG8_LAS unsigned char* lds, int wid, int lane) const {
;     ...
;         const int row0 = un.pm * BM + wr * 64 + fr, col0 = un.pn * BM + wc * 32 + 8 * fq;
;         const size_t boff = (size_t)(un.pm >> 3) * bstride + col0;
;         { f32x4 gv[2][2];
; #pragma unroll
;           for (int bj = 0; bj < 2; ++bj)
; #pragma unroll
;               for (int n = 0; n < 2; ++n) gv[bj][n] = *(const f32x4*)(gate + boff + bj * HALF + n * 4);
; #pragma unroll
;           for (int ai = 0; ai < 2; ++ai)
; #pragma unroll
;               for (int m = 0; m < 4; ++m) { const size_t off = (size_t)(row0 + ai * HALF + m * 16) * ldc + col0;
; #pragma unroll
;                   for (int bj = 0; bj < 2; ++bj) {
; #pragma unroll
;                       for (int n = 0; n < 2; ++n) { f32x4 bs;
;                           if (BASE_F32) bs = *(const f32x4*)((const float*)base + off + bj * HALF + n * 4);
;                           else { const u32x2v hw = *(const u32x2v*)((const bf16_t*)base + off + bj * HALF + n * 4);
;                                  bs = (f32x4){__uint_as_float(hw.x << 16), __uint_as_float(hw.x & 0xffff0000u), __uint_as_float(hw.y << 16), __uint_as_float(hw.y & 0xffff0000u)}; }
;                           acc[ai][bj][m][n] = bs + gv[bj][n] * acc[ai][bj][m][n]; }
.LBB0_3796:
	v_mov_b32_e32 v128, 0
	v_readlane_b32 s12, v254, 43
	s_barrier
	s_lshl_b32 s4, s24, 5
	v_readlane_b32 s14, v254, 45
	v_mbcnt_lo_u32_b32 v128, -1, v128
	v_readlane_b32 s15, v254, 46
	s_add_u32 s0, s14, 0x1a600000
	v_mbcnt_hi_u32_b32 v128, -1, v128
	s_addc_u32 s1, s15, 0
	v_or_b32_e32 v152, s33, v128
	s_lshl_b32 s20, s8, 8
	s_lshl_b32 s12, s2, 8
	s_add_i32 s5, s20, s9
	v_and_b32_e32 v153, 15, v152
	s_or_b32 s4, s12, s4
	v_lshrrev_b32_e32 v128, 1, v152
	v_and_or_b32 v144, v128, 24, s4
	v_or_b32_e32 v148, s5, v153
	s_ashr_i32 s4, s8, 3
	v_ashrrev_i32_e32 v149, 31, v148
	s_mul_hi_i32 s5, s4, 0xc000
	s_mul_i32 s4, s4, 0xc000
	v_ashrrev_i32_e32 v145, 31, v144
	v_lshlrev_b64 v[128:129], 12, v[148:149]
	s_add_u32 s4, s14, s4
	v_lshl_add_u64 v[128:129], s[0:1], 0, v[128:129]
	v_lshlrev_b64 v[150:151], 1, v[144:145]
	s_addc_u32 s5, s15, s5
	v_lshl_add_u64 v[146:147], v[128:129], 0, v[150:151]
	v_lshl_add_u64 v[128:129], v[144:145], 2, s[4:5]
	s_mov_b32 s12, 0x19a000
	s_mov_b64 s[4:5], 0x19a000
	v_add_co_u32_e32 v130, vcc, s12, v128
	v_addc_co_u32_e32 v131, vcc, 0, v129, vcc
	v_lshl_add_u64 v[128:129], v[128:129], 0, s[4:5]
	flat_load_dwordx4 v[136:139], v[130:131]
	flat_load_dwordx4 v[140:143], v[128:129] offset:16
	flat_load_dwordx4 v[132:135], v[128:129] offset:512
	s_nop 0
	flat_load_dwordx4 v[128:131], v[128:129] offset:528
	v_or_b32_e32 v162, 16, v148
	v_ashrrev_i32_e32 v163, 31, v162
	v_lshlrev_b64 v[162:163], 12, v[162:163]
	v_lshl_add_u64 v[162:163], s[0:1], 0, v[162:163]
	v_lshl_add_u64 v[162:163], v[162:163], 0, v[150:151]
	v_readlane_b32 s13, v254, 44
	s_mov_b64 s[98:99], 0x10000
	s_mov_b64 s[100:101], 0x80000
	v_lshl_add_u64 v[204:205], v[146:147], 0, 0
	v_lshl_add_u64 v[206:207], v[204:205], 0, s[98:99]
	v_lshl_add_u64 v[208:209], v[206:207], 0, s[98:99]
	v_lshl_add_u64 v[210:211], v[208:209], 0, s[98:99]
	global_load_dwordx4 v[172:175], v[204:205], off
	global_load_dwordx4 v[176:179], v[204:205], off offset:256
	global_load_dwordx4 v[180:183], v[206:207], off
	global_load_dwordx4 v[184:187], v[206:207], off offset:256
	global_load_dwordx4 v[188:191], v[208:209], off
	global_load_dwordx4 v[192:195], v[208:209], off offset:256
	global_load_dwordx4 v[196:199], v[210:211], off
	global_load_dwordx4 v[200:203], v[210:211], off offset:256
	s_waitcnt vmcnt(0) lgkmcnt(0)
	v_lshlrev_b32_e32 v164, 16, v172
	v_and_b32_e32 v165, 0xffff0000, v172
	v_lshlrev_b32_e32 v154, 16, v173
	v_and_b32_e32 v155, 0xffff0000, v173
	v_lshlrev_b32_e32 v166, 16, v174
	v_and_b32_e32 v167, 0xffff0000, v174
	v_lshlrev_b32_e32 v156, 16, v175
	v_and_b32_e32 v157, 0xffff0000, v175
	v_lshlrev_b32_e32 v168, 16, v176
	v_and_b32_e32 v169, 0xffff0000, v176
	v_lshlrev_b32_e32 v158, 16, v177
	v_and_b32_e32 v159, 0xffff0000, v177
	v_lshlrev_b32_e32 v170, 16, v178
	v_and_b32_e32 v171, 0xffff0000, v178
	v_lshlrev_b32_e32 v160, 16, v179
	v_and_b32_e32 v161, 0xffff0000, v179
	v_pk_fma_f32 v[34:35], v[34:35], v[138:139], v[154:155]
	v_pk_fma_f32 v[32:33], v[32:33], v[136:137], v[164:165]
	v_pk_fma_f32 v[38:39], v[38:39], v[142:143], v[156:157]
	v_pk_fma_f32 v[36:37], v[36:37], v[140:141], v[166:167]
	v_pk_fma_f32 v[42:43], v[42:43], v[134:135], v[158:159]
	v_pk_fma_f32 v[40:41], v[40:41], v[132:133], v[168:169]
	v_pk_fma_f32 v[46:47], v[46:47], v[130:131], v[160:161]
	v_pk_fma_f32 v[44:45], v[44:45], v[128:129], v[170:171]
	s_nop 0
	v_or_b32_e32 v162, 32, v148
	v_ashrrev_i32_e32 v163, 31, v162
	v_lshlrev_b64 v[162:163], 12, v[162:163]
	v_lshl_add_u64 v[162:163], s[0:1], 0, v[162:163]
	v_lshl_add_u64 v[162:163], v[162:163], 0, v[150:151]
	v_or_b32_e32 v148, 48, v148
	v_ashrrev_i32_e32 v149, 31, v148
	v_lshlrev_b64 v[148:149], 12, v[148:149]
	v_lshl_add_u64 v[148:149], s[0:1], 0, v[148:149]
	s_mov_b32 s0, 0x80000
	s_nop 1
	v_lshlrev_b32_e32 v164, 16, v180
	v_and_b32_e32 v165, 0xffff0000, v180
	v_lshlrev_b32_e32 v154, 16, v181
	v_and_b32_e32 v155, 0xffff0000, v181
	v_lshlrev_b32_e32 v166, 16, v182
	v_and_b32_e32 v167, 0xffff0000, v182
	v_lshlrev_b32_e32 v156, 16, v183
	v_and_b32_e32 v157, 0xffff0000, v183
	v_lshlrev_b32_e32 v168, 16, v184
	v_and_b32_e32 v169, 0xffff0000, v184
	v_lshlrev_b32_e32 v158, 16, v185
	v_and_b32_e32 v159, 0xffff0000, v185
	v_lshlrev_b32_e32 v170, 16, v186
	v_and_b32_e32 v171, 0xffff0000, v186
	v_lshlrev_b32_e32 v160, 16, v187
	v_and_b32_e32 v161, 0xffff0000, v187
	v_pk_fma_f32 v[78:79], v[78:79], v[138:139], v[154:155]
	v_pk_fma_f32 v[76:77], v[76:77], v[136:137], v[164:165]
	v_pk_fma_f32 v[82:83], v[82:83], v[142:143], v[156:157]
	v_pk_fma_f32 v[80:81], v[80:81], v[140:141], v[166:167]
	v_pk_fma_f32 v[70:71], v[70:71], v[134:135], v[158:159]
	v_pk_fma_f32 v[68:69], v[68:69], v[132:133], v[168:169]
	v_pk_fma_f32 v[66:67], v[66:67], v[130:131], v[160:161]
	v_pk_fma_f32 v[64:65], v[64:65], v[128:129], v[170:171]
	s_nop 0
	v_lshl_add_u64 v[162:163], v[148:149], 0, v[150:151]
	s_nop 1
	v_lshlrev_b32_e32 v148, 16, v188
	v_and_b32_e32 v149, 0xffff0000, v188
	v_lshlrev_b32_e32 v150, 16, v189
	v_and_b32_e32 v151, 0xffff0000, v189
	v_lshlrev_b32_e32 v154, 16, v190
	v_and_b32_e32 v155, 0xffff0000, v190
	v_lshlrev_b32_e32 v156, 16, v191
	v_and_b32_e32 v157, 0xffff0000, v191
	v_lshlrev_b32_e32 v164, 16, v192
	v_and_b32_e32 v165, 0xffff0000, v192
	v_lshlrev_b32_e32 v158, 16, v193
	v_and_b32_e32 v159, 0xffff0000, v193
	v_lshlrev_b32_e32 v166, 16, v194
	v_and_b32_e32 v167, 0xffff0000, v194
	v_lshlrev_b32_e32 v160, 16, v195
	v_and_b32_e32 v161, 0xffff0000, v195
	v_pk_fma_f32 v[94:95], v[94:95], v[138:139], v[150:151]
	v_pk_fma_f32 v[92:93], v[92:93], v[136:137], v[148:149]
	v_pk_fma_f32 v[86:87], v[86:87], v[142:143], v[156:157]
	v_pk_fma_f32 v[84:85], v[84:85], v[140:141], v[154:155]
;     __device__ __forceinline__ void fused(f32x4 (&acc)[2][2][4][2], const Unit& un, int wr, int wc, int fr, int fq, PG8_LAS unsigned char* lds, int wid, int lane) const {
;     ...
;           for (int ai = 0; ai < 2; ++ai)
; #pragma unroll
;               for (int m = 0; m < 4; ++m) { const size_t off = (size_t)(row0 + ai * HALF + m * 16) * ldc + col0;
; #pragma unroll
;                   for (int bj = 0; bj < 2; ++bj) {
; #pragma unroll
;                       for (int n = 0; n < 2; ++n) { f32x4 bs;
;                           if (BASE_F32) bs = *(const f32x4*)((const float*)base + off + bj * HALF + n * 4);
;                           else { const u32x2v hw = *(const u32x2v*)((const bf16_t*)base + off + bj * HALF + n * 4);
;                                  bs = (f32x4){__uint_as_float(hw.x << 16), __uint_as_float(hw.x & 0xffff0000u), __uint_as_float(hw.y << 16), __uint_as_float(hw.y & 0xffff0000u)}; }
;                           acc[ai][bj][m][n] = bs + gv[bj][n] * acc[ai][bj][m][n]; }
	v_pk_fma_f32 v[62:63], v[62:63], v[134:135], v[158:159]
	v_pk_fma_f32 v[60:61], v[60:61], v[132:133], v[164:165]
	v_pk_fma_f32 v[58:59], v[58:59], v[130:131], v[160:161]
	v_pk_fma_f32 v[56:57], v[56:57], v[128:129], v[166:167]
	v_add_co_u32_e32 v158, vcc, s0, v146
	s_mov_b64 s[0:1], 0x80000
	v_addc_co_u32_e32 v159, vcc, 0, v147, vcc
	s_nop 1
	v_lshlrev_b32_e32 v160, 16, v196
	v_and_b32_e32 v161, 0xffff0000, v196
	v_lshlrev_b32_e32 v148, 16, v197
	v_and_b32_e32 v149, 0xffff0000, v197
	v_lshlrev_b32_e32 v162, 16, v198
	v_and_b32_e32 v163, 0xffff0000, v198
	v_lshlrev_b32_e32 v150, 16, v199
	v_and_b32_e32 v151, 0xffff0000, v199
	v_lshlrev_b32_e32 v164, 16, v200
	v_and_b32_e32 v165, 0xffff0000, v200
	v_lshlrev_b32_e32 v154, 16, v201
	v_and_b32_e32 v155, 0xffff0000, v201
	v_lshlrev_b32_e32 v166, 16, v202
	v_and_b32_e32 v167, 0xffff0000, v202
	v_lshlrev_b32_e32 v156, 16, v203
	v_and_b32_e32 v157, 0xffff0000, v203
	v_pk_fma_f32 v[110:111], v[110:111], v[138:139], v[148:149]
	v_pk_fma_f32 v[108:109], v[108:109], v[136:137], v[160:161]
	v_pk_fma_f32 v[106:107], v[106:107], v[142:143], v[150:151]
	v_pk_fma_f32 v[104:105], v[104:105], v[140:141], v[162:163]
	v_pk_fma_f32 v[102:103], v[102:103], v[134:135], v[154:155]
	v_pk_fma_f32 v[100:101], v[100:101], v[132:133], v[164:165]
	v_pk_fma_f32 v[98:99], v[98:99], v[130:131], v[156:157]
	v_pk_fma_f32 v[96:97], v[96:97], v[128:129], v[166:167]
	v_lshl_add_u64 v[154:155], v[146:147], 0, s[0:1]
	s_mov_b32 s0, 0x90000
	v_add_co_u32_e32 v158, vcc, s0, v146
	s_mov_b64 s[0:1], 0x90000
	s_nop 0
	v_addc_co_u32_e32 v159, vcc, 0, v147, vcc
	v_lshl_add_u64 v[204:205], v[204:205], 0, s[100:101]
	v_lshl_add_u64 v[206:207], v[206:207], 0, s[100:101]
	v_lshl_add_u64 v[208:209], v[208:209], 0, s[100:101]
	v_lshl_add_u64 v[210:211], v[210:211], 0, s[100:101]
	global_load_dwordx4 v[172:175], v[204:205], off
	global_load_dwordx4 v[176:179], v[204:205], off offset:256
	global_load_dwordx4 v[180:183], v[206:207], off
	global_load_dwordx4 v[184:187], v[206:207], off offset:256
	global_load_dwordx4 v[188:191], v[208:209], off
	global_load_dwordx4 v[192:195], v[208:209], off offset:256
	global_load_dwordx4 v[196:199], v[210:211], off
	global_load_dwordx4 v[200:203], v[210:211], off offset:256
	s_waitcnt vmcnt(0) lgkmcnt(0)
; __device__ __forceinline__ unsigned cvt_pk_bf16(float lo, float hi) { unsigned r; asm volatile("v_cvt_pk_bf16_f32 %0, %1, %2" : "=v"(r) : "v"(lo), "v"(hi)); return r; }
;     __device__ __forceinline__ void fused(f32x4 (&acc)[2][2][4][2], const Unit& un, int wr, int wc, int fr, int fq, PG8_LAS unsigned char* lds, int wid, int lane) const {
;     ...
;           for (int ai = 0; ai < 2; ++ai)
; #pragma unroll
;               for (int m = 0; m < 4; ++m) { const size_t off = (size_t)(row0 + ai * HALF + m * 16) * ldc + col0;
; #pragma unroll
;                   for (int bj = 0; bj < 2; ++bj) {
; #pragma unroll
;                       for (int n = 0; n < 2; ++n) { f32x4 bs;
;                           if (BASE_F32) bs = *(const f32x4*)((const float*)base + off + bj * HALF + n * 4);
;                           else { const u32x2v hw = *(const u32x2v*)((const bf16_t*)base + off + bj * HALF + n * 4);
;                                  bs = (f32x4){__uint_as_float(hw.x << 16), __uint_as_float(hw.x & 0xffff0000u), __uint_as_float(hw.y << 16), __uint_as_float(hw.y & 0xffff0000u)}; }
;                           acc[ai][bj][m][n] = bs + gv[bj][n] * acc[ai][bj][m][n]; }
;                       if (out_h) { const f32x4 a0 = acc[ai][bj][m][0], a1 = acc[ai][bj][m][1]; u32x4 w; w.x = cvt_pk_bf16(a0[0], a0[1]); w.y = cvt_pk_bf16(a0[2], a0[3]); w.z = cvt_pk_bf16(a1[0], a1[1]); w.w = cvt_pk_bf16(a1[2], a1[3]);
;                           *(u32x4*)(out_h + off + bj * HALF) = w; } }
;                   asm volatile("" : "+v"(acc[ai][0][m][0]), "+v"(acc[ai][0][m][1]), "+v"(acc[ai][1][m][0]), "+v"(acc[ai][1][m][1]));
;                   asm volatile("" ::: "memory"); } }
; #pragma unroll
;         for (int ai = 0; ai < 2; ++ai)
; #pragma unroll
;             for (int m = 0; m < 4; ++m) { float s = 0.f;
; #pragma unroll
;                 for (int bj = 0; bj < 2; ++bj)
; #pragma unroll
;                     for (int n = 0; n < 2; ++n) { const f32x4 x = acc[ai][bj][m][n]; s += (x[0] * x[0] + x[1] * x[1]) + (x[2] * x[2] + x[3] * x[3]); }
;                 s += __shfl_xor(s, 16); s += __shfl_xor(s, 32);
;                 if (fq == 0) P[(ai * HALF + wr * 64 + m * 16 + fr) * 4 + wc] = s; }
	v_lshlrev_b32_e32 v160, 16, v172
	v_and_b32_e32 v161, 0xffff0000, v172
	v_lshlrev_b32_e32 v148, 16, v173
	v_and_b32_e32 v149, 0xffff0000, v173
	v_lshlrev_b32_e32 v162, 16, v174
	v_and_b32_e32 v163, 0xffff0000, v174
	v_lshlrev_b32_e32 v150, 16, v175
	v_and_b32_e32 v151, 0xffff0000, v175
	v_lshlrev_b32_e32 v164, 16, v176
	v_and_b32_e32 v165, 0xffff0000, v176
	v_lshlrev_b32_e32 v154, 16, v177
	v_and_b32_e32 v155, 0xffff0000, v177
	v_lshlrev_b32_e32 v166, 16, v178
	v_and_b32_e32 v167, 0xffff0000, v178
	v_lshlrev_b32_e32 v156, 16, v179
	v_and_b32_e32 v157, 0xffff0000, v179
	v_pk_fma_f32 v[126:127], v[126:127], v[138:139], v[148:149]
	v_pk_fma_f32 v[124:125], v[124:125], v[136:137], v[160:161]
	v_pk_fma_f32 v[122:123], v[122:123], v[142:143], v[150:151]
	v_pk_fma_f32 v[120:121], v[120:121], v[140:141], v[162:163]
	v_pk_fma_f32 v[118:119], v[118:119], v[134:135], v[154:155]
	v_pk_fma_f32 v[116:117], v[116:117], v[132:133], v[164:165]
	v_pk_fma_f32 v[114:115], v[114:115], v[130:131], v[156:157]
	v_pk_fma_f32 v[112:113], v[112:113], v[128:129], v[166:167]
	v_lshl_add_u64 v[154:155], v[146:147], 0, s[0:1]
	s_mov_b32 s0, 0xa0000
	v_add_co_u32_e32 v158, vcc, s0, v146
	s_mov_b64 s[0:1], 0xa0000
	s_nop 0
	v_addc_co_u32_e32 v159, vcc, 0, v147, vcc
	s_nop 1
	v_lshlrev_b32_e32 v160, 16, v180
	v_and_b32_e32 v161, 0xffff0000, v180
	v_lshlrev_b32_e32 v148, 16, v181
	v_and_b32_e32 v149, 0xffff0000, v181
	v_lshlrev_b32_e32 v162, 16, v182
	v_and_b32_e32 v163, 0xffff0000, v182
	v_lshlrev_b32_e32 v150, 16, v183
	v_and_b32_e32 v151, 0xffff0000, v183
	v_lshlrev_b32_e32 v164, 16, v184
	v_and_b32_e32 v165, 0xffff0000, v184
	v_lshlrev_b32_e32 v154, 16, v185
	v_and_b32_e32 v155, 0xffff0000, v185
	v_lshlrev_b32_e32 v166, 16, v186
	v_and_b32_e32 v167, 0xffff0000, v186
	v_lshlrev_b32_e32 v156, 16, v187
	v_and_b32_e32 v157, 0xffff0000, v187
	v_pk_fma_f32 v[90:91], v[90:91], v[138:139], v[148:149]
	v_pk_fma_f32 v[88:89], v[88:89], v[136:137], v[160:161]
	v_pk_fma_f32 v[74:75], v[74:75], v[142:143], v[150:151]
	v_pk_fma_f32 v[72:73], v[72:73], v[140:141], v[162:163]
	v_pk_fma_f32 v[54:55], v[54:55], v[134:135], v[154:155]
	v_pk_fma_f32 v[52:53], v[52:53], v[132:133], v[164:165]
	v_pk_fma_f32 v[50:51], v[50:51], v[130:131], v[156:157]
	v_pk_fma_f32 v[48:49], v[48:49], v[128:129], v[166:167]
	v_lshl_add_u64 v[154:155], v[146:147], 0, s[0:1]
	s_mov_b32 s0, 0xb0000
	v_add_co_u32_e32 v158, vcc, s0, v146
	s_mov_b64 s[0:1], 0xb0000
	s_nop 0
	v_addc_co_u32_e32 v159, vcc, 0, v147, vcc
	v_lshl_add_u64 v[146:147], v[146:147], 0, s[0:1]
	s_lshl_b32 s0, s24, 2
	s_add_i32 s0, s0, 0
	s_nop 1
	v_lshlrev_b32_e32 v160, 16, v188
	v_and_b32_e32 v161, 0xffff0000, v188
	v_lshlrev_b32_e32 v148, 16, v189
	v_and_b32_e32 v149, 0xffff0000, v189
	v_lshlrev_b32_e32 v162, 16, v190
	v_and_b32_e32 v163, 0xffff0000, v190
	v_lshlrev_b32_e32 v150, 16, v191
	v_and_b32_e32 v151, 0xffff0000, v191
	v_lshlrev_b32_e32 v164, 16, v192
	v_and_b32_e32 v165, 0xffff0000, v192
	v_lshlrev_b32_e32 v154, 16, v193
	v_and_b32_e32 v155, 0xffff0000, v193
	v_lshlrev_b32_e32 v166, 16, v194
	v_and_b32_e32 v167, 0xffff0000, v194
	v_lshlrev_b32_e32 v156, 16, v195
	v_and_b32_e32 v157, 0xffff0000, v195
	v_pk_fma_f32 v[30:31], v[30:31], v[138:139], v[148:149]
	v_pk_fma_f32 v[28:29], v[28:29], v[136:137], v[160:161]
	v_pk_fma_f32 v[26:27], v[26:27], v[142:143], v[150:151]
	v_pk_fma_f32 v[24:25], v[24:25], v[140:141], v[162:163]
	v_pk_fma_f32 v[22:23], v[22:23], v[134:135], v[154:155]
	v_pk_fma_f32 v[20:21], v[20:21], v[132:133], v[164:165]
	v_pk_fma_f32 v[18:19], v[18:19], v[130:131], v[156:157]
	v_pk_fma_f32 v[16:17], v[16:17], v[128:129], v[166:167]
	v_mul_f32_e32 v151, v35, v35
	v_mul_f32_e32 v162, v37, v37
	v_mbcnt_lo_u32_b32 v146, -1, 0
	v_mbcnt_hi_u32_b32 v146, -1, v146
	v_and_b32_e32 v148, 64, v146
	v_xor_b32_e32 v147, 16, v146
	v_add_u32_e32 v150, 64, v148
	v_cmp_lt_i32_e32 vcc, v147, v150
	v_mul_f32_e32 v163, v39, v39
	v_mul_f32_e32 v164, v41, v41
	v_cndmask_b32_e32 v147, v146, v147, vcc
	v_lshlrev_b32_e32 v148, 2, v147
	v_mul_f32_e32 v147, v33, v33
	v_mul_f32_e32 v165, v43, v43
	v_fmac_f32_e32 v147, v32, v32
	v_fmac_f32_e32 v151, v34, v34
	v_fmac_f32_e32 v162, v36, v36
	v_fmac_f32_e32 v163, v38, v38
	v_mul_f32_e32 v166, v45, v45
	v_mul_f32_e32 v167, v47, v47
	v_fmac_f32_e32 v164, v40, v40
	v_fmac_f32_e32 v165, v42, v42
	v_add_f32_e32 v147, v147, v151
	v_add_f32_e32 v151, v162, v163
	v_fmac_f32_e32 v166, v44, v44
	v_fmac_f32_e32 v167, v46, v46
	v_add_f32_e32 v162, v164, v165
	v_add_f32_e32 v147, v147, v151
	v_add_f32_e32 v163, v166, v167
	v_add_f32_e32 v147, v162, v147
	v_add_f32_e32 v151, v163, v147
	ds_bpermute_b32 v162, v148, v151
	v_xor_b32_e32 v149, 32, v146
	v_cmp_lt_i32_e32 vcc, v149, v150
	v_and_b32_e32 v147, 63, v152
	s_waitcnt lgkmcnt(0)
	v_add_f32_e32 v150, v151, v162
	v_cndmask_b32_e32 v146, v146, v149, vcc
	v_lshlrev_b32_e32 v149, 2, v146
	ds_bpermute_b32 v151, v149, v150
	v_or_b32_e32 v146, s9, v153
	v_cmp_gt_u32_e32 vcc, 16, v147
	s_waitcnt vmcnt(0)
	v_lshlrev_b32_e32 v162, 16, v196
	v_and_b32_e32 v163, 0xffff0000, v196
	v_lshlrev_b32_e32 v154, 16, v197
	v_and_b32_e32 v155, 0xffff0000, v197
	v_lshlrev_b32_e32 v164, 16, v198
	v_and_b32_e32 v165, 0xffff0000, v198
	v_lshlrev_b32_e32 v156, 16, v199
	v_and_b32_e32 v157, 0xffff0000, v199
	v_lshlrev_b32_e32 v166, 16, v200
	v_and_b32_e32 v167, 0xffff0000, v200
	v_lshlrev_b32_e32 v158, 16, v201
	v_and_b32_e32 v159, 0xffff0000, v201
	v_lshlrev_b32_e32 v168, 16, v202
	v_and_b32_e32 v169, 0xffff0000, v202
	v_lshlrev_b32_e32 v160, 16, v203
	v_and_b32_e32 v161, 0xffff0000, v203
	v_pk_fma_f32 v[14:15], v[14:15], v[138:139], v[154:155]
	v_pk_fma_f32 v[12:13], v[12:13], v[136:137], v[162:163]
	v_pk_fma_f32 v[10:11], v[10:11], v[142:143], v[156:157]
	v_pk_fma_f32 v[8:9], v[8:9], v[140:141], v[164:165]
	v_pk_fma_f32 v[6:7], v[6:7], v[134:135], v[158:159]
	v_pk_fma_f32 v[4:5], v[4:5], v[132:133], v[166:167]
	v_pk_fma_f32 v[2:3], v[2:3], v[130:131], v[160:161]
	v_pk_fma_f32 v[0:1], v[0:1], v[128:129], v[168:169]
	v_lshl_add_u32 v128, v146, 4, s0
	s_and_saveexec_b64 s[0:1], vcc
	s_cbranch_execz .LBB0_3798
	s_waitcnt lgkmcnt(0)
	v_add_f32_e32 v129, v150, v151
	ds_write_b32 v128, v129

; #define LAS __attribute__((address_space(3)))
; __global__ void __launch_bounds__(NWAVES * 64, 2) fwd_kernel(Args args) {
;     extern __shared__ __attribute__((aligned(16))) unsigned char lds_raw[];
;     LAS unsigned char* lds = (LAS unsigned char*)lds_raw;
;     volatile LAS unsigned* MISC = (volatile LAS unsigned*)(lds + MISC_OFF);
;     const int tid = threadIdx.x, lane = tid & 63, wave = __builtin_amdgcn_readfirstlane(tid >> 6);
;     const int G = gridDim.x;
;     const int gw = blockIdx.x * NWAVES + wave, NGW = G * NWAVES;
;     unsigned char* const ws_kernel = args.ws;
;     for (int u = tid; u < (LDS_BYTES - LDSCTL_OFF) / 4; u += NWAVES * 64) ((LAS unsigned*)(lds + LDSCTL_OFF))[u] = 0u;
	.amdhsa_kernel _Z10fwd_kernel4Args
		.amdhsa_group_segment_fixed_size 0
		.amdhsa_private_segment_fixed_size 0
		.amdhsa_kernarg_size 440
		.amdhsa_user_sgpr_count 2
		.amdhsa_user_sgpr_dispatch_ptr 0
		.amdhsa_user_sgpr_queue_ptr 0
		.amdhsa_user_sgpr_kernarg_segment_ptr 1
		.amdhsa_user_sgpr_dispatch_id 0
		.amdhsa_user_sgpr_kernarg_preload_length 0
		.amdhsa_user_sgpr_kernarg_preload_offset 0
		.amdhsa_user_sgpr_private_segment_size 0
		.amdhsa_uses_dynamic_stack 0
		.amdhsa_enable_private_segment 0
		.amdhsa_system_sgpr_workgroup_id_x 1
		.amdhsa_system_sgpr_workgroup_id_y 0
		.amdhsa_system_sgpr_workgroup_id_z 0
		.amdhsa_system_sgpr_workgroup_info 0
		.amdhsa_system_vgpr_workitem_id 0
		.amdhsa_next_free_vgpr 256
		.amdhsa_next_free_sgpr 102
		.amdhsa_accum_offset 256
		.amdhsa_reserve_vcc 1
		.amdhsa_float_round_mode_32 0
		.amdhsa_float_round_mode_16_64 0
		.amdhsa_float_denorm_mode_32 3
		.amdhsa_float_denorm_mode_16_64 3
		.amdhsa_dx10_clamp 1
		.amdhsa_ieee_mode 1
		.amdhsa_fp16_overflow 0
		.amdhsa_tg_split 0
		.amdhsa_exception_fp_ieee_invalid_op 0
		.amdhsa_exception_fp_denorm_src 0
		.amdhsa_exception_fp_ieee_div_zero 0
		.amdhsa_exception_fp_ieee_overflow 0
		.amdhsa_exception_fp_ieee_underflow 0
		.amdhsa_exception_fp_ieee_inexact 0
		.amdhsa_exception_int_div_zero 0
	.end_amdhsa_kernel

; #define LAS __attribute__((address_space(3)))
; __global__ void __launch_bounds__(NWAVES * 64, 2) fwd_kernel(Args args) {
;     extern __shared__ __attribute__((aligned(16))) unsigned char lds_raw[];
;     LAS unsigned char* lds = (LAS unsigned char*)lds_raw;
;     volatile LAS unsigned* MISC = (volatile LAS unsigned*)(lds + MISC_OFF);
;     const int tid = threadIdx.x, lane = tid & 63, wave = __builtin_amdgcn_readfirstlane(tid >> 6);
;     const int G = gridDim.x;
;     const int gw = blockIdx.x * NWAVES + wave, NGW = G * NWAVES;
;     unsigned char* const ws_kernel = args.ws;
;     for (int u = tid; u < (LDS_BYTES - LDSCTL_OFF) / 4; u += NWAVES * 64) ((LAS unsigned*)(lds + LDSCTL_OFF))[u] = 0u;
amdhsa.kernels:
  - .agpr_count:     0
    .args:
      - .offset:         0
        .size:           184
        .value_kind:     by_value
      - .offset:         184
        .size:           4
        .value_kind:     hidden_block_count_x
      - .offset:         188
        .size:           4
        .value_kind:     hidden_block_count_y
      - .offset:         192
        .size:           4
        .value_kind:     hidden_block_count_z
      - .offset:         196
        .size:           2
        .value_kind:     hidden_group_size_x
      - .offset:         198
        .size:           2
        .value_kind:     hidden_group_size_y
      - .offset:         200
        .size:           2
        .value_kind:     hidden_group_size_z
      - .offset:         202
        .size:           2
        .value_kind:     hidden_remainder_x
      - .offset:         204
        .size:           2
        .value_kind:     hidden_remainder_y
      - .offset:         206
        .size:           2
        .value_kind:     hidden_remainder_z
      - .offset:         224
        .size:           8
        .value_kind:     hidden_global_offset_x
      - .offset:         232
        .size:           8
        .value_kind:     hidden_global_offset_y
      - .offset:         240
        .size:           8
        .value_kind:     hidden_global_offset_z
      - .offset:         248
        .size:           2
        .value_kind:     hidden_grid_dims
      - .offset:         304
        .size:           4
        .value_kind:     hidden_dynamic_lds_size
    .group_segment_fixed_size: 0
    .kernarg_segment_align: 8
    .kernarg_segment_size: 440
    .language:       OpenCL C
    .language_version:
      - 2
      - 0
    .max_flat_workgroup_size: 512
    .name:           _Z10fwd_kernel4Args
    .private_segment_fixed_size: 0
    .sgpr_count:     108
    .sgpr_spill_count: 77
    .symbol:         _Z10fwd_kernel4Args.kd
    .uniform_work_group_size: 1
    .uses_dynamic_stack: false
    .vgpr_count:     256
    .vgpr_spill_count: 0
    .wavefront_size: 64
